# GEMM loops: per-MFMA-block s_setprio toggles removed, one static priority raise for the trailing wave half per phase
# baseline (speedup 1.0000x reference)
; #define PG8_STAGE(bufoff, gbase, voff) do { _Pragma("unroll") for (int _i = 0; _i < 2; ++_i) \
;         __builtin_amdgcn_global_load_lds((const unsigned*)((const char*)(gbase) + (voff)[_i]), (PG8_LAS unsigned*)(lds + (bufoff) + ldsw + _i * 8192), 16, 0, 0); } while (0)
; #define PG8_BAR __builtin_amdgcn_s_barrier()
; template <class Epi, class Sched, bool ALIGN_EPI = false, bool SP2 = false>
; __device__ __forceinline__ void gemm_phase(PG8_LAS unsigned char* lds, const Gemm g, const Sched& S, const Epi& E) {
;     const int tid = threadIdx.x, wid = __builtin_amdgcn_readfirstlane(tid >> 6), lane = tid & 63, wr = wid >> 2, wc = wid & 3, fr = lane & 15, fq = lane >> 4;
;     const int K = g.K, nt = K / BK;
;     unsigned voffA[2], voffB[2];
; #pragma unroll
;     for (int i = 0; i < 2; ++i) { int R, C; stage_rc(tid * 16 + i * 8192, R, C); const int Rb = Epi::PERM ? ((R & ~31) + perm32(R & 31)) : R;
;         voffA[i] = (unsigned)(R * K + C) * 2u; voffB[i] = (unsigned)(Rb * K + C) * 2u; }
;     const size_t kstep = (size_t)(BK * 2);
;     const size_t hstep = (size_t)HALF * K * 2;
;     const size_t tstep = 2 * hstep;
;     const unsigned ldsw = (unsigned)wid * 1024u;
;     const int aoff = lds_byte(wr * 64 + fr, fq * 8), boff = lds_byte(wc * 32 + fr, fq * 8);
;     ...
;     const char* cA = (const char*)g.A + (size_t)cur.pm * tstep; const char* cB = (const char*)g.Bt + (size_t)cur.pn * tstep;
;     S.a_ready(cur);
;     if constexpr (SP2) {
;         PG8_STAGE(PG8_SB(0, 0), cB, voffB); PG8_STAGE(PG8_SB(0, 1), cB + hstep, voffB); PG8_STAGE(PG8_SA(0, 0), cA, voffA); PG8_STAGE(PG8_SA(0, 1), cA + hstep, voffA);
;         if (wr == 1) PG8_BAR;
.LBB0_184:
	s_cmp_lt_i32 s82, 3
	s_cselect_b64 s[4:5], -1, 0
	s_waitcnt lgkmcnt(0)
	s_add_u32 s68, s86, 0x1300000
	s_addc_u32 s69, s87, 0
	s_add_u32 s30, s86, 0x4300000
	s_addc_u32 s31, s87, 0
	s_add_u32 s24, s86, 0x6300000
	s_addc_u32 s25, s87, 0
	s_and_b64 s[10:11], s[4:5], s[0:1]
	s_andn2_b64 vcc, exec, s[10:11]
	s_cbranch_vccnz .LBB0_207
	s_cmpk_gt_i32 s2, 0x57f
	v_readfirstlane_b32 s5, v226
	s_cbranch_scc1 .LBB0_201
	v_lshrrev_b32_e32 v0, 5, v226
	v_lshrrev_b32_e32 v2, 1, v226
	v_and_b32_e32 v0, 4, v0
	v_bfe_u32 v1, v226, 2, 2
	v_and_b32_e32 v11, 24, v2
	v_or3_b32 v0, v0, v1, v11
	v_lshlrev_b32_e32 v1, 4, v226
	v_add_u32_e32 v8, 0x2000, v1
	v_lshrrev_b32_e32 v2, 7, v8
	s_movk_i32 s0, 0xe0
	v_and_b32_e32 v4, 32, v226
	v_and_or_b32 v3, v2, s0, v0
	v_bitop3_b32 v9, v1, v4, 48 bitop3:0x6c
	v_and_b32_e32 v10, 64, v226
	v_bfe_u32 v12, v226, 2, 4
	s_movk_i32 s0, 0xf0
	v_or_b32_e32 v1, v9, v10
	v_and_or_b32 v2, v2, s0, v12
	v_lshl_or_b32 v130, v2, 11, v1
	v_lshrrev_b32_e32 v2, 3, v226
	s_movk_i32 s0, 0x60
	v_and_or_b32 v0, v2, s0, v0
	s_movk_i32 s0, 0x70
	s_ashr_i32 s54, s2, 31
	v_lshl_or_b32 v132, v0, 11, v1
	v_and_or_b32 v0, v2, s0, v12
	s_lshr_b32 s0, s54, 29
	s_add_i32 s0, s2, s0
	s_lshr_b32 s12, s5, 6
	s_ashr_i32 s1, s0, 3
	s_and_b32 s0, s0, -8
	s_lshr_b32 s14, s5, 8
	s_lshl_b32 s3, s12, 10
	s_sub_i32 s0, s2, s0
	s_cmp_lt_i32 s0, 0
	s_movk_i32 s55, 0xb1
	s_cselect_b32 s4, s55, 0xb0
	s_mul_i32 s0, s0, s4
	s_add_i32 s0, s0, s1
	s_mul_hi_i32 s1, s0, 0x2e8ba2e9
	s_lshr_b32 s4, s1, 31
	s_ashr_i32 s1, s1, 5
	s_add_i32 s1, s1, s4
	s_lshl_b32 s13, s1, 3
	s_mulk_i32 s1, 0xb0
	s_sub_i32 s0, s0, s1
	s_sext_i32_i16 s1, s0
	s_bfe_u32 s1, s1, 0x3001c
	s_add_i32 s1, s0, s1
	s_sext_i32_i16 s4, s1
	s_and_b32 s1, s1, 0xfff8
	s_sub_i32 s0, s0, s1
	s_sext_i32_i16 s0, s0
	s_lshr_b32 s4, s4, 3
	s_add_i32 s36, s13, s0
	s_ashr_i32 s37, s36, 31
	s_bfe_i64 s[16:17], s[4:5], 0x100000
	s_lshl_b64 s[0:1], s[36:37], 19
	s_lshl_b64 s[16:17], s[16:17], 19
	s_add_u32 s40, s88, s16
	s_addc_u32 s41, s89, s17
	s_add_i32 s37, s3, 0
	s_add_i32 m0, s37, 0x10000
	v_lshl_or_b32 v128, v3, 11, v1
	global_load_lds_dwordx4 v132, s[40:41]
	s_add_i32 m0, s37, 0x12000
	s_add_u32 s16, s40, 0x40000
	global_load_lds_dwordx4 v128, s[40:41]
	s_addc_u32 s17, s41, 0
	s_add_i32 m0, s37, 0x14000
	v_lshl_or_b32 v134, v0, 11, v1
	global_load_lds_dwordx4 v132, s[16:17]
	s_add_i32 m0, s37, 0x16000
	s_add_u32 s38, s30, s0
	s_addc_u32 s39, s31, s1
	s_add_i32 s56, s37, 0x2000
	global_load_lds_dwordx4 v128, s[16:17]
	s_mov_b32 m0, s37
	s_add_u32 s0, s38, 0x40000
	global_load_lds_dwordx4 v134, s[38:39]
	s_mov_b32 m0, s56
	s_addc_u32 s1, s39, 0
	s_add_i32 s57, s37, 0x4000
	global_load_lds_dwordx4 v130, s[38:39]
	s_mov_b32 m0, s57
	s_add_i32 s58, s37, 0x6000
	global_load_lds_dwordx4 v134, s[0:1]
	s_mov_b32 m0, s58
	v_mov_b32_e32 v133, 0
	global_load_lds_dwordx4 v130, s[0:1]
	v_mov_b32_e32 v129, v133
	v_mov_b32_e32 v135, v133
	v_mov_b32_e32 v131, v133
	s_cmp_eq_u32 s14, 1
	s_mov_b32 s59, 0
	v_lshl_add_u64 v[6:7], s[40:41], 0, v[132:133]
	v_lshl_add_u64 v[4:5], s[40:41], 0, v[128:129]
	v_lshl_add_u64 v[0:1], s[38:39], 0, v[134:135]
	s_cselect_b64 s[0:1], -1, 0
	s_cmp_lg_u32 s14, 1
	v_lshl_add_u64 v[2:3], s[38:39], 0, v[130:131]
	s_cbranch_scc1 .LBB0_188
	s_barrier
	s_setprio 1

; #define PG8_STAGE(bufoff, gbase, voff) do { _Pragma("unroll") for (int _i = 0; _i < 2; ++_i) \
;         __builtin_amdgcn_global_load_lds((const unsigned*)((const char*)(gbase) + (voff)[_i]), (PG8_LAS unsigned*)(lds + (bufoff) + ldsw + _i * 8192), 16, 0, 0); } while (0)
; #define PG8_LDA(dst, b, h) do { _Pragma("unroll") for (int m = 0; m < 4; ++m) _Pragma("unroll") for (int k = 0; k < 2; ++k) dst[m][k] = *(const PG8_LAS bf16x8*)(lds + PG8_SA(b, h) + aoff + m * 2048 + k * 1024); } while (0)
; #define PG8_LDB(dst, b, h) do { _Pragma("unroll") for (int n = 0; n < 2; ++n) _Pragma("unroll") for (int k = 0; k < 2; ++k) dst[n][k] = *(const PG8_LAS bf16x8*)(lds + PG8_SB(b, h) + boff + n * 2048 + k * 1024); } while (0)
; #define PG8_MMA(ai, bj, At, Bt) do { __builtin_amdgcn_s_setprio(1); _Pragma("unroll") for (int m = 0; m < 4; ++m) _Pragma("unroll") for (int n = 0; n < 2; ++n) _Pragma("unroll") for (int k = 0; k < 2; ++k) \
;         acc[ai][bj][m][n] = __builtin_amdgcn_mfma_f32_16x16x32_bf16(Bt[n][k], At[m][k], acc[ai][bj][m][n], 0, 0, 0); __builtin_amdgcn_s_setprio(0); } while (0)
; #define PG8_WAIT_V(n) asm volatile("s_waitcnt vmcnt(" #n ")" ::: "memory")
; template <class Epi, class Sched, bool ALIGN_EPI = false, bool SP2 = false>
; __device__ __forceinline__ void gemm_phase(PG8_LAS unsigned char* lds, const Gemm g, const Sched& S, const Epi& E) {
;     ...
;             PG8_LDB(B0, 0, 0); PG8_LDB(B1, 0, 1); PG8_SCHED; PG8_LDA(At, 0, 0); PG8_STAGE(PG8_SA(1, 1), a1 + hstep, voffA);
;             PG8_WAIT_V(8); PG8_WAIT_L(0); PG8_BAR; PG8_MMA(0, 0, At, B0); PG8_MMA(0, 1, At, B1); PG8_BAR; PG8_SCHED;
;             PG8_LDA(At, 0, 1); PG8_STAGE(PG8_SB(0, 0), b2, voffB); PG8_STAGE(PG8_SB(0, 1), b2 + hstep, voffB); PG8_STAGE(PG8_SA(0, 0), a2, voffA);
;             PG8_WAIT_V(8); PG8_WAIT_L(0); PG8_BAR; PG8_MMA(1, 0, At, B0); PG8_MMA(1, 1, At, B1); PG8_BAR; PG8_SCHED;
;             PG8_LDB(B0, 1, 0); PG8_LDB(B1, 1, 1); PG8_SCHED; PG8_LDA(At, 1, 0); PG8_STAGE(PG8_SA(0, 1), a2 + hstep, voffA);
;             PG8_WAIT_V(8); PG8_WAIT_L(0); PG8_BAR; PG8_MMA(0, 0, At, B0); PG8_MMA(0, 1, At, B1); PG8_BAR; PG8_SCHED;
;             PG8_LDA(At, 1, 1); PG8_STAGE(PG8_SB(1, 0), b3, voffB); PG8_STAGE(PG8_SB(1, 1), b3 + hstep, voffB); PG8_STAGE(PG8_SA(1, 0), a3, voffA);
;             PG8_WAIT_V(8); PG8_WAIT_L(0); PG8_BAR; PG8_MMA(1, 0, At, B0); PG8_MMA(1, 1, At, B1); PG8_BAR; PG8_SCHED;
.LBB0_194:
	ds_read_b128 v[152:155], v149
	ds_read_b128 v[156:159], v149 offset:1024
	ds_read_b128 v[162:165], v149 offset:2048
	ds_read_b128 v[166:169], v149 offset:3072
	ds_read_b128 v[170:173], v150
	ds_read_b128 v[174:177], v150 offset:1024
	ds_read_b128 v[178:181], v150 offset:2048
	ds_read_b128 v[182:185], v150 offset:3072
	s_add_u32 s40, s38, 0xfffc0080
	s_addc_u32 s41, s39, -1
	s_cmp_eq_u32 s78, 12
	s_cselect_b32 s53, s19, s41
	s_cselect_b32 s52, s72, s40
	s_cselect_b32 s41, s17, s77
	s_cselect_b32 s40, s73, s76
	v_lshl_add_u64 v[144:145], s[38:39], 0, v[136:137]
	s_add_i32 m0, s37, 0xc000
	ds_read_b128 v[186:189], v151
	ds_read_b128 v[190:193], v151 offset:1024
	ds_read_b128 v[194:197], v151 offset:2048
	ds_read_b128 v[198:201], v151 offset:3072
	ds_read_b128 v[202:205], v151 offset:4096
	ds_read_b128 v[206:209], v151 offset:5120
	ds_read_b128 v[210:213], v151 offset:6144
	ds_read_b128 v[214:217], v151 offset:7168
	global_load_lds_dwordx4 v[144:145], off
	v_lshl_add_u64 v[144:145], s[38:39], 0, v[138:139]
	s_add_i32 m0, s37, 0xe000
	s_nop 0
	global_load_lds_dwordx4 v[144:145], off
	s_waitcnt vmcnt(8)
	s_waitcnt lgkmcnt(0)
	s_barrier
	s_waitcnt lgkmcnt(0)
	v_mfma_f32_16x16x32_bf16 v[124:127], v[152:155], v[186:189], v[124:127]
	v_mfma_f32_16x16x32_bf16 v[116:119], v[162:165], v[186:189], v[116:119]
	v_mfma_f32_16x16x32_bf16 v[108:111], v[152:155], v[194:197], v[108:111]
	v_mfma_f32_16x16x32_bf16 v[100:103], v[162:165], v[194:197], v[100:103]
	v_mfma_f32_16x16x32_bf16 v[92:95], v[152:155], v[202:205], v[92:95]
	v_mfma_f32_16x16x32_bf16 v[84:87], v[162:165], v[202:205], v[84:87]
	v_mfma_f32_16x16x32_bf16 v[76:79], v[152:155], v[210:213], v[76:79]
	v_mfma_f32_16x16x32_bf16 v[68:71], v[162:165], v[210:213], v[68:71]
	v_mfma_f32_16x16x32_bf16 v[124:127], v[156:159], v[190:193], v[124:127]
	v_mfma_f32_16x16x32_bf16 v[116:119], v[166:169], v[190:193], v[116:119]
	v_mfma_f32_16x16x32_bf16 v[108:111], v[156:159], v[198:201], v[108:111]
	v_mfma_f32_16x16x32_bf16 v[100:103], v[166:169], v[198:201], v[100:103]
	v_mfma_f32_16x16x32_bf16 v[92:95], v[156:159], v[206:209], v[92:95]
	v_mfma_f32_16x16x32_bf16 v[84:87], v[166:169], v[206:209], v[84:87]
	v_mfma_f32_16x16x32_bf16 v[76:79], v[156:159], v[214:217], v[76:79]
	v_mfma_f32_16x16x32_bf16 v[68:71], v[166:169], v[214:217], v[68:71]
	v_mfma_f32_16x16x32_bf16 v[120:123], v[170:173], v[186:189], v[120:123]
	v_mfma_f32_16x16x32_bf16 v[112:115], v[178:181], v[186:189], v[112:115]
	v_mfma_f32_16x16x32_bf16 v[104:107], v[170:173], v[194:197], v[104:107]
	v_mfma_f32_16x16x32_bf16 v[96:99], v[178:181], v[194:197], v[96:99]
	v_mfma_f32_16x16x32_bf16 v[88:91], v[170:173], v[202:205], v[88:91]
	v_mfma_f32_16x16x32_bf16 v[80:83], v[178:181], v[202:205], v[80:83]
	v_mfma_f32_16x16x32_bf16 v[72:75], v[170:173], v[210:213], v[72:75]
	v_mfma_f32_16x16x32_bf16 v[64:67], v[178:181], v[210:213], v[64:67]
	v_mfma_f32_16x16x32_bf16 v[120:123], v[174:177], v[190:193], v[120:123]
	v_mfma_f32_16x16x32_bf16 v[112:115], v[182:185], v[190:193], v[112:115]
	v_mfma_f32_16x16x32_bf16 v[104:107], v[174:177], v[198:201], v[104:107]
	v_mfma_f32_16x16x32_bf16 v[96:99], v[182:185], v[198:201], v[96:99]
	v_mfma_f32_16x16x32_bf16 v[88:91], v[174:177], v[206:209], v[88:91]
	v_mfma_f32_16x16x32_bf16 v[80:83], v[182:185], v[206:209], v[80:83]
	v_mfma_f32_16x16x32_bf16 v[72:75], v[174:177], v[214:217], v[72:75]
	v_mfma_f32_16x16x32_bf16 v[64:67], v[182:185], v[214:217], v[64:67]
	s_barrier
	s_add_i32 s79, s66, s3
	v_lshl_add_u64 v[144:145], s[40:41], 0, v[132:133]
	s_mov_b32 m0, s79
	ds_read_b128 v[186:189], v151 offset:16384
	ds_read_b128 v[190:193], v151 offset:17408
	ds_read_b128 v[194:197], v151 offset:18432
	ds_read_b128 v[198:201], v151 offset:19456
	ds_read_b128 v[202:205], v151 offset:20480
	ds_read_b128 v[206:209], v151 offset:21504
	ds_read_b128 v[210:213], v151 offset:22528
	ds_read_b128 v[214:217], v151 offset:23552
	global_load_lds_dwordx4 v[144:145], off
	s_add_i32 m0, s79, 0x2000
	s_add_u32 s80, s40, 0x40000
	v_lshl_add_u64 v[218:219], s[40:41], 0, v[128:129]
	s_addc_u32 s81, s41, 0
	s_add_i32 s79, s67, s3
	global_load_lds_dwordx4 v[218:219], off
	v_lshl_add_u64 v[220:221], s[80:81], 0, v[132:133]
	s_mov_b32 m0, s79
	v_lshl_add_u64 v[222:223], s[52:53], 0, v[130:131]
	global_load_lds_dwordx4 v[220:221], off
	v_lshl_add_u64 v[220:221], s[80:81], 0, v[128:129]
	s_add_i32 m0, s79, 0x2000
	s_nop 0
	global_load_lds_dwordx4 v[220:221], off
	v_lshl_add_u64 v[220:221], s[52:53], 0, v[134:135]
	s_mov_b32 m0, s37
	s_nop 0
	global_load_lds_dwordx4 v[220:221], off
	s_mov_b32 m0, s56
	s_nop 0
	global_load_lds_dwordx4 v[222:223], off
	s_waitcnt vmcnt(8)
	s_waitcnt lgkmcnt(0)
	s_barrier
; #define PG8_STAGE(bufoff, gbase, voff) do { _Pragma("unroll") for (int _i = 0; _i < 2; ++_i) \
;         __builtin_amdgcn_global_load_lds((const unsigned*)((const char*)(gbase) + (voff)[_i]), (PG8_LAS unsigned*)(lds + (bufoff) + ldsw + _i * 8192), 16, 0, 0); } while (0)
; #define PG8_LDA(dst, b, h) do { _Pragma("unroll") for (int m = 0; m < 4; ++m) _Pragma("unroll") for (int k = 0; k < 2; ++k) dst[m][k] = *(const PG8_LAS bf16x8*)(lds + PG8_SA(b, h) + aoff + m * 2048 + k * 1024); } while (0)
; #define PG8_LDB(dst, b, h) do { _Pragma("unroll") for (int n = 0; n < 2; ++n) _Pragma("unroll") for (int k = 0; k < 2; ++k) dst[n][k] = *(const PG8_LAS bf16x8*)(lds + PG8_SB(b, h) + boff + n * 2048 + k * 1024); } while (0)
; #define PG8_MMA(ai, bj, At, Bt) do { __builtin_amdgcn_s_setprio(1); _Pragma("unroll") for (int m = 0; m < 4; ++m) _Pragma("unroll") for (int n = 0; n < 2; ++n) _Pragma("unroll") for (int k = 0; k < 2; ++k) \
;         acc[ai][bj][m][n] = __builtin_amdgcn_mfma_f32_16x16x32_bf16(Bt[n][k], At[m][k], acc[ai][bj][m][n], 0, 0, 0); __builtin_amdgcn_s_setprio(0); } while (0)
; #define PG8_WAIT_V(n) asm volatile("s_waitcnt vmcnt(" #n ")" ::: "memory")
; #define PG8_WAIT_L(n) asm volatile("s_waitcnt lgkmcnt(" #n ")" ::: "memory")
; #define PG8_BAR __builtin_amdgcn_s_barrier()
; #define PG8_SCHED __builtin_amdgcn_sched_barrier(0)
; template <class Epi, class Sched, bool ALIGN_EPI = false, bool SP2 = false>
; __device__ __forceinline__ void gemm_phase(PG8_LAS unsigned char* lds, const Gemm g, const Sched& S, const Epi& E) {
;     ...
;             PG8_WAIT_V(8); PG8_WAIT_L(0); PG8_BAR; PG8_MMA(0, 0, At, B0); PG8_MMA(0, 1, At, B1); PG8_BAR; PG8_SCHED;
;             PG8_LDA(At, 0, 1); PG8_STAGE(PG8_SB(0, 0), b2, voffB); PG8_STAGE(PG8_SB(0, 1), b2 + hstep, voffB); PG8_STAGE(PG8_SA(0, 0), a2, voffA);
;             PG8_WAIT_V(8); PG8_WAIT_L(0); PG8_BAR; PG8_MMA(1, 0, At, B0); PG8_MMA(1, 1, At, B1); PG8_BAR; PG8_SCHED;
;             PG8_LDB(B0, 1, 0); PG8_LDB(B1, 1, 1); PG8_SCHED; PG8_LDA(At, 1, 0); PG8_STAGE(PG8_SA(0, 1), a2 + hstep, voffA);
;             PG8_WAIT_V(8); PG8_WAIT_L(0); PG8_BAR; PG8_MMA(0, 0, At, B0); PG8_MMA(0, 1, At, B1); PG8_BAR; PG8_SCHED;
	s_waitcnt lgkmcnt(0)
	v_mfma_f32_16x16x32_bf16 v[60:63], v[152:155], v[186:189], v[60:63]
	v_mfma_f32_16x16x32_bf16 v[52:55], v[162:165], v[186:189], v[52:55]
	v_mfma_f32_16x16x32_bf16 v[44:47], v[152:155], v[194:197], v[44:47]
	v_mfma_f32_16x16x32_bf16 v[36:39], v[162:165], v[194:197], v[36:39]
	v_mfma_f32_16x16x32_bf16 v[28:31], v[152:155], v[202:205], v[28:31]
	v_mfma_f32_16x16x32_bf16 v[20:23], v[162:165], v[202:205], v[20:23]
	v_mfma_f32_16x16x32_bf16 v[12:15], v[152:155], v[210:213], v[12:15]
	v_mfma_f32_16x16x32_bf16 v[4:7], v[162:165], v[210:213], v[4:7]
	v_mfma_f32_16x16x32_bf16 v[60:63], v[156:159], v[190:193], v[60:63]
	v_mfma_f32_16x16x32_bf16 v[52:55], v[166:169], v[190:193], v[52:55]
	v_mfma_f32_16x16x32_bf16 v[44:47], v[156:159], v[198:201], v[44:47]
	v_mfma_f32_16x16x32_bf16 v[36:39], v[166:169], v[198:201], v[36:39]
	v_mfma_f32_16x16x32_bf16 v[28:31], v[156:159], v[206:209], v[28:31]
	v_mfma_f32_16x16x32_bf16 v[20:23], v[166:169], v[206:209], v[20:23]
	v_mfma_f32_16x16x32_bf16 v[12:15], v[156:159], v[214:217], v[12:15]
	v_mfma_f32_16x16x32_bf16 v[4:7], v[166:169], v[214:217], v[4:7]
	v_mfma_f32_16x16x32_bf16 v[56:59], v[170:173], v[186:189], v[56:59]
	v_mfma_f32_16x16x32_bf16 v[48:51], v[178:181], v[186:189], v[48:51]
	v_mfma_f32_16x16x32_bf16 v[40:43], v[170:173], v[194:197], v[40:43]
	v_mfma_f32_16x16x32_bf16 v[32:35], v[178:181], v[194:197], v[32:35]
	v_mfma_f32_16x16x32_bf16 v[24:27], v[170:173], v[202:205], v[24:27]
	v_mfma_f32_16x16x32_bf16 v[16:19], v[178:181], v[202:205], v[16:19]
	v_mfma_f32_16x16x32_bf16 v[8:11], v[170:173], v[210:213], v[8:11]
	v_mfma_f32_16x16x32_bf16 v[0:3], v[178:181], v[210:213], v[0:3]
	v_mfma_f32_16x16x32_bf16 v[56:59], v[174:177], v[190:193], v[56:59]
	v_mfma_f32_16x16x32_bf16 v[48:51], v[182:185], v[190:193], v[48:51]
	v_mfma_f32_16x16x32_bf16 v[40:43], v[174:177], v[198:201], v[40:43]
	v_mfma_f32_16x16x32_bf16 v[32:35], v[182:185], v[198:201], v[32:35]
	v_mfma_f32_16x16x32_bf16 v[24:27], v[174:177], v[206:209], v[24:27]
	v_mfma_f32_16x16x32_bf16 v[16:19], v[182:185], v[206:209], v[16:19]
	v_mfma_f32_16x16x32_bf16 v[8:11], v[174:177], v[214:217], v[8:11]
	v_mfma_f32_16x16x32_bf16 v[0:3], v[182:185], v[214:217], v[0:3]
	s_barrier
	s_add_i32 s79, 0, 0x18000
	v_add_u32_e32 v161, s79, v147
	s_add_i32 s80, 0, 0x1c000
	ds_read_b128 v[152:155], v161
	ds_read_b128 v[156:159], v161 offset:1024
	ds_read_b128 v[162:165], v161 offset:2048
	ds_read_b128 v[166:169], v161 offset:3072
	v_add_u32_e32 v161, s80, v147
	ds_read_b128 v[170:173], v161
	ds_read_b128 v[174:177], v161 offset:1024
	ds_read_b128 v[178:181], v161 offset:2048
	ds_read_b128 v[182:185], v161 offset:3072
	s_add_u32 s52, s52, 0x40000
	s_addc_u32 s53, s53, 0
	s_mov_b32 m0, s57
	v_lshl_add_u64 v[224:225], s[52:53], 0, v[134:135]
	ds_read_b128 v[186:189], v151 offset:32768
	ds_read_b128 v[190:193], v151 offset:33792
	ds_read_b128 v[194:197], v151 offset:34816
	ds_read_b128 v[198:201], v151 offset:35840
	ds_read_b128 v[202:205], v151 offset:36864
	ds_read_b128 v[206:209], v151 offset:37888
	ds_read_b128 v[210:213], v151 offset:38912
	ds_read_b128 v[214:217], v151 offset:39936
	global_load_lds_dwordx4 v[224:225], off
	v_lshl_add_u64 v[224:225], s[52:53], 0, v[130:131]
	s_mov_b32 m0, s58
	s_nop 0
	global_load_lds_dwordx4 v[224:225], off
	s_waitcnt vmcnt(8)
	s_waitcnt lgkmcnt(0)
	s_barrier
	s_waitcnt lgkmcnt(0)
	v_mfma_f32_16x16x32_bf16 v[124:127], v[152:155], v[186:189], v[124:127]
	v_mfma_f32_16x16x32_bf16 v[116:119], v[162:165], v[186:189], v[116:119]
	v_mfma_f32_16x16x32_bf16 v[108:111], v[152:155], v[194:197], v[108:111]
	v_mfma_f32_16x16x32_bf16 v[100:103], v[162:165], v[194:197], v[100:103]
	v_mfma_f32_16x16x32_bf16 v[92:95], v[152:155], v[202:205], v[92:95]
	v_mfma_f32_16x16x32_bf16 v[84:87], v[162:165], v[202:205], v[84:87]
	v_mfma_f32_16x16x32_bf16 v[76:79], v[152:155], v[210:213], v[76:79]
	v_mfma_f32_16x16x32_bf16 v[68:71], v[162:165], v[210:213], v[68:71]
	v_mfma_f32_16x16x32_bf16 v[124:127], v[156:159], v[190:193], v[124:127]
	v_mfma_f32_16x16x32_bf16 v[116:119], v[166:169], v[190:193], v[116:119]
	v_mfma_f32_16x16x32_bf16 v[108:111], v[156:159], v[198:201], v[108:111]
	v_mfma_f32_16x16x32_bf16 v[100:103], v[166:169], v[198:201], v[100:103]
	v_mfma_f32_16x16x32_bf16 v[92:95], v[156:159], v[206:209], v[92:95]
	v_mfma_f32_16x16x32_bf16 v[84:87], v[166:169], v[206:209], v[84:87]
	v_mfma_f32_16x16x32_bf16 v[76:79], v[156:159], v[214:217], v[76:79]
	v_mfma_f32_16x16x32_bf16 v[68:71], v[166:169], v[214:217], v[68:71]
	v_mfma_f32_16x16x32_bf16 v[120:123], v[170:173], v[186:189], v[120:123]
	v_mfma_f32_16x16x32_bf16 v[112:115], v[178:181], v[186:189], v[112:115]
	v_mfma_f32_16x16x32_bf16 v[104:107], v[170:173], v[194:197], v[104:107]
	v_mfma_f32_16x16x32_bf16 v[96:99], v[178:181], v[194:197], v[96:99]
	v_mfma_f32_16x16x32_bf16 v[88:91], v[170:173], v[202:205], v[88:91]
	v_mfma_f32_16x16x32_bf16 v[80:83], v[178:181], v[202:205], v[80:83]
	v_mfma_f32_16x16x32_bf16 v[72:75], v[170:173], v[210:213], v[72:75]
	v_mfma_f32_16x16x32_bf16 v[64:67], v[178:181], v[210:213], v[64:67]
	v_mfma_f32_16x16x32_bf16 v[120:123], v[174:177], v[190:193], v[120:123]
	v_mfma_f32_16x16x32_bf16 v[112:115], v[182:185], v[190:193], v[112:115]
	v_mfma_f32_16x16x32_bf16 v[104:107], v[174:177], v[198:201], v[104:107]
	v_mfma_f32_16x16x32_bf16 v[96:99], v[182:185], v[198:201], v[96:99]
	v_mfma_f32_16x16x32_bf16 v[88:91], v[174:177], v[206:209], v[88:91]
	v_mfma_f32_16x16x32_bf16 v[80:83], v[182:185], v[206:209], v[80:83]
	v_mfma_f32_16x16x32_bf16 v[72:75], v[174:177], v[214:217], v[72:75]
	v_mfma_f32_16x16x32_bf16 v[64:67], v[182:185], v[214:217], v[64:67]
	s_barrier
; #define PG8_STAGE(bufoff, gbase, voff) do { _Pragma("unroll") for (int _i = 0; _i < 2; ++_i) \
;         __builtin_amdgcn_global_load_lds((const unsigned*)((const char*)(gbase) + (voff)[_i]), (PG8_LAS unsigned*)(lds + (bufoff) + ldsw + _i * 8192), 16, 0, 0); } while (0)
; #define PG8_LDA(dst, b, h) do { _Pragma("unroll") for (int m = 0; m < 4; ++m) _Pragma("unroll") for (int k = 0; k < 2; ++k) dst[m][k] = *(const PG8_LAS bf16x8*)(lds + PG8_SA(b, h) + aoff + m * 2048 + k * 1024); } while (0)
; #define PG8_MMA(ai, bj, At, Bt) do { __builtin_amdgcn_s_setprio(1); _Pragma("unroll") for (int m = 0; m < 4; ++m) _Pragma("unroll") for (int n = 0; n < 2; ++n) _Pragma("unroll") for (int k = 0; k < 2; ++k) \
;         acc[ai][bj][m][n] = __builtin_amdgcn_mfma_f32_16x16x32_bf16(Bt[n][k], At[m][k], acc[ai][bj][m][n], 0, 0, 0); __builtin_amdgcn_s_setprio(0); } while (0)
; #define PG8_WAIT_V(n) asm volatile("s_waitcnt vmcnt(" #n ")" ::: "memory")
; #define PG8_WAIT_L(n) asm volatile("s_waitcnt lgkmcnt(" #n ")" ::: "memory")
; #define PG8_BAR __builtin_amdgcn_s_barrier()
; #define PG8_SCHED __builtin_amdgcn_sched_barrier(0)
; template <class Epi, class Sched, bool ALIGN_EPI = false, bool SP2 = false>
; __device__ __forceinline__ void gemm_phase(PG8_LAS unsigned char* lds, const Gemm g, const Sched& S, const Epi& E) {
;     ...
;             PG8_LDA(At, 1, 1); PG8_STAGE(PG8_SB(1, 0), b3, voffB); PG8_STAGE(PG8_SB(1, 1), b3 + hstep, voffB); PG8_STAGE(PG8_SA(1, 0), a3, voffA);
;             PG8_WAIT_V(8); PG8_WAIT_L(0); PG8_BAR; PG8_MMA(1, 0, At, B0); PG8_MMA(1, 1, At, B1); PG8_BAR; PG8_SCHED;
	s_add_i32 s52, s79, s3
	v_lshl_add_u64 v[144:145], v[144:145], 0, s[12:13]
	s_mov_b32 m0, s52
	ds_read_b128 v[186:189], v151 offset:49152
	ds_read_b128 v[190:193], v151 offset:50176
	ds_read_b128 v[194:197], v151 offset:51200
	ds_read_b128 v[198:201], v151 offset:52224
	ds_read_b128 v[202:205], v151 offset:53248
	ds_read_b128 v[206:209], v151 offset:54272
	ds_read_b128 v[210:213], v151 offset:55296
	ds_read_b128 v[214:217], v151 offset:56320
	global_load_lds_dwordx4 v[144:145], off
	s_add_i32 m0, s52, 0x2000
	s_add_u32 s40, s40, 0x40080
	v_lshl_add_u64 v[144:145], v[218:219], 0, s[12:13]
	s_addc_u32 s41, s41, 0
	s_add_i32 s52, s80, s3
	global_load_lds_dwordx4 v[144:145], off
	v_lshl_add_u64 v[144:145], s[40:41], 0, v[132:133]
	s_mov_b32 m0, s52
	s_nop 0
	global_load_lds_dwordx4 v[144:145], off
	v_lshl_add_u64 v[144:145], s[40:41], 0, v[128:129]
	s_add_i32 m0, s52, 0x2000
	s_nop 0
	global_load_lds_dwordx4 v[144:145], off
	v_lshl_add_u64 v[144:145], v[220:221], 0, s[12:13]
	s_mov_b32 m0, s62
	s_nop 0
	global_load_lds_dwordx4 v[144:145], off
	v_lshl_add_u64 v[144:145], v[222:223], 0, s[12:13]
	s_mov_b32 m0, s63
	s_nop 0
	global_load_lds_dwordx4 v[144:145], off
	s_waitcnt vmcnt(8)
	s_waitcnt lgkmcnt(0)
	s_barrier
	s_waitcnt lgkmcnt(0)
	v_mfma_f32_16x16x32_bf16 v[60:63], v[152:155], v[186:189], v[60:63]
	v_mfma_f32_16x16x32_bf16 v[52:55], v[162:165], v[186:189], v[52:55]
	v_mfma_f32_16x16x32_bf16 v[44:47], v[152:155], v[194:197], v[44:47]
	v_mfma_f32_16x16x32_bf16 v[36:39], v[162:165], v[194:197], v[36:39]
	v_mfma_f32_16x16x32_bf16 v[28:31], v[152:155], v[202:205], v[28:31]
	v_mfma_f32_16x16x32_bf16 v[20:23], v[162:165], v[202:205], v[20:23]
	v_mfma_f32_16x16x32_bf16 v[12:15], v[152:155], v[210:213], v[12:15]
	v_mfma_f32_16x16x32_bf16 v[4:7], v[162:165], v[210:213], v[4:7]
	v_mfma_f32_16x16x32_bf16 v[60:63], v[156:159], v[190:193], v[60:63]
	v_mfma_f32_16x16x32_bf16 v[52:55], v[166:169], v[190:193], v[52:55]
	v_mfma_f32_16x16x32_bf16 v[44:47], v[156:159], v[198:201], v[44:47]
	v_mfma_f32_16x16x32_bf16 v[36:39], v[166:169], v[198:201], v[36:39]
	v_mfma_f32_16x16x32_bf16 v[28:31], v[156:159], v[206:209], v[28:31]
	v_mfma_f32_16x16x32_bf16 v[20:23], v[166:169], v[206:209], v[20:23]
	v_mfma_f32_16x16x32_bf16 v[12:15], v[156:159], v[214:217], v[12:15]
	v_mfma_f32_16x16x32_bf16 v[4:7], v[166:169], v[214:217], v[4:7]
	v_mfma_f32_16x16x32_bf16 v[56:59], v[170:173], v[186:189], v[56:59]
	v_mfma_f32_16x16x32_bf16 v[48:51], v[178:181], v[186:189], v[48:51]
	v_mfma_f32_16x16x32_bf16 v[40:43], v[170:173], v[194:197], v[40:43]
	v_mfma_f32_16x16x32_bf16 v[32:35], v[178:181], v[194:197], v[32:35]
	v_mfma_f32_16x16x32_bf16 v[24:27], v[170:173], v[202:205], v[24:27]
	v_mfma_f32_16x16x32_bf16 v[16:19], v[178:181], v[202:205], v[16:19]
	v_mfma_f32_16x16x32_bf16 v[8:11], v[170:173], v[210:213], v[8:11]
	v_mfma_f32_16x16x32_bf16 v[0:3], v[178:181], v[210:213], v[0:3]
	v_mfma_f32_16x16x32_bf16 v[56:59], v[174:177], v[190:193], v[56:59]
	v_mfma_f32_16x16x32_bf16 v[48:51], v[182:185], v[190:193], v[48:51]
	v_mfma_f32_16x16x32_bf16 v[40:43], v[174:177], v[198:201], v[40:43]
	v_mfma_f32_16x16x32_bf16 v[32:35], v[182:185], v[198:201], v[32:35]
	v_mfma_f32_16x16x32_bf16 v[24:27], v[174:177], v[206:209], v[24:27]
	v_mfma_f32_16x16x32_bf16 v[16:19], v[182:185], v[206:209], v[16:19]
	v_mfma_f32_16x16x32_bf16 v[8:11], v[174:177], v[214:217], v[8:11]
	v_mfma_f32_16x16x32_bf16 v[0:3], v[182:185], v[214:217], v[0:3]
	s_barrier
	s_add_i32 s78, s78, 2
	s_add_u32 s38, s38, 0x100
	s_addc_u32 s39, s39, 0
	s_add_u32 s76, s76, 0x100
	s_addc_u32 s77, s77, 0
	s_cmp_gt_u32 s78, 13
	s_cbranch_scc0 .LBB0_194
	s_and_b64 vcc, exec, s[14:15]
	s_cbranch_vccz .LBB0_197
	s_barrier

; #define PG8_WAIT_V(n) asm volatile("s_waitcnt vmcnt(" #n ")" ::: "memory")
; #define PG8_BAR __builtin_amdgcn_s_barrier()
; template <class Epi, class Sched, bool ALIGN_EPI = false, bool SP2 = false>
; __device__ __forceinline__ void gemm_phase(PG8_LAS unsigned char* lds, const Gemm g, const Sched& S, const Epi& E) {
;     ...
;     PG8_WAIT_V(0);
;     if constexpr (!ALIGN_EPI) { if (wr == 0) PG8_BAR; }
;     PG8_BAR;
.LBB0_200:
	s_setprio 0
	s_waitcnt vmcnt(0)
	s_barrier

; #define PG8_STAGE(bufoff, gbase, voff) do { _Pragma("unroll") for (int _i = 0; _i < 2; ++_i) \
;         __builtin_amdgcn_global_load_lds((const unsigned*)((const char*)(gbase) + (voff)[_i]), (PG8_LAS unsigned*)(lds + (bufoff) + ldsw + _i * 8192), 16, 0, 0); } while (0)
; #define PG8_BAR __builtin_amdgcn_s_barrier()
;     __device__ bool next(int i, Unit& u) const { if (i > 1 || !so.next(0, u)) return false; if (i == 1) { u.pm += 64; u.pn += 4; } return true; }
; template <class Epi, class Sched, bool ALIGN_EPI = false, bool SP2 = false>
; __device__ __forceinline__ void gemm_phase(PG8_LAS unsigned char* lds, const Gemm g, const Sched& S, const Epi& E) {
;     ...
;     for (int i = 0; i < 2; ++i) { int R, C; stage_rc(tid * 16 + i * 8192, R, C); const int Rb = Epi::PERM ? ((R & ~31) + perm32(R & 31)) : R;
;         voffA[i] = (unsigned)(R * K + C) * 2u; voffB[i] = (unsigned)(Rb * K + C) * 2u; }
;     const size_t kstep = (size_t)(BK * 2);
;     const size_t hstep = (size_t)HALF * K * 2;
;     const size_t tstep = 2 * hstep;
;     const unsigned ldsw = (unsigned)wid * 1024u;
;     const int aoff = lds_byte(wr * 64 + fr, fq * 8), boff = lds_byte(wc * 32 + fr, fq * 8);
;     ...
;     Unit cur, nxt; int ui = 0;
;     if (!S.next(0, cur)) return;
;     f32x4 acc[2][2][4][2];
; #pragma unroll
;     for (int a = 0; a < 2; ++a)
; #pragma unroll
;         for (int b = 0; b < 2; ++b)
; #pragma unroll
;             for (int m = 0; m < 4; ++m)
; #pragma unroll
;                 for (int n = 0; n < 2; ++n) acc[a][b][m][n] = (f32x4){0.f, 0.f, 0.f, 0.f};
;     bf16x8 At[4][2], B0[2][2], B1[2][2];
;     const char* cA = (const char*)g.A + (size_t)cur.pm * tstep; const char* cB = (const char*)g.Bt + (size_t)cur.pn * tstep;
;     S.a_ready(cur);
;     if constexpr (SP2) {
;         PG8_STAGE(PG8_SB(0, 0), cB, voffB); PG8_STAGE(PG8_SB(0, 1), cB + hstep, voffB); PG8_STAGE(PG8_SA(0, 0), cA, voffA); PG8_STAGE(PG8_SA(0, 1), cA + hstep, voffA);
;         if (wr == 1) PG8_BAR;
.LBB0_272:
	s_andn2_b64 vcc, exec, s[0:1]
	s_cbranch_vccnz .LBB0_312
	v_lshrrev_b32_e32 v3, 1, v226
	v_lshrrev_b32_e32 v4, 5, v226
	v_and_b32_e32 v3, 24, v3
	v_and_b32_e32 v4, 4, v4
	v_bfe_u32 v5, v226, 2, 2
	v_lshlrev_b32_e32 v0, 4, v226
	v_and_b32_e32 v1, 32, v226
	v_bfe_u32 v2, v226, 2, 4
	v_or3_b32 v3, v4, v5, v3
	v_lshrrev_b32_e32 v4, 3, v226
	s_movk_i32 s0, 0x70
	v_bitop3_b32 v8, v0, v1, 48 bitop3:0x6c
	v_and_or_b32 v5, v4, s0, v2
	s_movk_i32 s0, 0x60
	v_add_u32_e32 v0, 0x2000, v0
	v_and_or_b32 v4, v4, s0, v3
	v_lshrrev_b32_e32 v0, 7, v0
	s_movk_i32 s0, 0xf0
	s_lshr_b32 s1, s6, 6
	v_and_b32_e32 v9, 64, v226
	v_and_or_b32 v2, v0, s0, v2
	s_movk_i32 s0, 0xe0
	v_or_b32_e32 v1, v8, v9
	v_and_or_b32 v0, v0, s0, v3
	s_lshr_b32 s0, s6, 8
	s_lshl_b32 s3, s1, 10
	s_mul_i32 s5, s12, 0x160000
	v_lshrrev_b32_e32 v1, 1, v1
	v_mul_u32_u24_e32 v4, 0xb00, v4
	s_mul_hi_i32 s4, s12, 0x160000
	s_add_u32 s34, s92, s5
	v_or_b32_e32 v4, v4, v1
	s_addc_u32 s35, s93, s4
	s_add_i32 s38, s3, 0
	v_lshlrev_b32_e32 v130, 1, v4
	v_mul_u32_u24_e32 v0, 0xb00, v0
	s_add_i32 m0, s38, 0x10000
	v_or_b32_e32 v0, v0, v1
	global_load_lds_dwordx4 v130, s[34:35]
	s_add_i32 m0, s38, 0x12000
	v_lshlrev_b32_e32 v134, 1, v0
	s_add_u32 s4, s34, 0xb0000
	global_load_lds_dwordx4 v134, s[34:35]
	s_addc_u32 s5, s35, 0
	s_add_i32 m0, s38, 0x14000
	s_mul_i32 s13, s65, 0x160000
	global_load_lds_dwordx4 v130, s[4:5]
	s_add_i32 m0, s38, 0x16000
	v_mul_u32_u24_e32 v10, 0xb00, v5
	s_mul_hi_i32 s7, s65, 0x160000
	s_add_u32 s22, s24, s13
	v_or_b32_e32 v5, v1, v10
	v_mul_u32_u24_e32 v11, 0xb00, v2
	s_addc_u32 s23, s25, s7
	s_add_i32 s39, s38, 0x2000
	v_lshlrev_b32_e32 v128, 1, v5
	v_or_b32_e32 v2, v11, v1
	global_load_lds_dwordx4 v134, s[4:5]
	s_mov_b32 m0, s38
	s_add_u32 s4, s22, 0xb0000
	v_lshlrev_b32_e32 v132, 1, v2
	global_load_lds_dwordx4 v128, s[22:23]
	s_mov_b32 m0, s39
	s_addc_u32 s5, s23, 0
	s_add_i32 s40, s38, 0x4000
	global_load_lds_dwordx4 v132, s[22:23]
	s_mov_b32 m0, s40
	s_add_i32 s41, s38, 0x6000
	global_load_lds_dwordx4 v128, s[4:5]
	s_mov_b32 m0, s41
	v_mov_b32_e32 v131, 0
	global_load_lds_dwordx4 v132, s[4:5]
	v_mov_b32_e32 v135, v131
	v_mov_b32_e32 v129, v131
	v_mov_b32_e32 v133, v131
	s_cmp_eq_u32 s0, 1
	s_mov_b32 s13, 0
	v_lshl_add_u64 v[6:7], s[34:35], 0, v[130:131]
	v_lshl_add_u64 v[4:5], s[34:35], 0, v[134:135]
	v_lshl_add_u64 v[0:1], s[22:23], 0, v[128:129]
	s_cselect_b64 s[14:15], -1, 0
	s_cmp_lg_u32 s0, 1
	v_lshl_add_u64 v[2:3], s[22:23], 0, v[132:133]
	s_cbranch_scc1 .LBB0_275
	s_barrier
	s_setprio 1

; #define PG8_STAGE(bufoff, gbase, voff) do { _Pragma("unroll") for (int _i = 0; _i < 2; ++_i) \
;         __builtin_amdgcn_global_load_lds((const unsigned*)((const char*)(gbase) + (voff)[_i]), (PG8_LAS unsigned*)(lds + (bufoff) + ldsw + _i * 8192), 16, 0, 0); } while (0)
; #define PG8_LDA(dst, b, h) do { _Pragma("unroll") for (int m = 0; m < 4; ++m) _Pragma("unroll") for (int k = 0; k < 2; ++k) dst[m][k] = *(const PG8_LAS bf16x8*)(lds + PG8_SA(b, h) + aoff + m * 2048 + k * 1024); } while (0)
; #define PG8_LDB(dst, b, h) do { _Pragma("unroll") for (int n = 0; n < 2; ++n) _Pragma("unroll") for (int k = 0; k < 2; ++k) dst[n][k] = *(const PG8_LAS bf16x8*)(lds + PG8_SB(b, h) + boff + n * 2048 + k * 1024); } while (0)
; #define PG8_MMA(ai, bj, At, Bt) do { __builtin_amdgcn_s_setprio(1); _Pragma("unroll") for (int m = 0; m < 4; ++m) _Pragma("unroll") for (int n = 0; n < 2; ++n) _Pragma("unroll") for (int k = 0; k < 2; ++k) \
;         acc[ai][bj][m][n] = __builtin_amdgcn_mfma_f32_16x16x32_bf16(Bt[n][k], At[m][k], acc[ai][bj][m][n], 0, 0, 0); __builtin_amdgcn_s_setprio(0); } while (0)
; #define PG8_WAIT_V(n) asm volatile("s_waitcnt vmcnt(" #n ")" ::: "memory")
; #define PG8_WAIT_L(n) asm volatile("s_waitcnt lgkmcnt(" #n ")" ::: "memory")
; template <class Epi, class Sched, bool ALIGN_EPI = false, bool SP2 = false>
; __device__ __forceinline__ void gemm_phase(PG8_LAS unsigned char* lds, const Gemm g, const Sched& S, const Epi& E) {
;     ...
;             const bool last = (t == nt - 2);
;             const char* a1 = cA + (size_t)(t + 1) * kstep;
;             const char* a2 = last ? nA : cA + (size_t)(t + 2) * kstep; const char* b2 = last ? nB : cB + (size_t)(t + 2) * kstep;
;             const char* a3 = a2 + kstep; const char* b3 = b2 + kstep;
;             if (last && has_next) S.a_ready(nxt);
;             if constexpr (SP2) {
;             PG8_LDB(B0, 0, 0); PG8_LDB(B1, 0, 1); PG8_SCHED; PG8_LDA(At, 0, 0); PG8_STAGE(PG8_SA(1, 1), a1 + hstep, voffA);
;             PG8_WAIT_V(8); PG8_WAIT_L(0); PG8_BAR; PG8_MMA(0, 0, At, B0); PG8_MMA(0, 1, At, B1); PG8_BAR; PG8_SCHED;
;             PG8_LDA(At, 0, 1); PG8_STAGE(PG8_SB(0, 0), b2, voffB); PG8_STAGE(PG8_SB(0, 1), b2 + hstep, voffB); PG8_STAGE(PG8_SA(0, 0), a2, voffA);
;             PG8_WAIT_V(8); PG8_WAIT_L(0); PG8_BAR; PG8_MMA(1, 0, At, B0); PG8_MMA(1, 1, At, B1); PG8_BAR; PG8_SCHED;
.LBB0_289:
	ds_read_b128 v[144:147], v168
	ds_read_b128 v[148:151], v168 offset:1024
	ds_read_b128 v[152:155], v168 offset:2048
	ds_read_b128 v[156:159], v168 offset:3072
	ds_read_b128 v[162:165], v169
	ds_read_b128 v[172:175], v169 offset:1024
	ds_read_b128 v[176:179], v169 offset:2048
	ds_read_b128 v[180:183], v169 offset:3072
	s_add_u32 s34, s22, 0xfff50080
	s_addc_u32 s35, s23, -1
	s_cmp_eq_u32 s70, 40
	s_cselect_b32 s37, s1, s35
	s_cselect_b32 s36, s0, s34
	s_cselect_b32 s35, s21, s67
	s_cselect_b32 s34, s20, s66
	v_lshl_add_u64 v[216:217], s[22:23], 0, v[136:137]
	s_add_i32 m0, s38, 0xc000
	ds_read_b128 v[184:187], v170
	ds_read_b128 v[188:191], v170 offset:1024
	ds_read_b128 v[192:195], v170 offset:2048
	ds_read_b128 v[196:199], v170 offset:3072
	ds_read_b128 v[200:203], v170 offset:4096
	ds_read_b128 v[204:207], v170 offset:5120
	ds_read_b128 v[208:211], v170 offset:6144
	ds_read_b128 v[212:215], v170 offset:7168
	global_load_lds_dwordx4 v[216:217], off
	v_lshl_add_u64 v[216:217], s[22:23], 0, v[138:139]
	s_add_i32 m0, s38, 0xe000
	s_nop 0
	global_load_lds_dwordx4 v[216:217], off
	s_waitcnt vmcnt(8)
	s_waitcnt lgkmcnt(0)
	s_barrier
	s_waitcnt lgkmcnt(0)
	v_mfma_f32_16x16x32_bf16 v[124:127], v[144:147], v[184:187], v[124:127]
	v_mfma_f32_16x16x32_bf16 v[120:123], v[152:155], v[184:187], v[120:123]
	v_mfma_f32_16x16x32_bf16 v[108:111], v[144:147], v[192:195], v[108:111]
	v_mfma_f32_16x16x32_bf16 v[104:107], v[152:155], v[192:195], v[104:107]
	v_mfma_f32_16x16x32_bf16 v[92:95], v[144:147], v[200:203], v[92:95]
	v_mfma_f32_16x16x32_bf16 v[88:91], v[152:155], v[200:203], v[88:91]
	v_mfma_f32_16x16x32_bf16 v[76:79], v[144:147], v[208:211], v[76:79]
	v_mfma_f32_16x16x32_bf16 v[72:75], v[152:155], v[208:211], v[72:75]
	v_mfma_f32_16x16x32_bf16 v[124:127], v[148:151], v[188:191], v[124:127]
	v_mfma_f32_16x16x32_bf16 v[120:123], v[156:159], v[188:191], v[120:123]
	v_mfma_f32_16x16x32_bf16 v[108:111], v[148:151], v[196:199], v[108:111]
	v_mfma_f32_16x16x32_bf16 v[104:107], v[156:159], v[196:199], v[104:107]
	v_mfma_f32_16x16x32_bf16 v[92:95], v[148:151], v[204:207], v[92:95]
	v_mfma_f32_16x16x32_bf16 v[88:91], v[156:159], v[204:207], v[88:91]
	v_mfma_f32_16x16x32_bf16 v[76:79], v[148:151], v[212:215], v[76:79]
	v_mfma_f32_16x16x32_bf16 v[72:75], v[156:159], v[212:215], v[72:75]
	v_mfma_f32_16x16x32_bf16 v[116:119], v[162:165], v[184:187], v[116:119]
	v_mfma_f32_16x16x32_bf16 v[112:115], v[176:179], v[184:187], v[112:115]
	v_mfma_f32_16x16x32_bf16 v[100:103], v[162:165], v[192:195], v[100:103]
	v_mfma_f32_16x16x32_bf16 v[96:99], v[176:179], v[192:195], v[96:99]
	v_mfma_f32_16x16x32_bf16 v[84:87], v[162:165], v[200:203], v[84:87]
	v_mfma_f32_16x16x32_bf16 v[80:83], v[176:179], v[200:203], v[80:83]
	v_mfma_f32_16x16x32_bf16 v[68:71], v[162:165], v[208:211], v[68:71]
	v_mfma_f32_16x16x32_bf16 v[64:67], v[176:179], v[208:211], v[64:67]
	v_mfma_f32_16x16x32_bf16 v[116:119], v[172:175], v[188:191], v[116:119]
	v_mfma_f32_16x16x32_bf16 v[112:115], v[180:183], v[188:191], v[112:115]
	v_mfma_f32_16x16x32_bf16 v[100:103], v[172:175], v[196:199], v[100:103]
	v_mfma_f32_16x16x32_bf16 v[96:99], v[180:183], v[196:199], v[96:99]
	v_mfma_f32_16x16x32_bf16 v[84:87], v[172:175], v[204:207], v[84:87]
	v_mfma_f32_16x16x32_bf16 v[80:83], v[180:183], v[204:207], v[80:83]
	v_mfma_f32_16x16x32_bf16 v[68:71], v[172:175], v[212:215], v[68:71]
	v_mfma_f32_16x16x32_bf16 v[64:67], v[180:183], v[212:215], v[64:67]
	s_barrier
	s_add_i32 s71, s58, s3
	v_lshl_add_u64 v[216:217], s[34:35], 0, v[130:131]
	s_mov_b32 m0, s71
	ds_read_b128 v[184:187], v170 offset:16384
	ds_read_b128 v[188:191], v170 offset:17408
	ds_read_b128 v[192:195], v170 offset:18432
	ds_read_b128 v[196:199], v170 offset:19456
	ds_read_b128 v[200:203], v170 offset:20480
	ds_read_b128 v[204:207], v170 offset:21504
	ds_read_b128 v[208:211], v170 offset:22528
	ds_read_b128 v[212:215], v170 offset:23552
	global_load_lds_dwordx4 v[216:217], off
	s_add_i32 m0, s71, 0x2000
	s_add_u32 s72, s34, 0xb0000
	v_lshl_add_u64 v[218:219], s[34:35], 0, v[134:135]
	s_addc_u32 s73, s35, 0
	s_add_i32 s71, s59, s3
	global_load_lds_dwordx4 v[218:219], off
	v_lshl_add_u64 v[220:221], s[72:73], 0, v[130:131]
	s_mov_b32 m0, s71
	v_lshl_add_u64 v[222:223], s[36:37], 0, v[132:133]
	global_load_lds_dwordx4 v[220:221], off
	v_lshl_add_u64 v[220:221], s[72:73], 0, v[134:135]
	s_add_i32 m0, s71, 0x2000
	s_nop 0
	global_load_lds_dwordx4 v[220:221], off
	v_lshl_add_u64 v[220:221], s[36:37], 0, v[128:129]
	s_mov_b32 m0, s38
	s_nop 0
	global_load_lds_dwordx4 v[220:221], off
	s_mov_b32 m0, s39
	s_nop 0
	global_load_lds_dwordx4 v[222:223], off
	s_waitcnt vmcnt(8)
	s_waitcnt lgkmcnt(0)
	s_barrier
; #define PG8_STAGE(bufoff, gbase, voff) do { _Pragma("unroll") for (int _i = 0; _i < 2; ++_i) \
;         __builtin_amdgcn_global_load_lds((const unsigned*)((const char*)(gbase) + (voff)[_i]), (PG8_LAS unsigned*)(lds + (bufoff) + ldsw + _i * 8192), 16, 0, 0); } while (0)
; #define PG8_LDA(dst, b, h) do { _Pragma("unroll") for (int m = 0; m < 4; ++m) _Pragma("unroll") for (int k = 0; k < 2; ++k) dst[m][k] = *(const PG8_LAS bf16x8*)(lds + PG8_SA(b, h) + aoff + m * 2048 + k * 1024); } while (0)
; #define PG8_LDB(dst, b, h) do { _Pragma("unroll") for (int n = 0; n < 2; ++n) _Pragma("unroll") for (int k = 0; k < 2; ++k) dst[n][k] = *(const PG8_LAS bf16x8*)(lds + PG8_SB(b, h) + boff + n * 2048 + k * 1024); } while (0)
; #define PG8_MMA(ai, bj, At, Bt) do { __builtin_amdgcn_s_setprio(1); _Pragma("unroll") for (int m = 0; m < 4; ++m) _Pragma("unroll") for (int n = 0; n < 2; ++n) _Pragma("unroll") for (int k = 0; k < 2; ++k) \
;         acc[ai][bj][m][n] = __builtin_amdgcn_mfma_f32_16x16x32_bf16(Bt[n][k], At[m][k], acc[ai][bj][m][n], 0, 0, 0); __builtin_amdgcn_s_setprio(0); } while (0)
; #define PG8_WAIT_V(n) asm volatile("s_waitcnt vmcnt(" #n ")" ::: "memory")
; #define PG8_WAIT_L(n) asm volatile("s_waitcnt lgkmcnt(" #n ")" ::: "memory")
; #define PG8_BAR __builtin_amdgcn_s_barrier()
; #define PG8_SCHED __builtin_amdgcn_sched_barrier(0)
; template <class Epi, class Sched, bool ALIGN_EPI = false, bool SP2 = false>
; __device__ __forceinline__ void gemm_phase(PG8_LAS unsigned char* lds, const Gemm g, const Sched& S, const Epi& E) {
;     ...
;             PG8_WAIT_V(8); PG8_WAIT_L(0); PG8_BAR; PG8_MMA(1, 0, At, B0); PG8_MMA(1, 1, At, B1); PG8_BAR; PG8_SCHED;
;             PG8_LDB(B0, 1, 0); PG8_LDB(B1, 1, 1); PG8_SCHED; PG8_LDA(At, 1, 0); PG8_STAGE(PG8_SA(0, 1), a2 + hstep, voffA);
;             PG8_WAIT_V(8); PG8_WAIT_L(0); PG8_BAR; PG8_MMA(0, 0, At, B0); PG8_MMA(0, 1, At, B1); PG8_BAR; PG8_SCHED;
;             PG8_LDA(At, 1, 1); PG8_STAGE(PG8_SB(1, 0), b3, voffB); PG8_STAGE(PG8_SB(1, 1), b3 + hstep, voffB); PG8_STAGE(PG8_SA(1, 0), a3, voffA);
	s_waitcnt lgkmcnt(0)
	v_mfma_f32_16x16x32_bf16 v[60:63], v[144:147], v[184:187], v[60:63]
	v_mfma_f32_16x16x32_bf16 v[56:59], v[152:155], v[184:187], v[56:59]
	v_mfma_f32_16x16x32_bf16 v[44:47], v[144:147], v[192:195], v[44:47]
	v_mfma_f32_16x16x32_bf16 v[40:43], v[152:155], v[192:195], v[40:43]
	v_mfma_f32_16x16x32_bf16 v[28:31], v[144:147], v[200:203], v[28:31]
	v_mfma_f32_16x16x32_bf16 v[24:27], v[152:155], v[200:203], v[24:27]
	v_mfma_f32_16x16x32_bf16 v[12:15], v[144:147], v[208:211], v[12:15]
	v_mfma_f32_16x16x32_bf16 v[8:11], v[152:155], v[208:211], v[8:11]
	v_mfma_f32_16x16x32_bf16 v[60:63], v[148:151], v[188:191], v[60:63]
	v_mfma_f32_16x16x32_bf16 v[56:59], v[156:159], v[188:191], v[56:59]
	v_mfma_f32_16x16x32_bf16 v[44:47], v[148:151], v[196:199], v[44:47]
	v_mfma_f32_16x16x32_bf16 v[40:43], v[156:159], v[196:199], v[40:43]
	v_mfma_f32_16x16x32_bf16 v[28:31], v[148:151], v[204:207], v[28:31]
	v_mfma_f32_16x16x32_bf16 v[24:27], v[156:159], v[204:207], v[24:27]
	v_mfma_f32_16x16x32_bf16 v[12:15], v[148:151], v[212:215], v[12:15]
	v_mfma_f32_16x16x32_bf16 v[8:11], v[156:159], v[212:215], v[8:11]
	v_mfma_f32_16x16x32_bf16 v[52:55], v[162:165], v[184:187], v[52:55]
	v_mfma_f32_16x16x32_bf16 v[48:51], v[176:179], v[184:187], v[48:51]
	v_mfma_f32_16x16x32_bf16 v[36:39], v[162:165], v[192:195], v[36:39]
	v_mfma_f32_16x16x32_bf16 v[32:35], v[176:179], v[192:195], v[32:35]
	v_mfma_f32_16x16x32_bf16 v[20:23], v[162:165], v[200:203], v[20:23]
	v_mfma_f32_16x16x32_bf16 v[16:19], v[176:179], v[200:203], v[16:19]
	v_mfma_f32_16x16x32_bf16 v[4:7], v[162:165], v[208:211], v[4:7]
	v_mfma_f32_16x16x32_bf16 v[0:3], v[176:179], v[208:211], v[0:3]
	v_mfma_f32_16x16x32_bf16 v[52:55], v[172:175], v[188:191], v[52:55]
	v_mfma_f32_16x16x32_bf16 v[48:51], v[180:183], v[188:191], v[48:51]
	v_mfma_f32_16x16x32_bf16 v[36:39], v[172:175], v[196:199], v[36:39]
	v_mfma_f32_16x16x32_bf16 v[32:35], v[180:183], v[196:199], v[32:35]
	v_mfma_f32_16x16x32_bf16 v[20:23], v[172:175], v[204:207], v[20:23]
	v_mfma_f32_16x16x32_bf16 v[16:19], v[180:183], v[204:207], v[16:19]
	v_mfma_f32_16x16x32_bf16 v[4:7], v[172:175], v[212:215], v[4:7]
	v_mfma_f32_16x16x32_bf16 v[0:3], v[180:183], v[212:215], v[0:3]
	s_barrier
	s_add_i32 s71, 0, 0x18000
	s_add_i32 s72, 0, 0x1c000
	v_add_u32_e32 v156, s71, v166
	v_add_u32_e32 v180, s72, v166
	ds_read_b128 v[144:147], v156
	ds_read_b128 v[148:151], v156 offset:1024
	ds_read_b128 v[152:155], v156 offset:2048
	ds_read_b128 v[156:159], v156 offset:3072
	ds_read_b128 v[162:165], v180
	ds_read_b128 v[172:175], v180 offset:1024
	ds_read_b128 v[176:179], v180 offset:2048
	ds_read_b128 v[180:183], v180 offset:3072
	s_add_u32 s36, s36, 0xb0000
	s_addc_u32 s37, s37, 0
	s_mov_b32 m0, s40
	v_lshl_add_u64 v[224:225], s[36:37], 0, v[128:129]
	ds_read_b128 v[184:187], v170 offset:32768
	ds_read_b128 v[188:191], v170 offset:33792
	ds_read_b128 v[192:195], v170 offset:34816
	ds_read_b128 v[196:199], v170 offset:35840
	ds_read_b128 v[200:203], v170 offset:36864
	ds_read_b128 v[204:207], v170 offset:37888
	ds_read_b128 v[208:211], v170 offset:38912
	ds_read_b128 v[212:215], v170 offset:39936
	global_load_lds_dwordx4 v[224:225], off
	v_lshl_add_u64 v[224:225], s[36:37], 0, v[132:133]
	s_mov_b32 m0, s41
	s_nop 0
	global_load_lds_dwordx4 v[224:225], off
	s_waitcnt vmcnt(8)
	s_waitcnt lgkmcnt(0)
	s_barrier
	s_waitcnt lgkmcnt(0)
	v_mfma_f32_16x16x32_bf16 v[124:127], v[144:147], v[184:187], v[124:127]
	v_mfma_f32_16x16x32_bf16 v[120:123], v[152:155], v[184:187], v[120:123]
	v_mfma_f32_16x16x32_bf16 v[108:111], v[144:147], v[192:195], v[108:111]
	v_mfma_f32_16x16x32_bf16 v[104:107], v[152:155], v[192:195], v[104:107]
	v_mfma_f32_16x16x32_bf16 v[92:95], v[144:147], v[200:203], v[92:95]
	v_mfma_f32_16x16x32_bf16 v[88:91], v[152:155], v[200:203], v[88:91]
	v_mfma_f32_16x16x32_bf16 v[76:79], v[144:147], v[208:211], v[76:79]
	v_mfma_f32_16x16x32_bf16 v[72:75], v[152:155], v[208:211], v[72:75]
	v_mfma_f32_16x16x32_bf16 v[124:127], v[148:151], v[188:191], v[124:127]
	v_mfma_f32_16x16x32_bf16 v[120:123], v[156:159], v[188:191], v[120:123]
	v_mfma_f32_16x16x32_bf16 v[108:111], v[148:151], v[196:199], v[108:111]
	v_mfma_f32_16x16x32_bf16 v[104:107], v[156:159], v[196:199], v[104:107]
	v_mfma_f32_16x16x32_bf16 v[92:95], v[148:151], v[204:207], v[92:95]
	v_mfma_f32_16x16x32_bf16 v[88:91], v[156:159], v[204:207], v[88:91]
	v_mfma_f32_16x16x32_bf16 v[76:79], v[148:151], v[212:215], v[76:79]
	v_mfma_f32_16x16x32_bf16 v[72:75], v[156:159], v[212:215], v[72:75]
	v_mfma_f32_16x16x32_bf16 v[116:119], v[162:165], v[184:187], v[116:119]
	v_mfma_f32_16x16x32_bf16 v[112:115], v[176:179], v[184:187], v[112:115]
	v_mfma_f32_16x16x32_bf16 v[100:103], v[162:165], v[192:195], v[100:103]
	v_mfma_f32_16x16x32_bf16 v[96:99], v[176:179], v[192:195], v[96:99]
	v_mfma_f32_16x16x32_bf16 v[84:87], v[162:165], v[200:203], v[84:87]
	v_mfma_f32_16x16x32_bf16 v[80:83], v[176:179], v[200:203], v[80:83]
	v_mfma_f32_16x16x32_bf16 v[68:71], v[162:165], v[208:211], v[68:71]
	v_mfma_f32_16x16x32_bf16 v[64:67], v[176:179], v[208:211], v[64:67]
	v_mfma_f32_16x16x32_bf16 v[116:119], v[172:175], v[188:191], v[116:119]
	v_mfma_f32_16x16x32_bf16 v[112:115], v[180:183], v[188:191], v[112:115]
	v_mfma_f32_16x16x32_bf16 v[100:103], v[172:175], v[196:199], v[100:103]
	v_mfma_f32_16x16x32_bf16 v[96:99], v[180:183], v[196:199], v[96:99]
	v_mfma_f32_16x16x32_bf16 v[84:87], v[172:175], v[204:207], v[84:87]
	v_mfma_f32_16x16x32_bf16 v[80:83], v[180:183], v[204:207], v[80:83]
	v_mfma_f32_16x16x32_bf16 v[68:71], v[172:175], v[212:215], v[68:71]
	v_mfma_f32_16x16x32_bf16 v[64:67], v[180:183], v[212:215], v[64:67]
	s_barrier
; #define PG8_STAGE(bufoff, gbase, voff) do { _Pragma("unroll") for (int _i = 0; _i < 2; ++_i) \
;         __builtin_amdgcn_global_load_lds((const unsigned*)((const char*)(gbase) + (voff)[_i]), (PG8_LAS unsigned*)(lds + (bufoff) + ldsw + _i * 8192), 16, 0, 0); } while (0)
; #define PG8_LDA(dst, b, h) do { _Pragma("unroll") for (int m = 0; m < 4; ++m) _Pragma("unroll") for (int k = 0; k < 2; ++k) dst[m][k] = *(const PG8_LAS bf16x8*)(lds + PG8_SA(b, h) + aoff + m * 2048 + k * 1024); } while (0)
; #define PG8_MMA(ai, bj, At, Bt) do { __builtin_amdgcn_s_setprio(1); _Pragma("unroll") for (int m = 0; m < 4; ++m) _Pragma("unroll") for (int n = 0; n < 2; ++n) _Pragma("unroll") for (int k = 0; k < 2; ++k) \
;         acc[ai][bj][m][n] = __builtin_amdgcn_mfma_f32_16x16x32_bf16(Bt[n][k], At[m][k], acc[ai][bj][m][n], 0, 0, 0); __builtin_amdgcn_s_setprio(0); } while (0)
; #define PG8_WAIT_V(n) asm volatile("s_waitcnt vmcnt(" #n ")" ::: "memory")
; #define PG8_WAIT_L(n) asm volatile("s_waitcnt lgkmcnt(" #n ")" ::: "memory")
; #define PG8_BAR __builtin_amdgcn_s_barrier()
; #define PG8_SCHED __builtin_amdgcn_sched_barrier(0)
; template <class Epi, class Sched, bool ALIGN_EPI = false, bool SP2 = false>
; __device__ __forceinline__ void gemm_phase(PG8_LAS unsigned char* lds, const Gemm g, const Sched& S, const Epi& E) {
;     ...
;             PG8_LDA(At, 1, 1); PG8_STAGE(PG8_SB(1, 0), b3, voffB); PG8_STAGE(PG8_SB(1, 1), b3 + hstep, voffB); PG8_STAGE(PG8_SA(1, 0), a3, voffA);
;             PG8_WAIT_V(8); PG8_WAIT_L(0); PG8_BAR; PG8_MMA(1, 0, At, B0); PG8_MMA(1, 1, At, B1); PG8_BAR; PG8_SCHED;
; __global__ void __launch_bounds__(512, 2) hybrid_fwd(Args args) {
;     ...
;         for (int idx = blk * 512 + tid; idx < 2 * NBIAS; idx += G * 512) { const int bb = idx / NBIAS, col = idx - bb * NBIAS; float sacc = 0.f;
; #pragma unroll
;             for (int kb = 0; kb < 16; ++kb) sacc += BIASP[((size_t)bb * 16 + kb) * NBIAS + col];
;             BIAS[idx] = sacc; }
	s_add_i32 s36, s71, s3
	v_lshl_add_u64 v[216:217], v[216:217], 0, s[16:17]
	s_mov_b32 m0, s36
	ds_read_b128 v[184:187], v170 offset:49152
	ds_read_b128 v[188:191], v170 offset:50176
	ds_read_b128 v[192:195], v170 offset:51200
	ds_read_b128 v[196:199], v170 offset:52224
	ds_read_b128 v[200:203], v170 offset:53248
	ds_read_b128 v[204:207], v170 offset:54272
	ds_read_b128 v[208:211], v170 offset:55296
	ds_read_b128 v[212:215], v170 offset:56320
	global_load_lds_dwordx4 v[216:217], off
	s_add_i32 m0, s36, 0x2000
	s_add_u32 s34, s34, 0xb0080
	v_lshl_add_u64 v[216:217], v[218:219], 0, s[16:17]
	s_addc_u32 s35, s35, 0
	s_add_i32 s36, s72, s3
	global_load_lds_dwordx4 v[216:217], off
	v_lshl_add_u64 v[216:217], s[34:35], 0, v[130:131]
	s_mov_b32 m0, s36
	s_nop 0
	global_load_lds_dwordx4 v[216:217], off
	v_lshl_add_u64 v[216:217], s[34:35], 0, v[134:135]
	s_add_i32 m0, s36, 0x2000
	s_nop 0
	global_load_lds_dwordx4 v[216:217], off
	v_lshl_add_u64 v[216:217], v[220:221], 0, s[16:17]
	s_mov_b32 m0, s53
	s_nop 0
	global_load_lds_dwordx4 v[216:217], off
	v_lshl_add_u64 v[216:217], v[222:223], 0, s[16:17]
	s_mov_b32 m0, s54
	s_nop 0
	global_load_lds_dwordx4 v[216:217], off
	s_waitcnt vmcnt(8)
	s_waitcnt lgkmcnt(0)
	s_barrier
	s_waitcnt lgkmcnt(0)
	v_mfma_f32_16x16x32_bf16 v[60:63], v[144:147], v[184:187], v[60:63]
	v_mfma_f32_16x16x32_bf16 v[56:59], v[152:155], v[184:187], v[56:59]
	v_mfma_f32_16x16x32_bf16 v[44:47], v[144:147], v[192:195], v[44:47]
	v_mfma_f32_16x16x32_bf16 v[40:43], v[152:155], v[192:195], v[40:43]
	v_mfma_f32_16x16x32_bf16 v[28:31], v[144:147], v[200:203], v[28:31]
	v_mfma_f32_16x16x32_bf16 v[24:27], v[152:155], v[200:203], v[24:27]
	v_mfma_f32_16x16x32_bf16 v[12:15], v[144:147], v[208:211], v[12:15]
	v_mfma_f32_16x16x32_bf16 v[8:11], v[152:155], v[208:211], v[8:11]
	v_mfma_f32_16x16x32_bf16 v[60:63], v[148:151], v[188:191], v[60:63]
	v_mfma_f32_16x16x32_bf16 v[56:59], v[156:159], v[188:191], v[56:59]
	v_mfma_f32_16x16x32_bf16 v[44:47], v[148:151], v[196:199], v[44:47]
	v_mfma_f32_16x16x32_bf16 v[40:43], v[156:159], v[196:199], v[40:43]
	v_mfma_f32_16x16x32_bf16 v[28:31], v[148:151], v[204:207], v[28:31]
	v_mfma_f32_16x16x32_bf16 v[24:27], v[156:159], v[204:207], v[24:27]
	v_mfma_f32_16x16x32_bf16 v[12:15], v[148:151], v[212:215], v[12:15]
	v_mfma_f32_16x16x32_bf16 v[8:11], v[156:159], v[212:215], v[8:11]
	v_mfma_f32_16x16x32_bf16 v[52:55], v[162:165], v[184:187], v[52:55]
	v_mfma_f32_16x16x32_bf16 v[48:51], v[176:179], v[184:187], v[48:51]
	v_mfma_f32_16x16x32_bf16 v[36:39], v[162:165], v[192:195], v[36:39]
	v_mfma_f32_16x16x32_bf16 v[32:35], v[176:179], v[192:195], v[32:35]
	v_mfma_f32_16x16x32_bf16 v[20:23], v[162:165], v[200:203], v[20:23]
	v_mfma_f32_16x16x32_bf16 v[16:19], v[176:179], v[200:203], v[16:19]
	v_mfma_f32_16x16x32_bf16 v[4:7], v[162:165], v[208:211], v[4:7]
	v_mfma_f32_16x16x32_bf16 v[0:3], v[176:179], v[208:211], v[0:3]
	v_mfma_f32_16x16x32_bf16 v[52:55], v[172:175], v[188:191], v[52:55]
	v_mfma_f32_16x16x32_bf16 v[48:51], v[180:183], v[188:191], v[48:51]
	v_mfma_f32_16x16x32_bf16 v[36:39], v[172:175], v[196:199], v[36:39]
	v_mfma_f32_16x16x32_bf16 v[32:35], v[180:183], v[196:199], v[32:35]
	v_mfma_f32_16x16x32_bf16 v[20:23], v[172:175], v[204:207], v[20:23]
	v_mfma_f32_16x16x32_bf16 v[16:19], v[180:183], v[204:207], v[16:19]
	v_mfma_f32_16x16x32_bf16 v[4:7], v[172:175], v[212:215], v[4:7]
	v_mfma_f32_16x16x32_bf16 v[0:3], v[180:183], v[212:215], v[0:3]
	s_barrier
	s_add_i32 s70, s70, 2
	s_add_u32 s22, s22, 0x100
	s_addc_u32 s23, s23, 0
	s_add_u32 s66, s66, 0x100
	s_addc_u32 s67, s67, 0
	s_cmp_gt_u32 s70, 41
	s_cbranch_scc0 .LBB0_289
	s_cmp_lt_u32 s2, 38
	s_cbranch_scc0 .Lp3_bias_noload
	s_cmp_ge_u32 s2, 19
	s_cselect_b32 s99, 0x98000, 0
	s_cselect_b32 s100, 19, 0
	s_sub_i32 s100, s2, s100
	s_lshl_b32 s100, s100, 11
	s_add_u32 s100, s100, s99
	s_add_u32 s100, s100, 0xe800000
	s_add_u32 s100, s86, s100
	s_addc_u32 s101, s87, 0
	v_lshlrev_b32_e32 v227, 2, v226
	global_load_dword v228, v227, s[100:101]
	s_add_u32 s100, s100, 0x9800
	s_addc_u32 s101, s101, 0
	global_load_dword v229, v227, s[100:101]
	s_add_u32 s100, s100, 0x9800
	s_addc_u32 s101, s101, 0
	global_load_dword v230, v227, s[100:101]
	s_add_u32 s100, s100, 0x9800
	s_addc_u32 s101, s101, 0
	global_load_dword v231, v227, s[100:101]
	s_add_u32 s100, s100, 0x9800
	s_addc_u32 s101, s101, 0
	global_load_dword v232, v227, s[100:101]
	s_add_u32 s100, s100, 0x9800
	s_addc_u32 s101, s101, 0
	global_load_dword v233, v227, s[100:101]
	s_add_u32 s100, s100, 0x9800
	s_addc_u32 s101, s101, 0
	global_load_dword v234, v227, s[100:101]
	s_add_u32 s100, s100, 0x9800
	s_addc_u32 s101, s101, 0
	global_load_dword v235, v227, s[100:101]
	s_add_u32 s100, s100, 0x9800
	s_addc_u32 s101, s101, 0
	global_load_dword v236, v227, s[100:101]
	s_add_u32 s100, s100, 0x9800
	s_addc_u32 s101, s101, 0
	global_load_dword v237, v227, s[100:101]
	s_add_u32 s100, s100, 0x9800
	s_addc_u32 s101, s101, 0
	global_load_dword v238, v227, s[100:101]
	s_add_u32 s100, s100, 0x9800
	s_addc_u32 s101, s101, 0
	global_load_dword v239, v227, s[100:101]
	s_add_u32 s100, s100, 0x9800
	s_addc_u32 s101, s101, 0
	global_load_dword v240, v227, s[100:101]
	s_add_u32 s100, s100, 0x9800
	s_addc_u32 s101, s101, 0
	global_load_dword v241, v227, s[100:101]
	s_add_u32 s100, s100, 0x9800
	s_addc_u32 s101, s101, 0
	global_load_dword v242, v227, s[100:101]
	s_add_u32 s100, s100, 0x9800
	s_addc_u32 s101, s101, 0
	global_load_dword v243, v227, s[100:101]

; #define PG8_STAGE(bufoff, gbase, voff) do { _Pragma("unroll") for (int _i = 0; _i < 2; ++_i) \
;         __builtin_amdgcn_global_load_lds((const unsigned*)((const char*)(gbase) + (voff)[_i]), (PG8_LAS unsigned*)(lds + (bufoff) + ldsw + _i * 8192), 16, 0, 0); } while (0)
; #define PG8_BAR __builtin_amdgcn_s_barrier()
;     __device__ bool next(int i, Unit& u) const { if (i > 1 || !so.next(0, u)) return false; if (i == 1) { u.pm += 64; u.pn += 4; } return true; }
; template <class Epi, class Sched, bool ALIGN_EPI = false, bool SP2 = false>
; __device__ __forceinline__ void gemm_phase(PG8_LAS unsigned char* lds, const Gemm g, const Sched& S, const Epi& E) {
;     ...
;     for (int i = 0; i < 2; ++i) { int R, C; stage_rc(tid * 16 + i * 8192, R, C); const int Rb = Epi::PERM ? ((R & ~31) + perm32(R & 31)) : R;
;         voffA[i] = (unsigned)(R * K + C) * 2u; voffB[i] = (unsigned)(Rb * K + C) * 2u; }
;     const size_t kstep = (size_t)(BK * 2);
;     const size_t hstep = (size_t)HALF * K * 2;
;     const size_t tstep = 2 * hstep;
;     const unsigned ldsw = (unsigned)wid * 1024u;
;     const int aoff = lds_byte(wr * 64 + fr, fq * 8), boff = lds_byte(wc * 32 + fr, fq * 8);
;     ...
;     Unit cur, nxt; int ui = 0;
;     if (!S.next(0, cur)) return;
;     f32x4 acc[2][2][4][2];
; #pragma unroll
;     for (int a = 0; a < 2; ++a)
; #pragma unroll
;         for (int b = 0; b < 2; ++b)
; #pragma unroll
;             for (int m = 0; m < 4; ++m)
; #pragma unroll
;                 for (int n = 0; n < 2; ++n) acc[a][b][m][n] = (f32x4){0.f, 0.f, 0.f, 0.f};
;     bf16x8 At[4][2], B0[2][2], B1[2][2];
;     const char* cA = (const char*)g.A + (size_t)cur.pm * tstep; const char* cB = (const char*)g.Bt + (size_t)cur.pn * tstep;
;     S.a_ready(cur);
;     if constexpr (SP2) {
;         PG8_STAGE(PG8_SB(0, 0), cB, voffB); PG8_STAGE(PG8_SB(0, 1), cB + hstep, voffB); PG8_STAGE(PG8_SA(0, 0), cA, voffA); PG8_STAGE(PG8_SA(0, 1), cA + hstep, voffA);
;         if (wr == 1) PG8_BAR;
.LBB0_394:
	s_and_b64 vcc, exec, s[0:1]
	s_cbranch_vccnz .LBB0_480
	s_ashr_i32 s13, s12, 31
	v_lshrrev_b32_e32 v2, 1, v226
	v_lshrrev_b32_e32 v3, 5, v226
	s_lshl_b64 s[0:1], s[12:13], 23
	v_and_b32_e32 v2, 24, v2
	v_and_b32_e32 v3, 4, v3
	v_bfe_u32 v4, v226, 2, 2
	s_add_u32 s21, s68, s0
	v_lshlrev_b32_e32 v0, 4, v226
	v_and_b32_e32 v1, 32, v226
	v_bfe_u32 v10, v226, 2, 4
	v_or3_b32 v2, v3, v4, v2
	v_lshrrev_b32_e32 v3, 3, v226
	s_movk_i32 s0, 0x70
	v_bitop3_b32 v8, v0, v1, 48 bitop3:0x6c
	v_and_b32_e32 v9, 64, v226
	v_and_or_b32 v4, v3, s0, v10
	s_movk_i32 s0, 0x60
	v_add_u32_e32 v11, 0x2000, v0
	v_or_b32_e32 v1, v8, v9
	v_and_or_b32 v3, v3, s0, v2
	v_lshrrev_b32_e32 v0, 7, v11
	s_movk_i32 s0, 0xf0
	s_addc_u32 s58, s69, s1
	s_lshr_b32 s5, s18, 6
	v_lshl_or_b32 v164, v3, 11, v1
	v_and_or_b32 v3, v0, s0, v10
	s_movk_i32 s0, 0xe0
	s_ashr_i32 s9, s8, 31
	s_ashr_i32 s7, s6, 31
	v_and_or_b32 v0, v0, s0, v2
	s_lshr_b32 s4, s18, 8
	s_lshl_b32 s59, s5, 10
	s_lshl_b64 s[0:1], s[8:9], 19
	s_lshl_b64 s[12:13], s[6:7], 19
	s_add_u32 s48, s21, s12
	s_addc_u32 s49, s58, s13
	s_add_i32 s60, s59, 0
	s_add_i32 m0, s60, 0x10000
	v_lshl_or_b32 v168, v0, 11, v1
	global_load_lds_dwordx4 v164, s[48:49]
	s_add_i32 m0, s60, 0x12000
	s_add_u32 s12, s48, 0x40000
	global_load_lds_dwordx4 v168, s[48:49]
	s_addc_u32 s13, s49, 0
	s_add_i32 m0, s60, 0x14000
	v_lshl_or_b32 v162, v4, 11, v1
	global_load_lds_dwordx4 v164, s[12:13]
	s_add_i32 m0, s60, 0x16000
	s_add_u32 s0, s84, s0
	s_addc_u32 s1, s85, s1
	s_add_i32 s61, s60, 0x2000
	global_load_lds_dwordx4 v168, s[12:13]
	s_mov_b32 m0, s60
	s_add_u32 s12, s0, 0x40000
	v_lshl_or_b32 v166, v3, 11, v1
	global_load_lds_dwordx4 v162, s[0:1]
	s_mov_b32 m0, s61
	s_addc_u32 s13, s1, 0
	s_add_i32 s62, s60, 0x4000
	global_load_lds_dwordx4 v166, s[0:1]
	s_mov_b32 m0, s62
	s_add_i32 s63, s60, 0x6000
	global_load_lds_dwordx4 v162, s[12:13]
	s_mov_b32 m0, s63
	v_mov_b32_e32 v171, 0
	global_load_lds_dwordx4 v166, s[12:13]
	v_mov_b32_e32 v165, v171
	v_mov_b32_e32 v169, v171
	v_mov_b32_e32 v163, v171
	v_mov_b32_e32 v167, v171
	s_cmp_eq_u32 s4, 1
	s_mov_b32 s13, 0
	v_lshl_add_u64 v[6:7], s[48:49], 0, v[164:165]
	v_lshl_add_u64 v[4:5], s[48:49], 0, v[168:169]
	v_lshl_add_u64 v[0:1], s[0:1], 0, v[162:163]
	s_cselect_b64 s[14:15], -1, 0
	s_cmp_lg_u32 s4, 1
	v_lshl_add_u64 v[2:3], s[0:1], 0, v[166:167]
	s_cbranch_scc1 .LBB0_397
	s_barrier
	s_setprio 1

; #define PG8_STAGE(bufoff, gbase, voff) do { _Pragma("unroll") for (int _i = 0; _i < 2; ++_i) \
;         __builtin_amdgcn_global_load_lds((const unsigned*)((const char*)(gbase) + (voff)[_i]), (PG8_LAS unsigned*)(lds + (bufoff) + ldsw + _i * 8192), 16, 0, 0); } while (0)
; #define PG8_LDA(dst, b, h) do { _Pragma("unroll") for (int m = 0; m < 4; ++m) _Pragma("unroll") for (int k = 0; k < 2; ++k) dst[m][k] = *(const PG8_LAS bf16x8*)(lds + PG8_SA(b, h) + aoff + m * 2048 + k * 1024); } while (0)
; #define PG8_LDB(dst, b, h) do { _Pragma("unroll") for (int n = 0; n < 2; ++n) _Pragma("unroll") for (int k = 0; k < 2; ++k) dst[n][k] = *(const PG8_LAS bf16x8*)(lds + PG8_SB(b, h) + boff + n * 2048 + k * 1024); } while (0)
; #define PG8_MMA(ai, bj, At, Bt) do { __builtin_amdgcn_s_setprio(1); _Pragma("unroll") for (int m = 0; m < 4; ++m) _Pragma("unroll") for (int n = 0; n < 2; ++n) _Pragma("unroll") for (int k = 0; k < 2; ++k) \
;         acc[ai][bj][m][n] = __builtin_amdgcn_mfma_f32_16x16x32_bf16(Bt[n][k], At[m][k], acc[ai][bj][m][n], 0, 0, 0); __builtin_amdgcn_s_setprio(0); } while (0)
; #define PG8_WAIT_V(n) asm volatile("s_waitcnt vmcnt(" #n ")" ::: "memory")
; #define PG8_WAIT_L(n) asm volatile("s_waitcnt lgkmcnt(" #n ")" ::: "memory")
; template <class Epi, class Sched, bool ALIGN_EPI = false, bool SP2 = false>
; __device__ __forceinline__ void gemm_phase(PG8_LAS unsigned char* lds, const Gemm g, const Sched& S, const Epi& E) {
;     ...
;             const bool last = (t == nt - 2);
;             const char* a1 = cA + (size_t)(t + 1) * kstep;
;             const char* a2 = last ? nA : cA + (size_t)(t + 2) * kstep; const char* b2 = last ? nB : cB + (size_t)(t + 2) * kstep;
;             const char* a3 = a2 + kstep; const char* b3 = b2 + kstep;
;             if (last && has_next) S.a_ready(nxt);
;             if constexpr (SP2) {
;             PG8_LDB(B0, 0, 0); PG8_LDB(B1, 0, 1); PG8_SCHED; PG8_LDA(At, 0, 0); PG8_STAGE(PG8_SA(1, 1), a1 + hstep, voffA);
;             PG8_WAIT_V(8); PG8_WAIT_L(0); PG8_BAR; PG8_MMA(0, 0, At, B0); PG8_MMA(0, 1, At, B1); PG8_BAR; PG8_SCHED;
;             PG8_LDA(At, 0, 1); PG8_STAGE(PG8_SB(0, 0), b2, voffB); PG8_STAGE(PG8_SB(0, 1), b2 + hstep, voffB); PG8_STAGE(PG8_SA(0, 0), a2, voffA);
;             PG8_WAIT_V(8); PG8_WAIT_L(0); PG8_BAR; PG8_MMA(1, 0, At, B0); PG8_MMA(1, 1, At, B1); PG8_BAR; PG8_SCHED;
.LBB0_407:
	ds_read_b128 v[24:27], v189
	ds_read_b128 v[28:31], v189 offset:1024
	ds_read_b128 v[36:39], v189 offset:2048
	ds_read_b128 v[44:47], v189 offset:3072
	ds_read_b128 v[48:51], v190
	ds_read_b128 v[52:55], v190 offset:1024
	ds_read_b128 v[56:59], v190 offset:2048
	ds_read_b128 v[60:63], v190 offset:3072
	s_add_u32 s48, s0, 0xfffc0080
	s_addc_u32 s49, s1, -1
	s_cmp_eq_u32 s55, 12
	s_cselect_b32 s53, s7, s49
	s_cselect_b32 s52, s9, s48
	s_cselect_b32 s49, s12, s54
	s_cselect_b32 s48, s23, s41
	v_lshl_add_u64 v[184:185], s[0:1], 0, v[176:177]
	s_add_i32 m0, s60, 0xc000
	ds_read_b128 v[196:199], v191
	ds_read_b128 v[200:203], v191 offset:1024
	ds_read_b128 v[204:207], v191 offset:2048
	ds_read_b128 v[208:211], v191 offset:3072
	ds_read_b128 v[212:215], v191 offset:4096
	ds_read_b128 v[216:219], v191 offset:5120
	ds_read_b128 v[220:223], v191 offset:6144
	ds_read_b128 v[228:231], v191 offset:7168
	global_load_lds_dwordx4 v[184:185], off
	v_lshl_add_u64 v[184:185], s[0:1], 0, v[178:179]
	s_add_i32 m0, s60, 0xe000
	s_nop 0
	global_load_lds_dwordx4 v[184:185], off
	s_waitcnt vmcnt(8)
	s_waitcnt lgkmcnt(0)
	s_barrier
	s_waitcnt lgkmcnt(0)
	v_mfma_f32_16x16x32_bf16 v[156:159], v[24:27], v[196:199], v[156:159]
	v_mfma_f32_16x16x32_bf16 v[152:155], v[36:39], v[196:199], v[152:155]
	v_mfma_f32_16x16x32_bf16 v[140:143], v[24:27], v[204:207], v[140:143]
	v_mfma_f32_16x16x32_bf16 v[136:139], v[36:39], v[204:207], v[136:139]
	v_mfma_f32_16x16x32_bf16 v[124:127], v[24:27], v[212:215], v[124:127]
	v_mfma_f32_16x16x32_bf16 v[120:123], v[36:39], v[212:215], v[120:123]
	v_mfma_f32_16x16x32_bf16 v[108:111], v[24:27], v[220:223], v[108:111]
	v_mfma_f32_16x16x32_bf16 v[104:107], v[36:39], v[220:223], v[104:107]
	v_mfma_f32_16x16x32_bf16 v[156:159], v[28:31], v[200:203], v[156:159]
	v_mfma_f32_16x16x32_bf16 v[152:155], v[44:47], v[200:203], v[152:155]
	v_mfma_f32_16x16x32_bf16 v[140:143], v[28:31], v[208:211], v[140:143]
	v_mfma_f32_16x16x32_bf16 v[136:139], v[44:47], v[208:211], v[136:139]
	v_mfma_f32_16x16x32_bf16 v[124:127], v[28:31], v[216:219], v[124:127]
	v_mfma_f32_16x16x32_bf16 v[120:123], v[44:47], v[216:219], v[120:123]
	v_mfma_f32_16x16x32_bf16 v[108:111], v[28:31], v[228:231], v[108:111]
	v_mfma_f32_16x16x32_bf16 v[104:107], v[44:47], v[228:231], v[104:107]
	v_mfma_f32_16x16x32_bf16 v[148:151], v[48:51], v[196:199], v[148:151]
	v_mfma_f32_16x16x32_bf16 v[144:147], v[56:59], v[196:199], v[144:147]
	v_mfma_f32_16x16x32_bf16 v[132:135], v[48:51], v[204:207], v[132:135]
	v_mfma_f32_16x16x32_bf16 v[128:131], v[56:59], v[204:207], v[128:131]
	v_mfma_f32_16x16x32_bf16 v[116:119], v[48:51], v[212:215], v[116:119]
	v_mfma_f32_16x16x32_bf16 v[112:115], v[56:59], v[212:215], v[112:115]
	v_mfma_f32_16x16x32_bf16 v[100:103], v[48:51], v[220:223], v[100:103]
	v_mfma_f32_16x16x32_bf16 v[96:99], v[56:59], v[220:223], v[96:99]
	v_mfma_f32_16x16x32_bf16 v[148:151], v[52:55], v[200:203], v[148:151]
	v_mfma_f32_16x16x32_bf16 v[144:147], v[60:63], v[200:203], v[144:147]
	v_mfma_f32_16x16x32_bf16 v[132:135], v[52:55], v[208:211], v[132:135]
	v_mfma_f32_16x16x32_bf16 v[128:131], v[60:63], v[208:211], v[128:131]
	v_mfma_f32_16x16x32_bf16 v[116:119], v[52:55], v[216:219], v[116:119]
	v_mfma_f32_16x16x32_bf16 v[112:115], v[60:63], v[216:219], v[112:115]
	v_mfma_f32_16x16x32_bf16 v[100:103], v[52:55], v[228:231], v[100:103]
	v_mfma_f32_16x16x32_bf16 v[96:99], v[60:63], v[228:231], v[96:99]
	s_barrier
	s_add_i32 s56, s74, s59
	v_lshl_add_u64 v[184:185], s[48:49], 0, v[164:165]
	s_mov_b32 m0, s56
	ds_read_b128 v[196:199], v191 offset:16384
	ds_read_b128 v[200:203], v191 offset:17408
	ds_read_b128 v[204:207], v191 offset:18432
	ds_read_b128 v[208:211], v191 offset:19456
	ds_read_b128 v[212:215], v191 offset:20480
	ds_read_b128 v[216:219], v191 offset:21504
	ds_read_b128 v[220:223], v191 offset:22528
	ds_read_b128 v[228:231], v191 offset:23552
	global_load_lds_dwordx4 v[184:185], off
	s_add_i32 m0, s56, 0x2000
	s_add_u32 s56, s48, 0x40000
	v_lshl_add_u64 v[224:225], s[48:49], 0, v[168:169]
	s_addc_u32 s57, s49, 0
	s_add_i32 s79, s75, s59
	global_load_lds_dwordx4 v[224:225], off
	v_lshl_add_u64 v[232:233], s[56:57], 0, v[164:165]
	s_mov_b32 m0, s79
	v_lshl_add_u64 v[240:241], s[52:53], 0, v[162:163]
	global_load_lds_dwordx4 v[232:233], off
	v_lshl_add_u64 v[232:233], s[56:57], 0, v[168:169]
	s_add_i32 m0, s79, 0x2000
	v_lshl_add_u64 v[242:243], s[52:53], 0, v[166:167]
	global_load_lds_dwordx4 v[232:233], off
	s_mov_b32 m0, s60
	s_nop 0
	global_load_lds_dwordx4 v[240:241], off
	s_mov_b32 m0, s61
	s_nop 0
	global_load_lds_dwordx4 v[242:243], off
	s_waitcnt vmcnt(8)
	s_waitcnt lgkmcnt(0)
	s_barrier
; #define PG8_STAGE(bufoff, gbase, voff) do { _Pragma("unroll") for (int _i = 0; _i < 2; ++_i) \
;         __builtin_amdgcn_global_load_lds((const unsigned*)((const char*)(gbase) + (voff)[_i]), (PG8_LAS unsigned*)(lds + (bufoff) + ldsw + _i * 8192), 16, 0, 0); } while (0)
; #define PG8_LDA(dst, b, h) do { _Pragma("unroll") for (int m = 0; m < 4; ++m) _Pragma("unroll") for (int k = 0; k < 2; ++k) dst[m][k] = *(const PG8_LAS bf16x8*)(lds + PG8_SA(b, h) + aoff + m * 2048 + k * 1024); } while (0)
; #define PG8_LDB(dst, b, h) do { _Pragma("unroll") for (int n = 0; n < 2; ++n) _Pragma("unroll") for (int k = 0; k < 2; ++k) dst[n][k] = *(const PG8_LAS bf16x8*)(lds + PG8_SB(b, h) + boff + n * 2048 + k * 1024); } while (0)
; #define PG8_MMA(ai, bj, At, Bt) do { __builtin_amdgcn_s_setprio(1); _Pragma("unroll") for (int m = 0; m < 4; ++m) _Pragma("unroll") for (int n = 0; n < 2; ++n) _Pragma("unroll") for (int k = 0; k < 2; ++k) \
;         acc[ai][bj][m][n] = __builtin_amdgcn_mfma_f32_16x16x32_bf16(Bt[n][k], At[m][k], acc[ai][bj][m][n], 0, 0, 0); __builtin_amdgcn_s_setprio(0); } while (0)
; #define PG8_WAIT_V(n) asm volatile("s_waitcnt vmcnt(" #n ")" ::: "memory")
; #define PG8_WAIT_L(n) asm volatile("s_waitcnt lgkmcnt(" #n ")" ::: "memory")
; #define PG8_BAR __builtin_amdgcn_s_barrier()
; #define PG8_SCHED __builtin_amdgcn_sched_barrier(0)
; template <class Epi, class Sched, bool ALIGN_EPI = false, bool SP2 = false>
; __device__ __forceinline__ void gemm_phase(PG8_LAS unsigned char* lds, const Gemm g, const Sched& S, const Epi& E) {
;     ...
;             PG8_WAIT_V(8); PG8_WAIT_L(0); PG8_BAR; PG8_MMA(1, 0, At, B0); PG8_MMA(1, 1, At, B1); PG8_BAR; PG8_SCHED;
;             PG8_LDB(B0, 1, 0); PG8_LDB(B1, 1, 1); PG8_SCHED; PG8_LDA(At, 1, 0); PG8_STAGE(PG8_SA(0, 1), a2 + hstep, voffA);
;             PG8_WAIT_V(8); PG8_WAIT_L(0); PG8_BAR; PG8_MMA(0, 0, At, B0); PG8_MMA(0, 1, At, B1); PG8_BAR; PG8_SCHED;
;             PG8_LDA(At, 1, 1); PG8_STAGE(PG8_SB(1, 0), b3, voffB); PG8_STAGE(PG8_SB(1, 1), b3 + hstep, voffB); PG8_STAGE(PG8_SA(1, 0), a3, voffA);
	s_waitcnt lgkmcnt(0)
	v_mfma_f32_16x16x32_bf16 v[92:95], v[24:27], v[196:199], v[92:95]
	v_mfma_f32_16x16x32_bf16 v[88:91], v[36:39], v[196:199], v[88:91]
	v_mfma_f32_16x16x32_bf16 v[76:79], v[24:27], v[204:207], v[76:79]
	v_mfma_f32_16x16x32_bf16 v[72:75], v[36:39], v[204:207], v[72:75]
	v_mfma_f32_16x16x32_bf16 v[40:43], v[24:27], v[212:215], v[40:43]
	v_mfma_f32_16x16x32_bf16 v[32:35], v[36:39], v[212:215], v[32:35]
	v_mfma_f32_16x16x32_bf16 v[12:15], v[24:27], v[220:223], v[12:15]
	v_mfma_f32_16x16x32_bf16 v[8:11], v[36:39], v[220:223], v[8:11]
	v_mfma_f32_16x16x32_bf16 v[92:95], v[28:31], v[200:203], v[92:95]
	v_mfma_f32_16x16x32_bf16 v[88:91], v[44:47], v[200:203], v[88:91]
	v_mfma_f32_16x16x32_bf16 v[76:79], v[28:31], v[208:211], v[76:79]
	v_mfma_f32_16x16x32_bf16 v[72:75], v[44:47], v[208:211], v[72:75]
	v_mfma_f32_16x16x32_bf16 v[40:43], v[28:31], v[216:219], v[40:43]
	v_mfma_f32_16x16x32_bf16 v[32:35], v[44:47], v[216:219], v[32:35]
	v_mfma_f32_16x16x32_bf16 v[12:15], v[28:31], v[228:231], v[12:15]
	v_mfma_f32_16x16x32_bf16 v[8:11], v[44:47], v[228:231], v[8:11]
	v_mfma_f32_16x16x32_bf16 v[20:23], v[48:51], v[212:215], v[20:23]
	v_mfma_f32_16x16x32_bf16 v[16:19], v[56:59], v[212:215], v[16:19]
	v_mfma_f32_16x16x32_bf16 v[4:7], v[48:51], v[220:223], v[4:7]
	v_mfma_f32_16x16x32_bf16 v[0:3], v[56:59], v[220:223], v[0:3]
	v_mfma_f32_16x16x32_bf16 v[24:27], v[48:51], v[196:199], v[84:87]
	v_mfma_f32_16x16x32_bf16 v[28:31], v[56:59], v[196:199], v[80:83]
	v_mfma_f32_16x16x32_bf16 v[36:39], v[48:51], v[204:207], v[68:71]
	v_mfma_f32_16x16x32_bf16 v[44:47], v[56:59], v[204:207], v[64:67]
	v_mfma_f32_16x16x32_bf16 v[20:23], v[52:55], v[216:219], v[20:23]
	v_mfma_f32_16x16x32_bf16 v[16:19], v[60:63], v[216:219], v[16:19]
	v_mfma_f32_16x16x32_bf16 v[4:7], v[52:55], v[228:231], v[4:7]
	v_mfma_f32_16x16x32_bf16 v[0:3], v[60:63], v[228:231], v[0:3]
	v_mfma_f32_16x16x32_bf16 v[24:27], v[52:55], v[200:203], v[24:27]
	v_mfma_f32_16x16x32_bf16 v[28:31], v[60:63], v[200:203], v[28:31]
	v_mfma_f32_16x16x32_bf16 v[36:39], v[52:55], v[208:211], v[36:39]
	v_mfma_f32_16x16x32_bf16 v[44:47], v[60:63], v[208:211], v[44:47]
	s_barrier
	s_add_i32 s56, 0, 0x18000
	s_add_i32 s57, 0, 0x1c000
	v_add_u32_e32 v60, s56, v186
	v_add_u32_e32 v64, s57, v186
	ds_read_b128 v[48:51], v60
	ds_read_b128 v[52:55], v60 offset:1024
	ds_read_b128 v[56:59], v60 offset:2048
	ds_read_b128 v[60:63], v60 offset:3072
	ds_read_b128 v[196:199], v64
	ds_read_b128 v[200:203], v64 offset:1024
	ds_read_b128 v[204:207], v64 offset:2048
	ds_read_b128 v[208:211], v64 offset:3072
	s_add_u32 s52, s52, 0x40000
	s_addc_u32 s53, s53, 0
	s_mov_b32 m0, s62
	v_lshl_add_u64 v[232:233], s[52:53], 0, v[162:163]
	ds_read_b128 v[64:67], v191 offset:32768
	ds_read_b128 v[68:71], v191 offset:33792
	ds_read_b128 v[80:83], v191 offset:34816
	ds_read_b128 v[84:87], v191 offset:35840
	ds_read_b128 v[212:215], v191 offset:36864
	ds_read_b128 v[216:219], v191 offset:37888
	ds_read_b128 v[220:223], v191 offset:38912
	ds_read_b128 v[228:231], v191 offset:39936
	global_load_lds_dwordx4 v[232:233], off
	v_lshl_add_u64 v[232:233], s[52:53], 0, v[166:167]
	s_mov_b32 m0, s63
	s_nop 0
	global_load_lds_dwordx4 v[232:233], off
	s_waitcnt vmcnt(8)
	s_waitcnt lgkmcnt(0)
	s_barrier
	s_waitcnt lgkmcnt(0)
	v_mfma_f32_16x16x32_bf16 v[156:159], v[48:51], v[64:67], v[156:159]
	v_mfma_f32_16x16x32_bf16 v[152:155], v[56:59], v[64:67], v[152:155]
	v_mfma_f32_16x16x32_bf16 v[140:143], v[48:51], v[80:83], v[140:143]
	v_mfma_f32_16x16x32_bf16 v[136:139], v[56:59], v[80:83], v[136:139]
	v_mfma_f32_16x16x32_bf16 v[124:127], v[48:51], v[212:215], v[124:127]
	v_mfma_f32_16x16x32_bf16 v[120:123], v[56:59], v[212:215], v[120:123]
	v_mfma_f32_16x16x32_bf16 v[108:111], v[48:51], v[220:223], v[108:111]
	v_mfma_f32_16x16x32_bf16 v[104:107], v[56:59], v[220:223], v[104:107]
	v_mfma_f32_16x16x32_bf16 v[156:159], v[52:55], v[68:71], v[156:159]
	v_mfma_f32_16x16x32_bf16 v[152:155], v[60:63], v[68:71], v[152:155]
	v_mfma_f32_16x16x32_bf16 v[140:143], v[52:55], v[84:87], v[140:143]
	v_mfma_f32_16x16x32_bf16 v[136:139], v[60:63], v[84:87], v[136:139]
	v_mfma_f32_16x16x32_bf16 v[124:127], v[52:55], v[216:219], v[124:127]
	v_mfma_f32_16x16x32_bf16 v[120:123], v[60:63], v[216:219], v[120:123]
	v_mfma_f32_16x16x32_bf16 v[108:111], v[52:55], v[228:231], v[108:111]
	v_mfma_f32_16x16x32_bf16 v[104:107], v[60:63], v[228:231], v[104:107]
	v_mfma_f32_16x16x32_bf16 v[148:151], v[196:199], v[64:67], v[148:151]
	v_mfma_f32_16x16x32_bf16 v[64:67], v[204:207], v[64:67], v[144:147]
	v_mfma_f32_16x16x32_bf16 v[144:147], v[208:211], v[68:71], v[64:67]
	v_mfma_f32_16x16x32_bf16 v[64:67], v[196:199], v[80:83], v[132:135]
	v_mfma_f32_16x16x32_bf16 v[132:135], v[200:203], v[84:87], v[64:67]
	v_mfma_f32_16x16x32_bf16 v[64:67], v[204:207], v[80:83], v[128:131]
	v_mfma_f32_16x16x32_bf16 v[128:131], v[208:211], v[84:87], v[64:67]
	v_mfma_f32_16x16x32_bf16 v[64:67], v[196:199], v[212:215], v[116:119]
	v_mfma_f32_16x16x32_bf16 v[116:119], v[200:203], v[216:219], v[64:67]
	v_mfma_f32_16x16x32_bf16 v[64:67], v[204:207], v[212:215], v[112:115]
	v_mfma_f32_16x16x32_bf16 v[112:115], v[208:211], v[216:219], v[64:67]
	v_mfma_f32_16x16x32_bf16 v[64:67], v[196:199], v[220:223], v[100:103]
	v_mfma_f32_16x16x32_bf16 v[100:103], v[200:203], v[228:231], v[64:67]
	v_mfma_f32_16x16x32_bf16 v[64:67], v[204:207], v[220:223], v[96:99]
	v_mfma_f32_16x16x32_bf16 v[148:151], v[200:203], v[68:71], v[148:151]
	v_mfma_f32_16x16x32_bf16 v[96:99], v[208:211], v[228:231], v[64:67]
	s_barrier
; #define PG8_STAGE(bufoff, gbase, voff) do { _Pragma("unroll") for (int _i = 0; _i < 2; ++_i) \
;         __builtin_amdgcn_global_load_lds((const unsigned*)((const char*)(gbase) + (voff)[_i]), (PG8_LAS unsigned*)(lds + (bufoff) + ldsw + _i * 8192), 16, 0, 0); } while (0)
; #define PG8_LDA(dst, b, h) do { _Pragma("unroll") for (int m = 0; m < 4; ++m) _Pragma("unroll") for (int k = 0; k < 2; ++k) dst[m][k] = *(const PG8_LAS bf16x8*)(lds + PG8_SA(b, h) + aoff + m * 2048 + k * 1024); } while (0)
; #define PG8_MMA(ai, bj, At, Bt) do { __builtin_amdgcn_s_setprio(1); _Pragma("unroll") for (int m = 0; m < 4; ++m) _Pragma("unroll") for (int n = 0; n < 2; ++n) _Pragma("unroll") for (int k = 0; k < 2; ++k) \
;         acc[ai][bj][m][n] = __builtin_amdgcn_mfma_f32_16x16x32_bf16(Bt[n][k], At[m][k], acc[ai][bj][m][n], 0, 0, 0); __builtin_amdgcn_s_setprio(0); } while (0)
; #define PG8_WAIT_V(n) asm volatile("s_waitcnt vmcnt(" #n ")" ::: "memory")
; #define PG8_WAIT_L(n) asm volatile("s_waitcnt lgkmcnt(" #n ")" ::: "memory")
; #define PG8_BAR __builtin_amdgcn_s_barrier()
; #define PG8_SCHED __builtin_amdgcn_sched_barrier(0)
; template <class Epi, class Sched, bool ALIGN_EPI = false, bool SP2 = false>
; __device__ __forceinline__ void gemm_phase(PG8_LAS unsigned char* lds, const Gemm g, const Sched& S, const Epi& E) {
;     ...
;             PG8_LDA(At, 1, 1); PG8_STAGE(PG8_SB(1, 0), b3, voffB); PG8_STAGE(PG8_SB(1, 1), b3 + hstep, voffB); PG8_STAGE(PG8_SA(1, 0), a3, voffA);
;             PG8_WAIT_V(8); PG8_WAIT_L(0); PG8_BAR; PG8_MMA(1, 0, At, B0); PG8_MMA(1, 1, At, B1); PG8_BAR; PG8_SCHED;
;     ...
;         if constexpr (ALIGN_EPI) { if (wr == 0) PG8_BAR; }
	s_add_i32 s52, s56, s59
	v_lshl_add_u64 v[80:81], v[184:185], 0, s[16:17]
	s_mov_b32 m0, s52
	s_nop 0
	ds_read_b128 v[64:67], v191 offset:49152
	ds_read_b128 v[68:71], v191 offset:50176
	ds_read_b128 v[212:215], v191 offset:51200
	ds_read_b128 v[216:219], v191 offset:52224
	ds_read_b128 v[220:223], v191 offset:53248
	ds_read_b128 v[228:231], v191 offset:54272
	ds_read_b128 v[232:235], v191 offset:55296
	ds_read_b128 v[236:239], v191 offset:56320
	global_load_lds_dwordx4 v[80:81], off
	s_add_i32 m0, s52, 0x2000
	s_add_u32 s48, s48, 0x40080
	v_lshl_add_u64 v[80:81], v[224:225], 0, s[16:17]
	s_addc_u32 s49, s49, 0
	s_add_i32 s52, s57, s59
	global_load_lds_dwordx4 v[80:81], off
	v_lshl_add_u64 v[80:81], s[48:49], 0, v[164:165]
	s_mov_b32 m0, s52
	s_nop 0
	global_load_lds_dwordx4 v[80:81], off
	v_lshl_add_u64 v[80:81], s[48:49], 0, v[168:169]
	s_add_i32 m0, s52, 0x2000
	s_nop 0
	global_load_lds_dwordx4 v[80:81], off
	v_lshl_add_u64 v[80:81], v[240:241], 0, s[16:17]
	s_mov_b32 m0, s65
	s_nop 0
	global_load_lds_dwordx4 v[80:81], off
	v_lshl_add_u64 v[80:81], v[242:243], 0, s[16:17]
	s_mov_b32 m0, s68
	s_nop 0
	global_load_lds_dwordx4 v[80:81], off
	s_waitcnt vmcnt(8)
	s_waitcnt lgkmcnt(0)
	s_barrier
	s_waitcnt lgkmcnt(0)
	v_mfma_f32_16x16x32_bf16 v[80:83], v[48:51], v[64:67], v[92:95]
	v_mfma_f32_16x16x32_bf16 v[92:95], v[52:55], v[68:71], v[80:83]
	v_mfma_f32_16x16x32_bf16 v[80:83], v[56:59], v[64:67], v[88:91]
	v_mfma_f32_16x16x32_bf16 v[76:79], v[48:51], v[212:215], v[76:79]
	v_mfma_f32_16x16x32_bf16 v[72:75], v[56:59], v[212:215], v[72:75]
	v_mfma_f32_16x16x32_bf16 v[40:43], v[48:51], v[220:223], v[40:43]
	v_mfma_f32_16x16x32_bf16 v[32:35], v[56:59], v[220:223], v[32:35]
	v_mfma_f32_16x16x32_bf16 v[12:15], v[48:51], v[232:235], v[12:15]
	v_mfma_f32_16x16x32_bf16 v[8:11], v[56:59], v[232:235], v[8:11]
	v_mfma_f32_16x16x32_bf16 v[88:91], v[60:63], v[68:71], v[80:83]
	v_mfma_f32_16x16x32_bf16 v[76:79], v[52:55], v[216:219], v[76:79]
	v_mfma_f32_16x16x32_bf16 v[72:75], v[60:63], v[216:219], v[72:75]
	v_mfma_f32_16x16x32_bf16 v[40:43], v[52:55], v[228:231], v[40:43]
	v_mfma_f32_16x16x32_bf16 v[32:35], v[60:63], v[228:231], v[32:35]
	v_mfma_f32_16x16x32_bf16 v[12:15], v[52:55], v[236:239], v[12:15]
	v_mfma_f32_16x16x32_bf16 v[8:11], v[60:63], v[236:239], v[8:11]
	v_mfma_f32_16x16x32_bf16 v[24:27], v[196:199], v[64:67], v[24:27]
	v_mfma_f32_16x16x32_bf16 v[84:87], v[200:203], v[68:71], v[24:27]
	v_mfma_f32_16x16x32_bf16 v[24:27], v[204:207], v[64:67], v[28:31]
	v_mfma_f32_16x16x32_bf16 v[80:83], v[208:211], v[68:71], v[24:27]
	v_mfma_f32_16x16x32_bf16 v[24:27], v[196:199], v[212:215], v[36:39]
	v_mfma_f32_16x16x32_bf16 v[68:71], v[200:203], v[216:219], v[24:27]
	v_mfma_f32_16x16x32_bf16 v[24:27], v[204:207], v[212:215], v[44:47]
	v_mfma_f32_16x16x32_bf16 v[20:23], v[196:199], v[220:223], v[20:23]
	v_mfma_f32_16x16x32_bf16 v[16:19], v[204:207], v[220:223], v[16:19]
	v_mfma_f32_16x16x32_bf16 v[4:7], v[196:199], v[232:235], v[4:7]
	v_mfma_f32_16x16x32_bf16 v[0:3], v[204:207], v[232:235], v[0:3]
	v_mfma_f32_16x16x32_bf16 v[64:67], v[208:211], v[216:219], v[24:27]
	v_mfma_f32_16x16x32_bf16 v[20:23], v[200:203], v[228:231], v[20:23]
	v_mfma_f32_16x16x32_bf16 v[16:19], v[208:211], v[228:231], v[16:19]
	v_mfma_f32_16x16x32_bf16 v[4:7], v[200:203], v[236:239], v[4:7]
	v_mfma_f32_16x16x32_bf16 v[0:3], v[208:211], v[236:239], v[0:3]
	s_barrier
	s_add_i32 s55, s55, 2
	s_add_u32 s0, s0, 0x100
	s_addc_u32 s1, s1, 0
	s_add_u32 s41, s41, 0x100
	s_addc_u32 s54, s54, 0
	s_cmp_gt_u32 s55, 13
	s_cbranch_scc0 .LBB0_407
	s_and_b64 vcc, exec, s[18:19]
	s_cbranch_vccz .LBB0_410
	s_barrier

; #define PG8_STAGE(bufoff, gbase, voff) do { _Pragma("unroll") for (int _i = 0; _i < 2; ++_i) \
;         __builtin_amdgcn_global_load_lds((const unsigned*)((const char*)(gbase) + (voff)[_i]), (PG8_LAS unsigned*)(lds + (bufoff) + ldsw + _i * 8192), 16, 0, 0); } while (0)
; #define PG8_BAR __builtin_amdgcn_s_barrier()
;     __device__ bool next(int i, Unit& u) const { if (i > 1 || !so.next(0, u)) return false; if (i == 1) { u.pm += 64; u.pn += 4; } return true; }
; template <class Epi, class Sched, bool ALIGN_EPI = false, bool SP2 = false>
; __device__ __forceinline__ void gemm_phase(PG8_LAS unsigned char* lds, const Gemm g, const Sched& S, const Epi& E) {
;     ...
;     for (int i = 0; i < 2; ++i) { int R, C; stage_rc(tid * 16 + i * 8192, R, C); const int Rb = Epi::PERM ? ((R & ~31) + perm32(R & 31)) : R;
;         voffA[i] = (unsigned)(R * K + C) * 2u; voffB[i] = (unsigned)(Rb * K + C) * 2u; }
;     const size_t kstep = (size_t)(BK * 2);
;     const size_t hstep = (size_t)HALF * K * 2;
;     const size_t tstep = 2 * hstep;
;     const unsigned ldsw = (unsigned)wid * 1024u;
;     const int aoff = lds_byte(wr * 64 + fr, fq * 8), boff = lds_byte(wc * 32 + fr, fq * 8);
;     ...
;     Unit cur, nxt; int ui = 0;
;     if (!S.next(0, cur)) return;
;     f32x4 acc[2][2][4][2];
; #pragma unroll
;     for (int a = 0; a < 2; ++a)
; #pragma unroll
;         for (int b = 0; b < 2; ++b)
; #pragma unroll
;             for (int m = 0; m < 4; ++m)
; #pragma unroll
;                 for (int n = 0; n < 2; ++n) acc[a][b][m][n] = (f32x4){0.f, 0.f, 0.f, 0.f};
;     bf16x8 At[4][2], B0[2][2], B1[2][2];
;     const char* cA = (const char*)g.A + (size_t)cur.pm * tstep; const char* cB = (const char*)g.Bt + (size_t)cur.pn * tstep;
;     S.a_ready(cur);
;     if constexpr (SP2) {
;         PG8_STAGE(PG8_SB(0, 0), cB, voffB); PG8_STAGE(PG8_SB(0, 1), cB + hstep, voffB); PG8_STAGE(PG8_SA(0, 0), cA, voffA); PG8_STAGE(PG8_SA(0, 1), cA + hstep, voffA);
;         if (wr == 1) PG8_BAR;
.LBB0_640:
	s_andn2_b64 vcc, exec, s[4:5]
	s_cbranch_vccnz .LBB0_718
	v_lshrrev_b32_e32 v2, 1, v226
	v_and_b32_e32 v11, 24, v2
	v_lshrrev_b32_e32 v2, 5, v226
	v_and_b32_e32 v2, 4, v2
	v_bfe_u32 v3, v226, 2, 2
	v_lshlrev_b32_e32 v0, 4, v226
	s_waitcnt lgkmcnt(0)
	v_and_b32_e32 v1, 32, v226
	v_bfe_u32 v10, v226, 2, 4
	v_or3_b32 v2, v2, v3, v11
	v_lshrrev_b32_e32 v3, 3, v226
	s_movk_i32 s5, 0x70
	v_bitop3_b32 v8, v0, v1, 48 bitop3:0x6c
	v_and_b32_e32 v9, 64, v226
	v_and_or_b32 v4, v3, s5, v10
	s_movk_i32 s5, 0x60
	v_add_u32_e32 v12, 0x2000, v0
	v_or_b32_e32 v1, v8, v9
	v_and_or_b32 v3, v3, s5, v2
	v_lshrrev_b32_e32 v0, 7, v12
	s_movk_i32 s5, 0xf0
	v_lshl_or_b32 v164, v3, 10, v1
	v_and_or_b32 v3, v0, s5, v10
	s_movk_i32 s5, 0xe0
	v_and_or_b32 v0, v0, s5, v2
	s_lshr_b32 s5, s12, 6
	s_ashr_i32 s7, s6, 31
	s_ashr_i32 s39, s38, 31
	s_lshr_b32 s4, s12, 8
	s_lshl_b32 s19, s5, 10
	s_lshl_b64 s[8:9], s[6:7], 18
	s_lshl_b64 s[10:11], s[38:39], 18
	s_add_u32 s44, s68, s10
	s_addc_u32 s45, s69, s11
	s_add_i32 s48, s19, 0
	s_add_i32 m0, s48, 0x10000
	v_lshl_or_b32 v168, v0, 10, v1
	global_load_lds_dwordx4 v164, s[44:45]
	s_add_i32 m0, s48, 0x12000
	s_add_u32 s10, s44, 0x20000
	global_load_lds_dwordx4 v168, s[44:45]
	s_addc_u32 s11, s45, 0
	s_add_i32 m0, s48, 0x14000
	v_lshl_or_b32 v160, v4, 10, v1
	global_load_lds_dwordx4 v164, s[10:11]
	s_add_i32 m0, s48, 0x16000
	s_add_u32 s40, s3, s8
	s_addc_u32 s41, s62, s9
	s_add_i32 s49, s48, 0x2000
	global_load_lds_dwordx4 v168, s[10:11]
	s_mov_b32 m0, s48
	s_add_u32 s8, s40, 0x20000
	v_lshl_or_b32 v166, v3, 10, v1
	global_load_lds_dwordx4 v160, s[40:41]
	s_mov_b32 m0, s49
	s_addc_u32 s9, s41, 0
	s_add_i32 s50, s48, 0x4000
	global_load_lds_dwordx4 v166, s[40:41]
	s_mov_b32 m0, s50
	s_add_i32 s51, s48, 0x6000
	global_load_lds_dwordx4 v160, s[8:9]
	s_mov_b32 m0, s51
	v_mov_b32_e32 v165, 0
	global_load_lds_dwordx4 v166, s[8:9]
	v_mov_b32_e32 v169, v165
	v_mov_b32_e32 v161, v165
	v_mov_b32_e32 v167, v165
	s_cmp_eq_u32 s4, 1
	v_lshl_add_u64 v[6:7], s[44:45], 0, v[164:165]
	v_lshl_add_u64 v[4:5], s[44:45], 0, v[168:169]
	v_lshl_add_u64 v[0:1], s[40:41], 0, v[160:161]
	s_cselect_b64 s[8:9], -1, 0
	s_cmp_lg_u32 s4, 1
	v_lshl_add_u64 v[2:3], s[40:41], 0, v[166:167]
	s_cbranch_scc1 .LBB0_643
	s_barrier
	s_setprio 1

; #define PG8_STAGE(bufoff, gbase, voff) do { _Pragma("unroll") for (int _i = 0; _i < 2; ++_i) \
;         __builtin_amdgcn_global_load_lds((const unsigned*)((const char*)(gbase) + (voff)[_i]), (PG8_LAS unsigned*)(lds + (bufoff) + ldsw + _i * 8192), 16, 0, 0); } while (0)
; #define PG8_LDA(dst, b, h) do { _Pragma("unroll") for (int m = 0; m < 4; ++m) _Pragma("unroll") for (int k = 0; k < 2; ++k) dst[m][k] = *(const PG8_LAS bf16x8*)(lds + PG8_SA(b, h) + aoff + m * 2048 + k * 1024); } while (0)
; #define PG8_LDB(dst, b, h) do { _Pragma("unroll") for (int n = 0; n < 2; ++n) _Pragma("unroll") for (int k = 0; k < 2; ++k) dst[n][k] = *(const PG8_LAS bf16x8*)(lds + PG8_SB(b, h) + boff + n * 2048 + k * 1024); } while (0)
; #define PG8_MMA(ai, bj, At, Bt) do { __builtin_amdgcn_s_setprio(1); _Pragma("unroll") for (int m = 0; m < 4; ++m) _Pragma("unroll") for (int n = 0; n < 2; ++n) _Pragma("unroll") for (int k = 0; k < 2; ++k) \
;         acc[ai][bj][m][n] = __builtin_amdgcn_mfma_f32_16x16x32_bf16(Bt[n][k], At[m][k], acc[ai][bj][m][n], 0, 0, 0); __builtin_amdgcn_s_setprio(0); } while (0)
; #define PG8_WAIT_V(n) asm volatile("s_waitcnt vmcnt(" #n ")" ::: "memory")
; #define PG8_WAIT_L(n) asm volatile("s_waitcnt lgkmcnt(" #n ")" ::: "memory")
; template <class Epi, class Sched, bool ALIGN_EPI = false, bool SP2 = false>
; __device__ __forceinline__ void gemm_phase(PG8_LAS unsigned char* lds, const Gemm g, const Sched& S, const Epi& E) {
;     ...
;             const bool last = (t == nt - 2);
;             const char* a1 = cA + (size_t)(t + 1) * kstep;
;             const char* a2 = last ? nA : cA + (size_t)(t + 2) * kstep; const char* b2 = last ? nB : cB + (size_t)(t + 2) * kstep;
;             const char* a3 = a2 + kstep; const char* b3 = b2 + kstep;
;             if (last && has_next) S.a_ready(nxt);
;             if constexpr (SP2) {
;             PG8_LDB(B0, 0, 0); PG8_LDB(B1, 0, 1); PG8_SCHED; PG8_LDA(At, 0, 0); PG8_STAGE(PG8_SA(1, 1), a1 + hstep, voffA);
;             PG8_WAIT_V(8); PG8_WAIT_L(0); PG8_BAR; PG8_MMA(0, 0, At, B0); PG8_MMA(0, 1, At, B1); PG8_BAR; PG8_SCHED;
;             PG8_LDA(At, 0, 1); PG8_STAGE(PG8_SB(0, 0), b2, voffB); PG8_STAGE(PG8_SB(0, 1), b2 + hstep, voffB); PG8_STAGE(PG8_SA(0, 0), a2, voffA);
;             PG8_WAIT_V(8); PG8_WAIT_L(0); PG8_BAR; PG8_MMA(1, 0, At, B0); PG8_MMA(1, 1, At, B1); PG8_BAR; PG8_SCHED;
.LBB0_647:
	v_add_u32_e32 v52, s54, v178
	v_add_u32_e32 v116, s55, v178
	ds_read_b128 v[16:19], v52
	ds_read_b128 v[20:23], v52 offset:1024
	ds_read_b128 v[48:51], v52 offset:2048
	ds_read_b128 v[52:55], v52 offset:3072
	ds_read_b128 v[80:83], v116
	ds_read_b128 v[84:87], v116 offset:1024
	ds_read_b128 v[112:115], v116 offset:2048
	ds_read_b128 v[116:119], v116 offset:3072
	s_add_u32 s44, s40, 0xfffe0080
	s_addc_u32 s45, s41, -1
	s_cmp_eq_u32 s59, 4
	s_cselect_b32 s47, s7, s45
	s_cselect_b32 s46, s15, s44
	s_cselect_b32 s45, s17, s58
	s_cselect_b32 s44, s39, s57
	v_lshl_add_u64 v[210:211], s[40:41], 0, v[170:171]
	s_add_i32 m0, s48, 0xc000
	ds_read_b128 v[174:177], v180
	ds_read_b128 v[182:185], v180 offset:1024
	ds_read_b128 v[186:189], v180 offset:2048
	ds_read_b128 v[190:193], v180 offset:3072
	ds_read_b128 v[194:197], v180 offset:4096
	ds_read_b128 v[198:201], v180 offset:5120
	ds_read_b128 v[202:205], v180 offset:6144
	ds_read_b128 v[206:209], v180 offset:7168
	global_load_lds_dwordx4 v[210:211], off
	v_lshl_add_u64 v[210:211], s[40:41], 0, v[172:173]
	s_add_i32 m0, s48, 0xe000
	s_nop 0
	global_load_lds_dwordx4 v[210:211], off
	s_waitcnt vmcnt(8)
	s_waitcnt lgkmcnt(0)
	s_barrier
	s_waitcnt lgkmcnt(0)
	v_mfma_f32_16x16x32_bf16 v[36:39], v[16:19], v[174:177], v[36:39]
	v_mfma_f32_16x16x32_bf16 v[32:35], v[48:51], v[174:177], v[32:35]
	v_mfma_f32_16x16x32_bf16 v[68:71], v[16:19], v[186:189], v[68:71]
	v_mfma_f32_16x16x32_bf16 v[64:67], v[48:51], v[186:189], v[64:67]
	v_mfma_f32_16x16x32_bf16 v[100:103], v[16:19], v[194:197], v[100:103]
	v_mfma_f32_16x16x32_bf16 v[96:99], v[48:51], v[194:197], v[96:99]
	v_mfma_f32_16x16x32_bf16 v[132:135], v[16:19], v[202:205], v[132:135]
	v_mfma_f32_16x16x32_bf16 v[128:131], v[48:51], v[202:205], v[128:131]
	v_mfma_f32_16x16x32_bf16 v[36:39], v[20:23], v[182:185], v[36:39]
	v_mfma_f32_16x16x32_bf16 v[32:35], v[52:55], v[182:185], v[32:35]
	v_mfma_f32_16x16x32_bf16 v[68:71], v[20:23], v[190:193], v[68:71]
	v_mfma_f32_16x16x32_bf16 v[64:67], v[52:55], v[190:193], v[64:67]
	v_mfma_f32_16x16x32_bf16 v[100:103], v[20:23], v[198:201], v[100:103]
	v_mfma_f32_16x16x32_bf16 v[96:99], v[52:55], v[198:201], v[96:99]
	v_mfma_f32_16x16x32_bf16 v[132:135], v[20:23], v[206:209], v[132:135]
	v_mfma_f32_16x16x32_bf16 v[128:131], v[52:55], v[206:209], v[128:131]
	v_mfma_f32_16x16x32_bf16 v[156:159], v[80:83], v[174:177], v[156:159]
	v_mfma_f32_16x16x32_bf16 v[152:155], v[112:115], v[174:177], v[152:155]
	v_mfma_f32_16x16x32_bf16 v[148:151], v[80:83], v[186:189], v[148:151]
	v_mfma_f32_16x16x32_bf16 v[144:147], v[112:115], v[186:189], v[144:147]
	v_mfma_f32_16x16x32_bf16 v[140:143], v[80:83], v[194:197], v[140:143]
	v_mfma_f32_16x16x32_bf16 v[136:139], v[112:115], v[194:197], v[136:139]
	v_mfma_f32_16x16x32_bf16 v[124:127], v[80:83], v[202:205], v[124:127]
	v_mfma_f32_16x16x32_bf16 v[120:123], v[112:115], v[202:205], v[120:123]
	v_mfma_f32_16x16x32_bf16 v[156:159], v[84:87], v[182:185], v[156:159]
	v_mfma_f32_16x16x32_bf16 v[152:155], v[116:119], v[182:185], v[152:155]
	v_mfma_f32_16x16x32_bf16 v[148:151], v[84:87], v[190:193], v[148:151]
	v_mfma_f32_16x16x32_bf16 v[144:147], v[116:119], v[190:193], v[144:147]
	v_mfma_f32_16x16x32_bf16 v[140:143], v[84:87], v[198:201], v[140:143]
	v_mfma_f32_16x16x32_bf16 v[136:139], v[116:119], v[198:201], v[136:139]
	v_mfma_f32_16x16x32_bf16 v[124:127], v[84:87], v[206:209], v[124:127]
	v_mfma_f32_16x16x32_bf16 v[120:123], v[116:119], v[206:209], v[120:123]
	s_barrier
	s_add_i32 s60, s54, s19
	v_lshl_add_u64 v[214:215], s[44:45], 0, v[164:165]
	s_mov_b32 m0, s60
	ds_read_b128 v[174:177], v180 offset:16384
	ds_read_b128 v[182:185], v180 offset:17408
	ds_read_b128 v[186:189], v180 offset:18432
	ds_read_b128 v[190:193], v180 offset:19456
	ds_read_b128 v[194:197], v180 offset:20480
	ds_read_b128 v[198:201], v180 offset:21504
	ds_read_b128 v[202:205], v180 offset:22528
	ds_read_b128 v[206:209], v180 offset:23552
	global_load_lds_dwordx4 v[214:215], off
	s_add_i32 m0, s60, 0x2000
	s_add_u32 s60, s44, 0x20000
	v_lshl_add_u64 v[216:217], s[44:45], 0, v[168:169]
	s_addc_u32 s61, s45, 0
	s_add_i32 s63, s55, s19
	global_load_lds_dwordx4 v[216:217], off
	v_lshl_add_u64 v[210:211], s[60:61], 0, v[164:165]
	s_mov_b32 m0, s63
	v_lshl_add_u64 v[218:219], s[46:47], 0, v[160:161]
	global_load_lds_dwordx4 v[210:211], off
	v_lshl_add_u64 v[210:211], s[60:61], 0, v[168:169]
	s_add_i32 m0, s63, 0x2000
	v_lshl_add_u64 v[220:221], s[46:47], 0, v[166:167]
	global_load_lds_dwordx4 v[210:211], off
	s_mov_b32 m0, s48
	s_nop 0
	global_load_lds_dwordx4 v[218:219], off
	s_mov_b32 m0, s49
	s_nop 0
	global_load_lds_dwordx4 v[220:221], off
	s_waitcnt vmcnt(8)
	s_waitcnt lgkmcnt(0)
	s_barrier
; #define PG8_STAGE(bufoff, gbase, voff) do { _Pragma("unroll") for (int _i = 0; _i < 2; ++_i) \
;         __builtin_amdgcn_global_load_lds((const unsigned*)((const char*)(gbase) + (voff)[_i]), (PG8_LAS unsigned*)(lds + (bufoff) + ldsw + _i * 8192), 16, 0, 0); } while (0)
; #define PG8_LDA(dst, b, h) do { _Pragma("unroll") for (int m = 0; m < 4; ++m) _Pragma("unroll") for (int k = 0; k < 2; ++k) dst[m][k] = *(const PG8_LAS bf16x8*)(lds + PG8_SA(b, h) + aoff + m * 2048 + k * 1024); } while (0)
; #define PG8_LDB(dst, b, h) do { _Pragma("unroll") for (int n = 0; n < 2; ++n) _Pragma("unroll") for (int k = 0; k < 2; ++k) dst[n][k] = *(const PG8_LAS bf16x8*)(lds + PG8_SB(b, h) + boff + n * 2048 + k * 1024); } while (0)
; #define PG8_MMA(ai, bj, At, Bt) do { __builtin_amdgcn_s_setprio(1); _Pragma("unroll") for (int m = 0; m < 4; ++m) _Pragma("unroll") for (int n = 0; n < 2; ++n) _Pragma("unroll") for (int k = 0; k < 2; ++k) \
;         acc[ai][bj][m][n] = __builtin_amdgcn_mfma_f32_16x16x32_bf16(Bt[n][k], At[m][k], acc[ai][bj][m][n], 0, 0, 0); __builtin_amdgcn_s_setprio(0); } while (0)
; #define PG8_WAIT_V(n) asm volatile("s_waitcnt vmcnt(" #n ")" ::: "memory")
; #define PG8_WAIT_L(n) asm volatile("s_waitcnt lgkmcnt(" #n ")" ::: "memory")
; #define PG8_BAR __builtin_amdgcn_s_barrier()
; #define PG8_SCHED __builtin_amdgcn_sched_barrier(0)
; template <class Epi, class Sched, bool ALIGN_EPI = false, bool SP2 = false>
; __device__ __forceinline__ void gemm_phase(PG8_LAS unsigned char* lds, const Gemm g, const Sched& S, const Epi& E) {
;     ...
;             PG8_WAIT_V(8); PG8_WAIT_L(0); PG8_BAR; PG8_MMA(1, 0, At, B0); PG8_MMA(1, 1, At, B1); PG8_BAR; PG8_SCHED;
;             PG8_LDB(B0, 1, 0); PG8_LDB(B1, 1, 1); PG8_SCHED; PG8_LDA(At, 1, 0); PG8_STAGE(PG8_SA(0, 1), a2 + hstep, voffA);
;             PG8_WAIT_V(8); PG8_WAIT_L(0); PG8_BAR; PG8_MMA(0, 0, At, B0); PG8_MMA(0, 1, At, B1); PG8_BAR; PG8_SCHED;
;             PG8_LDA(At, 1, 1); PG8_STAGE(PG8_SB(1, 0), b3, voffB); PG8_STAGE(PG8_SB(1, 1), b3 + hstep, voffB); PG8_STAGE(PG8_SA(1, 0), a3, voffA);
	s_waitcnt lgkmcnt(0)
	v_mfma_f32_16x16x32_bf16 v[108:111], v[16:19], v[174:177], v[108:111]
	v_mfma_f32_16x16x32_bf16 v[104:107], v[48:51], v[174:177], v[104:107]
	v_mfma_f32_16x16x32_bf16 v[76:79], v[16:19], v[186:189], v[76:79]
	v_mfma_f32_16x16x32_bf16 v[72:75], v[48:51], v[186:189], v[72:75]
	v_mfma_f32_16x16x32_bf16 v[44:47], v[16:19], v[194:197], v[44:47]
	v_mfma_f32_16x16x32_bf16 v[40:43], v[48:51], v[194:197], v[40:43]
	v_mfma_f32_16x16x32_bf16 v[12:15], v[16:19], v[202:205], v[12:15]
	v_mfma_f32_16x16x32_bf16 v[8:11], v[48:51], v[202:205], v[8:11]
	v_mfma_f32_16x16x32_bf16 v[108:111], v[20:23], v[182:185], v[108:111]
	v_mfma_f32_16x16x32_bf16 v[104:107], v[52:55], v[182:185], v[104:107]
	v_mfma_f32_16x16x32_bf16 v[76:79], v[20:23], v[190:193], v[76:79]
	v_mfma_f32_16x16x32_bf16 v[72:75], v[52:55], v[190:193], v[72:75]
	v_mfma_f32_16x16x32_bf16 v[44:47], v[20:23], v[198:201], v[44:47]
	v_mfma_f32_16x16x32_bf16 v[40:43], v[52:55], v[198:201], v[40:43]
	v_mfma_f32_16x16x32_bf16 v[12:15], v[20:23], v[206:209], v[12:15]
	v_mfma_f32_16x16x32_bf16 v[8:11], v[52:55], v[206:209], v[8:11]
	v_mfma_f32_16x16x32_bf16 v[28:31], v[80:83], v[194:197], v[28:31]
	v_mfma_f32_16x16x32_bf16 v[24:27], v[112:115], v[194:197], v[24:27]
	v_mfma_f32_16x16x32_bf16 v[4:7], v[80:83], v[202:205], v[4:7]
	v_mfma_f32_16x16x32_bf16 v[0:3], v[112:115], v[202:205], v[0:3]
	v_mfma_f32_16x16x32_bf16 v[16:19], v[80:83], v[174:177], v[92:95]
	v_mfma_f32_16x16x32_bf16 v[20:23], v[112:115], v[174:177], v[88:91]
	v_mfma_f32_16x16x32_bf16 v[48:51], v[80:83], v[186:189], v[60:63]
	v_mfma_f32_16x16x32_bf16 v[52:55], v[112:115], v[186:189], v[56:59]
	v_mfma_f32_16x16x32_bf16 v[28:31], v[84:87], v[198:201], v[28:31]
	v_mfma_f32_16x16x32_bf16 v[24:27], v[116:119], v[198:201], v[24:27]
	v_mfma_f32_16x16x32_bf16 v[4:7], v[84:87], v[206:209], v[4:7]
	v_mfma_f32_16x16x32_bf16 v[0:3], v[116:119], v[206:209], v[0:3]
	v_mfma_f32_16x16x32_bf16 v[16:19], v[84:87], v[182:185], v[16:19]
	v_mfma_f32_16x16x32_bf16 v[20:23], v[116:119], v[182:185], v[20:23]
	v_mfma_f32_16x16x32_bf16 v[48:51], v[84:87], v[190:193], v[48:51]
	v_mfma_f32_16x16x32_bf16 v[52:55], v[116:119], v[190:193], v[52:55]
	s_barrier
	s_add_i32 s60, 0, 0x18000
	s_add_i32 s61, 0, 0x1c000
	v_add_u32_e32 v84, s60, v178
	v_add_u32_e32 v88, s61, v178
	ds_read_b128 v[56:59], v84
	ds_read_b128 v[60:63], v84 offset:1024
	ds_read_b128 v[80:83], v84 offset:2048
	ds_read_b128 v[84:87], v84 offset:3072
	ds_read_b128 v[112:115], v88
	ds_read_b128 v[116:119], v88 offset:1024
	ds_read_b128 v[174:177], v88 offset:2048
	ds_read_b128 v[182:185], v88 offset:3072
	s_add_u32 s46, s46, 0x20000
	s_addc_u32 s47, s47, 0
	s_mov_b32 m0, s50
	v_lshl_add_u64 v[210:211], s[46:47], 0, v[160:161]
	ds_read_b128 v[88:91], v180 offset:32768
	ds_read_b128 v[92:95], v180 offset:33792
	ds_read_b128 v[186:189], v180 offset:34816
	ds_read_b128 v[190:193], v180 offset:35840
	ds_read_b128 v[194:197], v180 offset:36864
	ds_read_b128 v[198:201], v180 offset:37888
	ds_read_b128 v[202:205], v180 offset:38912
	ds_read_b128 v[206:209], v180 offset:39936
	global_load_lds_dwordx4 v[210:211], off
	v_lshl_add_u64 v[210:211], s[46:47], 0, v[166:167]
	s_mov_b32 m0, s51
	s_nop 0
	global_load_lds_dwordx4 v[210:211], off
	s_waitcnt vmcnt(8)
	s_waitcnt lgkmcnt(0)
	s_barrier
	s_waitcnt lgkmcnt(0)
	v_mfma_f32_16x16x32_bf16 v[36:39], v[56:59], v[88:91], v[36:39]
	v_mfma_f32_16x16x32_bf16 v[32:35], v[80:83], v[88:91], v[32:35]
	v_mfma_f32_16x16x32_bf16 v[68:71], v[56:59], v[186:189], v[68:71]
	v_mfma_f32_16x16x32_bf16 v[64:67], v[80:83], v[186:189], v[64:67]
	v_mfma_f32_16x16x32_bf16 v[100:103], v[56:59], v[194:197], v[100:103]
	v_mfma_f32_16x16x32_bf16 v[96:99], v[80:83], v[194:197], v[96:99]
	v_mfma_f32_16x16x32_bf16 v[132:135], v[56:59], v[202:205], v[132:135]
	v_mfma_f32_16x16x32_bf16 v[128:131], v[80:83], v[202:205], v[128:131]
	v_mfma_f32_16x16x32_bf16 v[36:39], v[60:63], v[92:95], v[36:39]
	v_mfma_f32_16x16x32_bf16 v[32:35], v[84:87], v[92:95], v[32:35]
	v_mfma_f32_16x16x32_bf16 v[68:71], v[60:63], v[190:193], v[68:71]
	v_mfma_f32_16x16x32_bf16 v[64:67], v[84:87], v[190:193], v[64:67]
	v_mfma_f32_16x16x32_bf16 v[100:103], v[60:63], v[198:201], v[100:103]
	v_mfma_f32_16x16x32_bf16 v[96:99], v[84:87], v[198:201], v[96:99]
	v_mfma_f32_16x16x32_bf16 v[132:135], v[60:63], v[206:209], v[132:135]
	v_mfma_f32_16x16x32_bf16 v[128:131], v[84:87], v[206:209], v[128:131]
	v_mfma_f32_16x16x32_bf16 v[156:159], v[112:115], v[88:91], v[156:159]
	v_mfma_f32_16x16x32_bf16 v[88:91], v[174:177], v[88:91], v[152:155]
	v_mfma_f32_16x16x32_bf16 v[152:155], v[182:185], v[92:95], v[88:91]
	v_mfma_f32_16x16x32_bf16 v[88:91], v[112:115], v[186:189], v[148:151]
	v_mfma_f32_16x16x32_bf16 v[148:151], v[116:119], v[190:193], v[88:91]
	v_mfma_f32_16x16x32_bf16 v[88:91], v[174:177], v[186:189], v[144:147]
	v_mfma_f32_16x16x32_bf16 v[144:147], v[182:185], v[190:193], v[88:91]
	v_mfma_f32_16x16x32_bf16 v[88:91], v[112:115], v[194:197], v[140:143]
	v_mfma_f32_16x16x32_bf16 v[140:143], v[116:119], v[198:201], v[88:91]
	v_mfma_f32_16x16x32_bf16 v[88:91], v[174:177], v[194:197], v[136:139]
	v_mfma_f32_16x16x32_bf16 v[136:139], v[182:185], v[198:201], v[88:91]
	v_mfma_f32_16x16x32_bf16 v[88:91], v[112:115], v[202:205], v[124:127]
	v_mfma_f32_16x16x32_bf16 v[124:127], v[116:119], v[206:209], v[88:91]
	v_mfma_f32_16x16x32_bf16 v[88:91], v[174:177], v[202:205], v[120:123]
	v_mfma_f32_16x16x32_bf16 v[156:159], v[116:119], v[92:95], v[156:159]
	v_mfma_f32_16x16x32_bf16 v[120:123], v[182:185], v[206:209], v[88:91]
	s_barrier
; #define PG8_STAGE(bufoff, gbase, voff) do { _Pragma("unroll") for (int _i = 0; _i < 2; ++_i) \
;         __builtin_amdgcn_global_load_lds((const unsigned*)((const char*)(gbase) + (voff)[_i]), (PG8_LAS unsigned*)(lds + (bufoff) + ldsw + _i * 8192), 16, 0, 0); } while (0)
; #define PG8_LDA(dst, b, h) do { _Pragma("unroll") for (int m = 0; m < 4; ++m) _Pragma("unroll") for (int k = 0; k < 2; ++k) dst[m][k] = *(const PG8_LAS bf16x8*)(lds + PG8_SA(b, h) + aoff + m * 2048 + k * 1024); } while (0)
; #define PG8_MMA(ai, bj, At, Bt) do { __builtin_amdgcn_s_setprio(1); _Pragma("unroll") for (int m = 0; m < 4; ++m) _Pragma("unroll") for (int n = 0; n < 2; ++n) _Pragma("unroll") for (int k = 0; k < 2; ++k) \
;         acc[ai][bj][m][n] = __builtin_amdgcn_mfma_f32_16x16x32_bf16(Bt[n][k], At[m][k], acc[ai][bj][m][n], 0, 0, 0); __builtin_amdgcn_s_setprio(0); } while (0)
; #define PG8_WAIT_V(n) asm volatile("s_waitcnt vmcnt(" #n ")" ::: "memory")
; #define PG8_WAIT_L(n) asm volatile("s_waitcnt lgkmcnt(" #n ")" ::: "memory")
; #define PG8_BAR __builtin_amdgcn_s_barrier()
; #define PG8_SCHED __builtin_amdgcn_sched_barrier(0)
; template <class Epi, class Sched, bool ALIGN_EPI = false, bool SP2 = false>
; __device__ __forceinline__ void gemm_phase(PG8_LAS unsigned char* lds, const Gemm g, const Sched& S, const Epi& E) {
;     ...
;             PG8_LDA(At, 1, 1); PG8_STAGE(PG8_SB(1, 0), b3, voffB); PG8_STAGE(PG8_SB(1, 1), b3 + hstep, voffB); PG8_STAGE(PG8_SA(1, 0), a3, voffA);
;             PG8_WAIT_V(8); PG8_WAIT_L(0); PG8_BAR; PG8_MMA(1, 0, At, B0); PG8_MMA(1, 1, At, B1); PG8_BAR; PG8_SCHED;
;     ...
;         if constexpr (ALIGN_EPI) { if (wr == 0) PG8_BAR; }
	s_add_i32 s46, s60, s19
	v_lshl_add_u64 v[92:93], v[214:215], 0, s[10:11]
	s_mov_b32 m0, s46
	s_nop 0
	ds_read_b128 v[88:91], v180 offset:49152
	ds_read_b128 v[186:189], v180 offset:50176
	ds_read_b128 v[190:193], v180 offset:51200
	ds_read_b128 v[194:197], v180 offset:52224
	ds_read_b128 v[198:201], v180 offset:53248
	ds_read_b128 v[202:205], v180 offset:54272
	ds_read_b128 v[206:209], v180 offset:55296
	ds_read_b128 v[210:213], v180 offset:56320
	global_load_lds_dwordx4 v[92:93], off
	s_add_i32 m0, s46, 0x2000
	s_add_u32 s44, s44, 0x20080
	v_lshl_add_u64 v[92:93], v[216:217], 0, s[10:11]
	s_addc_u32 s45, s45, 0
	s_add_i32 s46, s61, s19
	global_load_lds_dwordx4 v[92:93], off
	v_lshl_add_u64 v[92:93], s[44:45], 0, v[164:165]
	s_mov_b32 m0, s46
	s_nop 0
	global_load_lds_dwordx4 v[92:93], off
	v_lshl_add_u64 v[92:93], s[44:45], 0, v[168:169]
	s_add_i32 m0, s46, 0x2000
	s_nop 0
	global_load_lds_dwordx4 v[92:93], off
	v_lshl_add_u64 v[92:93], v[218:219], 0, s[10:11]
	s_mov_b32 m0, s52
	s_nop 0
	global_load_lds_dwordx4 v[92:93], off
	v_lshl_add_u64 v[92:93], v[220:221], 0, s[10:11]
	s_mov_b32 m0, s53
	s_nop 0
	global_load_lds_dwordx4 v[92:93], off
	s_waitcnt vmcnt(8)
	s_waitcnt lgkmcnt(0)
	s_barrier
	s_waitcnt lgkmcnt(0)
	v_mfma_f32_16x16x32_bf16 v[92:95], v[56:59], v[88:91], v[108:111]
	v_mfma_f32_16x16x32_bf16 v[108:111], v[60:63], v[186:189], v[92:95]
	v_mfma_f32_16x16x32_bf16 v[92:95], v[80:83], v[88:91], v[104:107]
	v_mfma_f32_16x16x32_bf16 v[76:79], v[56:59], v[190:193], v[76:79]
	v_mfma_f32_16x16x32_bf16 v[72:75], v[80:83], v[190:193], v[72:75]
	v_mfma_f32_16x16x32_bf16 v[44:47], v[56:59], v[198:201], v[44:47]
	v_mfma_f32_16x16x32_bf16 v[40:43], v[80:83], v[198:201], v[40:43]
	v_mfma_f32_16x16x32_bf16 v[12:15], v[56:59], v[206:209], v[12:15]
	v_mfma_f32_16x16x32_bf16 v[8:11], v[80:83], v[206:209], v[8:11]
	v_mfma_f32_16x16x32_bf16 v[104:107], v[84:87], v[186:189], v[92:95]
	v_mfma_f32_16x16x32_bf16 v[76:79], v[60:63], v[194:197], v[76:79]
	v_mfma_f32_16x16x32_bf16 v[72:75], v[84:87], v[194:197], v[72:75]
	v_mfma_f32_16x16x32_bf16 v[44:47], v[60:63], v[202:205], v[44:47]
	v_mfma_f32_16x16x32_bf16 v[40:43], v[84:87], v[202:205], v[40:43]
	v_mfma_f32_16x16x32_bf16 v[12:15], v[60:63], v[210:213], v[12:15]
	v_mfma_f32_16x16x32_bf16 v[8:11], v[84:87], v[210:213], v[8:11]
	v_mfma_f32_16x16x32_bf16 v[16:19], v[112:115], v[88:91], v[16:19]
	v_mfma_f32_16x16x32_bf16 v[92:95], v[116:119], v[186:189], v[16:19]
	v_mfma_f32_16x16x32_bf16 v[16:19], v[174:177], v[88:91], v[20:23]
	v_mfma_f32_16x16x32_bf16 v[88:91], v[182:185], v[186:189], v[16:19]
	v_mfma_f32_16x16x32_bf16 v[16:19], v[112:115], v[190:193], v[48:51]
	v_mfma_f32_16x16x32_bf16 v[60:63], v[116:119], v[194:197], v[16:19]
	v_mfma_f32_16x16x32_bf16 v[16:19], v[174:177], v[190:193], v[52:55]
	v_mfma_f32_16x16x32_bf16 v[56:59], v[182:185], v[194:197], v[16:19]
	v_mfma_f32_16x16x32_bf16 v[16:19], v[112:115], v[198:201], v[28:31]
	v_mfma_f32_16x16x32_bf16 v[28:31], v[116:119], v[202:205], v[16:19]
	v_mfma_f32_16x16x32_bf16 v[16:19], v[174:177], v[198:201], v[24:27]
	v_mfma_f32_16x16x32_bf16 v[4:7], v[112:115], v[206:209], v[4:7]
	v_mfma_f32_16x16x32_bf16 v[0:3], v[174:177], v[206:209], v[0:3]
	v_mfma_f32_16x16x32_bf16 v[24:27], v[182:185], v[202:205], v[16:19]
	v_mfma_f32_16x16x32_bf16 v[4:7], v[116:119], v[210:213], v[4:7]
	v_mfma_f32_16x16x32_bf16 v[0:3], v[182:185], v[210:213], v[0:3]
	s_barrier
	s_add_i32 s59, s59, 2
	s_add_u32 s40, s40, 0x100
	s_addc_u32 s41, s41, 0
	s_add_u32 s57, s57, 0x100
	s_addc_u32 s58, s58, 0
	s_cmp_gt_u32 s59, 5
	s_cbranch_scc0 .LBB0_647
	s_and_b64 vcc, exec, s[12:13]
	s_cbranch_vccz .LBB0_650
	s_barrier

; #define PG8_STAGE(bufoff, gbase, voff) do { _Pragma("unroll") for (int _i = 0; _i < 2; ++_i) \
;         __builtin_amdgcn_global_load_lds((const unsigned*)((const char*)(gbase) + (voff)[_i]), (PG8_LAS unsigned*)(lds + (bufoff) + ldsw + _i * 8192), 16, 0, 0); } while (0)
; #define PG8_BAR __builtin_amdgcn_s_barrier()
;     __device__ bool next(int i, Unit& u) const { if (i > 1 || !so.next(0, u)) return false; if (i == 1) { u.pm += 64; u.pn += 4; } return true; }
; template <class Epi, class Sched, bool ALIGN_EPI = false, bool SP2 = false>
; __device__ __forceinline__ void gemm_phase(PG8_LAS unsigned char* lds, const Gemm g, const Sched& S, const Epi& E) {
;     ...
;     for (int i = 0; i < 2; ++i) { int R, C; stage_rc(tid * 16 + i * 8192, R, C); const int Rb = Epi::PERM ? ((R & ~31) + perm32(R & 31)) : R;
;         voffA[i] = (unsigned)(R * K + C) * 2u; voffB[i] = (unsigned)(Rb * K + C) * 2u; }
;     const size_t kstep = (size_t)(BK * 2);
;     const size_t hstep = (size_t)HALF * K * 2;
;     const size_t tstep = 2 * hstep;
;     const unsigned ldsw = (unsigned)wid * 1024u;
;     const int aoff = lds_byte(wr * 64 + fr, fq * 8), boff = lds_byte(wc * 32 + fr, fq * 8);
;     ...
;     Unit cur, nxt; int ui = 0;
;     if (!S.next(0, cur)) return;
;     f32x4 acc[2][2][4][2];
; #pragma unroll
;     for (int a = 0; a < 2; ++a)
; #pragma unroll
;         for (int b = 0; b < 2; ++b)
; #pragma unroll
;             for (int m = 0; m < 4; ++m)
; #pragma unroll
;                 for (int n = 0; n < 2; ++n) acc[a][b][m][n] = (f32x4){0.f, 0.f, 0.f, 0.f};
;     bf16x8 At[4][2], B0[2][2], B1[2][2];
;     const char* cA = (const char*)g.A + (size_t)cur.pm * tstep; const char* cB = (const char*)g.Bt + (size_t)cur.pn * tstep;
;     S.a_ready(cur);
;     if constexpr (SP2) {
;         PG8_STAGE(PG8_SB(0, 0), cB, voffB); PG8_STAGE(PG8_SB(0, 1), cB + hstep, voffB); PG8_STAGE(PG8_SA(0, 0), cA, voffA); PG8_STAGE(PG8_SA(0, 1), cA + hstep, voffA);
;         if (wr == 1) PG8_BAR;
.LBB0_795:
	s_andn2_b64 vcc, exec, s[4:5]
	s_cbranch_vccnz .LBB0_831
	v_lshrrev_b32_e32 v2, 1, v226
	v_lshrrev_b32_e32 v3, 5, v226
	v_and_b32_e32 v2, 24, v2
	v_and_b32_e32 v3, 4, v3
	v_bfe_u32 v4, v226, 2, 2
	v_lshlrev_b32_e32 v0, 4, v226
	s_waitcnt lgkmcnt(0)
	v_and_b32_e32 v1, 32, v226
	v_bfe_u32 v10, v226, 2, 4
	v_or3_b32 v2, v3, v4, v2
	v_lshrrev_b32_e32 v3, 3, v226
	s_movk_i32 s3, 0x70
	v_bitop3_b32 v8, v0, v1, 48 bitop3:0x6c
	v_and_b32_e32 v9, 64, v226
	v_and_or_b32 v4, v3, s3, v10
	s_movk_i32 s3, 0x60
	v_add_u32_e32 v11, 0x2000, v0
	v_or_b32_e32 v1, v8, v9
	v_and_or_b32 v3, v3, s3, v2
	v_lshrrev_b32_e32 v0, 7, v11
	s_movk_i32 s3, 0xf0
	s_lshr_b32 s5, s18, 6
	v_lshl_or_b32 v146, v3, 11, v1
	v_and_or_b32 v3, v0, s3, v10
	s_movk_i32 s3, 0xe0
	s_ashr_i32 s41, s40, 31
	s_ashr_i32 s13, s12, 31
	v_and_or_b32 v0, v0, s3, v2
	s_lshr_b32 s4, s18, 8
	s_lshl_b32 s3, s5, 10
	s_lshl_b64 s[6:7], s[40:41], 19
	s_lshl_b64 s[14:15], s[12:13], 19
	s_add_u32 s46, s92, s14
	s_addc_u32 s47, s93, s15
	s_add_i32 s50, s3, 0
	s_add_i32 m0, s50, 0x10000
	v_lshl_or_b32 v150, v0, 11, v1
	global_load_lds_dwordx4 v146, s[46:47]
	s_add_i32 m0, s50, 0x12000
	s_add_u32 s14, s46, 0x40000
	global_load_lds_dwordx4 v150, s[46:47]
	s_addc_u32 s15, s47, 0
	s_add_i32 m0, s50, 0x14000
	v_lshl_or_b32 v144, v4, 11, v1
	global_load_lds_dwordx4 v146, s[14:15]
	s_add_i32 m0, s50, 0x16000
	s_add_u32 s44, s30, s6
	s_addc_u32 s45, s31, s7
	s_add_i32 s51, s50, 0x2000
	global_load_lds_dwordx4 v150, s[14:15]
	s_mov_b32 m0, s50
	s_add_u32 s6, s44, 0x40000
	v_lshl_or_b32 v148, v3, 11, v1
	global_load_lds_dwordx4 v144, s[44:45]
	s_mov_b32 m0, s51
	s_addc_u32 s7, s45, 0
	s_add_i32 s52, s50, 0x4000
	global_load_lds_dwordx4 v148, s[44:45]
	s_mov_b32 m0, s52
	s_add_i32 s53, s50, 0x6000
	global_load_lds_dwordx4 v144, s[6:7]
	s_mov_b32 m0, s53
	v_mov_b32_e32 v147, 0
	global_load_lds_dwordx4 v148, s[6:7]
	v_mov_b32_e32 v151, v147
	v_mov_b32_e32 v145, v147
	v_mov_b32_e32 v149, v147
	s_cmp_eq_u32 s4, 1
	s_mov_b32 s13, 0
	v_lshl_add_u64 v[6:7], s[46:47], 0, v[146:147]
	v_lshl_add_u64 v[4:5], s[46:47], 0, v[150:151]
	v_lshl_add_u64 v[0:1], s[44:45], 0, v[144:145]
	s_cselect_b64 s[14:15], -1, 0
	s_cmp_lg_u32 s4, 1
	v_lshl_add_u64 v[2:3], s[44:45], 0, v[148:149]
	s_cbranch_scc1 .LBB0_798
	s_barrier
	s_setprio 1

; #define PG8_STAGE(bufoff, gbase, voff) do { _Pragma("unroll") for (int _i = 0; _i < 2; ++_i) \
;         __builtin_amdgcn_global_load_lds((const unsigned*)((const char*)(gbase) + (voff)[_i]), (PG8_LAS unsigned*)(lds + (bufoff) + ldsw + _i * 8192), 16, 0, 0); } while (0)
; #define PG8_LDA(dst, b, h) do { _Pragma("unroll") for (int m = 0; m < 4; ++m) _Pragma("unroll") for (int k = 0; k < 2; ++k) dst[m][k] = *(const PG8_LAS bf16x8*)(lds + PG8_SA(b, h) + aoff + m * 2048 + k * 1024); } while (0)
; #define PG8_LDB(dst, b, h) do { _Pragma("unroll") for (int n = 0; n < 2; ++n) _Pragma("unroll") for (int k = 0; k < 2; ++k) dst[n][k] = *(const PG8_LAS bf16x8*)(lds + PG8_SB(b, h) + boff + n * 2048 + k * 1024); } while (0)
; #define PG8_MMA(ai, bj, At, Bt) do { __builtin_amdgcn_s_setprio(1); _Pragma("unroll") for (int m = 0; m < 4; ++m) _Pragma("unroll") for (int n = 0; n < 2; ++n) _Pragma("unroll") for (int k = 0; k < 2; ++k) \
;         acc[ai][bj][m][n] = __builtin_amdgcn_mfma_f32_16x16x32_bf16(Bt[n][k], At[m][k], acc[ai][bj][m][n], 0, 0, 0); __builtin_amdgcn_s_setprio(0); } while (0)
; #define PG8_WAIT_V(n) asm volatile("s_waitcnt vmcnt(" #n ")" ::: "memory")
; #define PG8_WAIT_L(n) asm volatile("s_waitcnt lgkmcnt(" #n ")" ::: "memory")
; template <class Epi, class Sched, bool ALIGN_EPI = false, bool SP2 = false>
; __device__ __forceinline__ void gemm_phase(PG8_LAS unsigned char* lds, const Gemm g, const Sched& S, const Epi& E) {
;     ...
;             const bool last = (t == nt - 2);
;             const char* a1 = cA + (size_t)(t + 1) * kstep;
;             const char* a2 = last ? nA : cA + (size_t)(t + 2) * kstep; const char* b2 = last ? nB : cB + (size_t)(t + 2) * kstep;
;             const char* a3 = a2 + kstep; const char* b3 = b2 + kstep;
;             if (last && has_next) S.a_ready(nxt);
;             if constexpr (SP2) {
;             PG8_LDB(B0, 0, 0); PG8_LDB(B1, 0, 1); PG8_SCHED; PG8_LDA(At, 0, 0); PG8_STAGE(PG8_SA(1, 1), a1 + hstep, voffA);
;             PG8_WAIT_V(8); PG8_WAIT_L(0); PG8_BAR; PG8_MMA(0, 0, At, B0); PG8_MMA(0, 1, At, B1); PG8_BAR; PG8_SCHED;
;             PG8_LDA(At, 0, 1); PG8_STAGE(PG8_SB(0, 0), b2, voffB); PG8_STAGE(PG8_SB(0, 1), b2 + hstep, voffB); PG8_STAGE(PG8_SA(0, 0), a2, voffA);
;             PG8_WAIT_V(8); PG8_WAIT_L(0); PG8_BAR; PG8_MMA(1, 0, At, B0); PG8_MMA(1, 1, At, B1); PG8_BAR; PG8_SCHED;
.LBB0_808:
	ds_read_b128 v[80:83], v168
	ds_read_b128 v[84:87], v168 offset:1024
	ds_read_b128 v[96:99], v168 offset:2048
	ds_read_b128 v[100:103], v168 offset:3072
	ds_read_b128 v[172:175], v169
	ds_read_b128 v[176:179], v169 offset:1024
	ds_read_b128 v[180:183], v169 offset:2048
	ds_read_b128 v[184:187], v169 offset:3072
	s_add_u32 s46, s44, 0xfffc0080
	s_addc_u32 s47, s45, -1
	s_cmp_eq_u32 s71, 12
	s_cselect_b32 s49, s23, s47
	s_cselect_b32 s48, s41, s46
	s_cselect_b32 s47, s21, s70
	s_cselect_b32 s46, s68, s69
	v_lshl_add_u64 v[160:161], s[44:45], 0, v[152:153]
	s_add_i32 m0, s50, 0xc000
	ds_read_b128 v[188:191], v170
	ds_read_b128 v[192:195], v170 offset:1024
	ds_read_b128 v[196:199], v170 offset:2048
	ds_read_b128 v[200:203], v170 offset:3072
	ds_read_b128 v[204:207], v170 offset:4096
	ds_read_b128 v[208:211], v170 offset:5120
	ds_read_b128 v[212:215], v170 offset:6144
	ds_read_b128 v[216:219], v170 offset:7168
	global_load_lds_dwordx4 v[160:161], off
	v_lshl_add_u64 v[160:161], s[44:45], 0, v[154:155]
	s_add_i32 m0, s50, 0xe000
	s_nop 0
	global_load_lds_dwordx4 v[160:161], off
	s_waitcnt vmcnt(8)
	s_waitcnt lgkmcnt(0)
	s_barrier
	s_waitcnt lgkmcnt(0)
	v_mfma_f32_16x16x32_bf16 v[140:143], v[80:83], v[188:191], v[140:143]
	v_mfma_f32_16x16x32_bf16 v[136:139], v[96:99], v[188:191], v[136:139]
	v_mfma_f32_16x16x32_bf16 v[124:127], v[80:83], v[196:199], v[124:127]
	v_mfma_f32_16x16x32_bf16 v[120:123], v[96:99], v[196:199], v[120:123]
	v_mfma_f32_16x16x32_bf16 v[108:111], v[80:83], v[204:207], v[108:111]
	v_mfma_f32_16x16x32_bf16 v[104:107], v[96:99], v[204:207], v[104:107]
	v_mfma_f32_16x16x32_bf16 v[76:79], v[80:83], v[212:215], v[76:79]
	v_mfma_f32_16x16x32_bf16 v[72:75], v[96:99], v[212:215], v[72:75]
	v_mfma_f32_16x16x32_bf16 v[140:143], v[84:87], v[192:195], v[140:143]
	v_mfma_f32_16x16x32_bf16 v[136:139], v[100:103], v[192:195], v[136:139]
	v_mfma_f32_16x16x32_bf16 v[124:127], v[84:87], v[200:203], v[124:127]
	v_mfma_f32_16x16x32_bf16 v[120:123], v[100:103], v[200:203], v[120:123]
	v_mfma_f32_16x16x32_bf16 v[108:111], v[84:87], v[208:211], v[108:111]
	v_mfma_f32_16x16x32_bf16 v[104:107], v[100:103], v[208:211], v[104:107]
	v_mfma_f32_16x16x32_bf16 v[76:79], v[84:87], v[216:219], v[76:79]
	v_mfma_f32_16x16x32_bf16 v[72:75], v[100:103], v[216:219], v[72:75]
	v_mfma_f32_16x16x32_bf16 v[132:135], v[172:175], v[188:191], v[132:135]
	v_mfma_f32_16x16x32_bf16 v[128:131], v[180:183], v[188:191], v[128:131]
	v_mfma_f32_16x16x32_bf16 v[116:119], v[172:175], v[196:199], v[116:119]
	v_mfma_f32_16x16x32_bf16 v[112:115], v[180:183], v[196:199], v[112:115]
	v_mfma_f32_16x16x32_bf16 v[92:95], v[172:175], v[204:207], v[92:95]
	v_mfma_f32_16x16x32_bf16 v[88:91], v[180:183], v[204:207], v[88:91]
	v_mfma_f32_16x16x32_bf16 v[68:71], v[172:175], v[212:215], v[68:71]
	v_mfma_f32_16x16x32_bf16 v[64:67], v[180:183], v[212:215], v[64:67]
	v_mfma_f32_16x16x32_bf16 v[132:135], v[176:179], v[192:195], v[132:135]
	v_mfma_f32_16x16x32_bf16 v[128:131], v[184:187], v[192:195], v[128:131]
	v_mfma_f32_16x16x32_bf16 v[116:119], v[176:179], v[200:203], v[116:119]
	v_mfma_f32_16x16x32_bf16 v[112:115], v[184:187], v[200:203], v[112:115]
	v_mfma_f32_16x16x32_bf16 v[92:95], v[176:179], v[208:211], v[92:95]
	v_mfma_f32_16x16x32_bf16 v[88:91], v[184:187], v[208:211], v[88:91]
	v_mfma_f32_16x16x32_bf16 v[68:71], v[176:179], v[216:219], v[68:71]
	v_mfma_f32_16x16x32_bf16 v[64:67], v[184:187], v[216:219], v[64:67]
	s_barrier
	s_add_i32 s72, s63, s3
	v_lshl_add_u64 v[160:161], s[46:47], 0, v[146:147]
	s_mov_b32 m0, s72
	ds_read_b128 v[188:191], v170 offset:16384
	ds_read_b128 v[192:195], v170 offset:17408
	ds_read_b128 v[196:199], v170 offset:18432
	ds_read_b128 v[200:203], v170 offset:19456
	ds_read_b128 v[204:207], v170 offset:20480
	ds_read_b128 v[208:211], v170 offset:21504
	ds_read_b128 v[212:215], v170 offset:22528
	ds_read_b128 v[216:219], v170 offset:23552
	global_load_lds_dwordx4 v[160:161], off
	s_add_i32 m0, s72, 0x2000
	s_add_u32 s72, s46, 0x40000
	v_lshl_add_u64 v[164:165], s[46:47], 0, v[150:151]
	s_addc_u32 s73, s47, 0
	s_add_i32 s74, s64, s3
	global_load_lds_dwordx4 v[164:165], off
	v_lshl_add_u64 v[220:221], s[72:73], 0, v[146:147]
	s_mov_b32 m0, s74
	v_lshl_add_u64 v[222:223], s[48:49], 0, v[148:149]
	global_load_lds_dwordx4 v[220:221], off
	v_lshl_add_u64 v[220:221], s[72:73], 0, v[150:151]
	s_add_i32 m0, s74, 0x2000
	s_nop 0
	global_load_lds_dwordx4 v[220:221], off
	v_lshl_add_u64 v[220:221], s[48:49], 0, v[144:145]
	s_mov_b32 m0, s50
	s_nop 0
	global_load_lds_dwordx4 v[220:221], off
	s_mov_b32 m0, s51
	s_nop 0
	global_load_lds_dwordx4 v[222:223], off
	s_waitcnt vmcnt(8)
	s_waitcnt lgkmcnt(0)
	s_barrier
; #define PG8_STAGE(bufoff, gbase, voff) do { _Pragma("unroll") for (int _i = 0; _i < 2; ++_i) \
;         __builtin_amdgcn_global_load_lds((const unsigned*)((const char*)(gbase) + (voff)[_i]), (PG8_LAS unsigned*)(lds + (bufoff) + ldsw + _i * 8192), 16, 0, 0); } while (0)
; #define PG8_LDA(dst, b, h) do { _Pragma("unroll") for (int m = 0; m < 4; ++m) _Pragma("unroll") for (int k = 0; k < 2; ++k) dst[m][k] = *(const PG8_LAS bf16x8*)(lds + PG8_SA(b, h) + aoff + m * 2048 + k * 1024); } while (0)
; #define PG8_LDB(dst, b, h) do { _Pragma("unroll") for (int n = 0; n < 2; ++n) _Pragma("unroll") for (int k = 0; k < 2; ++k) dst[n][k] = *(const PG8_LAS bf16x8*)(lds + PG8_SB(b, h) + boff + n * 2048 + k * 1024); } while (0)
; #define PG8_MMA(ai, bj, At, Bt) do { __builtin_amdgcn_s_setprio(1); _Pragma("unroll") for (int m = 0; m < 4; ++m) _Pragma("unroll") for (int n = 0; n < 2; ++n) _Pragma("unroll") for (int k = 0; k < 2; ++k) \
;         acc[ai][bj][m][n] = __builtin_amdgcn_mfma_f32_16x16x32_bf16(Bt[n][k], At[m][k], acc[ai][bj][m][n], 0, 0, 0); __builtin_amdgcn_s_setprio(0); } while (0)
; #define PG8_WAIT_V(n) asm volatile("s_waitcnt vmcnt(" #n ")" ::: "memory")
; #define PG8_WAIT_L(n) asm volatile("s_waitcnt lgkmcnt(" #n ")" ::: "memory")
; #define PG8_BAR __builtin_amdgcn_s_barrier()
; #define PG8_SCHED __builtin_amdgcn_sched_barrier(0)
; template <class Epi, class Sched, bool ALIGN_EPI = false, bool SP2 = false>
; __device__ __forceinline__ void gemm_phase(PG8_LAS unsigned char* lds, const Gemm g, const Sched& S, const Epi& E) {
;     ...
;             PG8_WAIT_V(8); PG8_WAIT_L(0); PG8_BAR; PG8_MMA(1, 0, At, B0); PG8_MMA(1, 1, At, B1); PG8_BAR; PG8_SCHED;
;             PG8_LDB(B0, 1, 0); PG8_LDB(B1, 1, 1); PG8_SCHED; PG8_LDA(At, 1, 0); PG8_STAGE(PG8_SA(0, 1), a2 + hstep, voffA);
;             PG8_WAIT_V(8); PG8_WAIT_L(0); PG8_BAR; PG8_MMA(0, 0, At, B0); PG8_MMA(0, 1, At, B1); PG8_BAR; PG8_SCHED;
;             PG8_LDA(At, 1, 1); PG8_STAGE(PG8_SB(1, 0), b3, voffB); PG8_STAGE(PG8_SB(1, 1), b3 + hstep, voffB); PG8_STAGE(PG8_SA(1, 0), a3, voffA);
	s_waitcnt lgkmcnt(0)
	v_mfma_f32_16x16x32_bf16 v[60:63], v[80:83], v[188:191], v[60:63]
	v_mfma_f32_16x16x32_bf16 v[56:59], v[96:99], v[188:191], v[56:59]
	v_mfma_f32_16x16x32_bf16 v[44:47], v[80:83], v[196:199], v[44:47]
	v_mfma_f32_16x16x32_bf16 v[40:43], v[96:99], v[196:199], v[40:43]
	v_mfma_f32_16x16x32_bf16 v[28:31], v[80:83], v[204:207], v[28:31]
	v_mfma_f32_16x16x32_bf16 v[24:27], v[96:99], v[204:207], v[24:27]
	v_mfma_f32_16x16x32_bf16 v[12:15], v[80:83], v[212:215], v[12:15]
	v_mfma_f32_16x16x32_bf16 v[8:11], v[96:99], v[212:215], v[8:11]
	v_mfma_f32_16x16x32_bf16 v[60:63], v[84:87], v[192:195], v[60:63]
	v_mfma_f32_16x16x32_bf16 v[56:59], v[100:103], v[192:195], v[56:59]
	v_mfma_f32_16x16x32_bf16 v[44:47], v[84:87], v[200:203], v[44:47]
	v_mfma_f32_16x16x32_bf16 v[40:43], v[100:103], v[200:203], v[40:43]
	v_mfma_f32_16x16x32_bf16 v[28:31], v[84:87], v[208:211], v[28:31]
	v_mfma_f32_16x16x32_bf16 v[24:27], v[100:103], v[208:211], v[24:27]
	v_mfma_f32_16x16x32_bf16 v[12:15], v[84:87], v[216:219], v[12:15]
	v_mfma_f32_16x16x32_bf16 v[8:11], v[100:103], v[216:219], v[8:11]
	v_mfma_f32_16x16x32_bf16 v[52:55], v[172:175], v[188:191], v[52:55]
	v_mfma_f32_16x16x32_bf16 v[48:51], v[180:183], v[188:191], v[48:51]
	v_mfma_f32_16x16x32_bf16 v[36:39], v[172:175], v[196:199], v[36:39]
	v_mfma_f32_16x16x32_bf16 v[32:35], v[180:183], v[196:199], v[32:35]
	v_mfma_f32_16x16x32_bf16 v[20:23], v[172:175], v[204:207], v[20:23]
	v_mfma_f32_16x16x32_bf16 v[16:19], v[180:183], v[204:207], v[16:19]
	v_mfma_f32_16x16x32_bf16 v[4:7], v[172:175], v[212:215], v[4:7]
	v_mfma_f32_16x16x32_bf16 v[0:3], v[180:183], v[212:215], v[0:3]
	v_mfma_f32_16x16x32_bf16 v[52:55], v[176:179], v[192:195], v[52:55]
	v_mfma_f32_16x16x32_bf16 v[48:51], v[184:187], v[192:195], v[48:51]
	v_mfma_f32_16x16x32_bf16 v[36:39], v[176:179], v[200:203], v[36:39]
	v_mfma_f32_16x16x32_bf16 v[32:35], v[184:187], v[200:203], v[32:35]
	v_mfma_f32_16x16x32_bf16 v[20:23], v[176:179], v[208:211], v[20:23]
	v_mfma_f32_16x16x32_bf16 v[16:19], v[184:187], v[208:211], v[16:19]
	v_mfma_f32_16x16x32_bf16 v[4:7], v[176:179], v[216:219], v[4:7]
	v_mfma_f32_16x16x32_bf16 v[0:3], v[184:187], v[216:219], v[0:3]
	s_barrier
	s_add_i32 s72, 0, 0x18000
	s_add_i32 s73, 0, 0x1c000
	v_add_u32_e32 v100, s72, v166
	v_add_u32_e32 v184, s73, v166
	ds_read_b128 v[80:83], v100
	ds_read_b128 v[84:87], v100 offset:1024
	ds_read_b128 v[96:99], v100 offset:2048
	ds_read_b128 v[100:103], v100 offset:3072
	ds_read_b128 v[172:175], v184
	ds_read_b128 v[176:179], v184 offset:1024
	ds_read_b128 v[180:183], v184 offset:2048
	ds_read_b128 v[184:187], v184 offset:3072
	s_add_u32 s48, s48, 0x40000
	s_addc_u32 s49, s49, 0
	s_mov_b32 m0, s52
	v_lshl_add_u64 v[224:225], s[48:49], 0, v[144:145]
	ds_read_b128 v[188:191], v170 offset:32768
	ds_read_b128 v[192:195], v170 offset:33792
	ds_read_b128 v[196:199], v170 offset:34816
	ds_read_b128 v[200:203], v170 offset:35840
	ds_read_b128 v[204:207], v170 offset:36864
	ds_read_b128 v[208:211], v170 offset:37888
	ds_read_b128 v[212:215], v170 offset:38912
	ds_read_b128 v[216:219], v170 offset:39936
	global_load_lds_dwordx4 v[224:225], off
	v_lshl_add_u64 v[224:225], s[48:49], 0, v[148:149]
	s_mov_b32 m0, s53
	s_nop 0
	global_load_lds_dwordx4 v[224:225], off
	s_waitcnt vmcnt(8)
	s_waitcnt lgkmcnt(0)
	s_barrier
	s_waitcnt lgkmcnt(0)
	v_mfma_f32_16x16x32_bf16 v[140:143], v[80:83], v[188:191], v[140:143]
	v_mfma_f32_16x16x32_bf16 v[136:139], v[96:99], v[188:191], v[136:139]
	v_mfma_f32_16x16x32_bf16 v[124:127], v[80:83], v[196:199], v[124:127]
	v_mfma_f32_16x16x32_bf16 v[120:123], v[96:99], v[196:199], v[120:123]
	v_mfma_f32_16x16x32_bf16 v[108:111], v[80:83], v[204:207], v[108:111]
	v_mfma_f32_16x16x32_bf16 v[104:107], v[96:99], v[204:207], v[104:107]
	v_mfma_f32_16x16x32_bf16 v[76:79], v[80:83], v[212:215], v[76:79]
	v_mfma_f32_16x16x32_bf16 v[72:75], v[96:99], v[212:215], v[72:75]
	v_mfma_f32_16x16x32_bf16 v[140:143], v[84:87], v[192:195], v[140:143]
	v_mfma_f32_16x16x32_bf16 v[136:139], v[100:103], v[192:195], v[136:139]
	v_mfma_f32_16x16x32_bf16 v[124:127], v[84:87], v[200:203], v[124:127]
	v_mfma_f32_16x16x32_bf16 v[120:123], v[100:103], v[200:203], v[120:123]
	v_mfma_f32_16x16x32_bf16 v[108:111], v[84:87], v[208:211], v[108:111]
	v_mfma_f32_16x16x32_bf16 v[104:107], v[100:103], v[208:211], v[104:107]
	v_mfma_f32_16x16x32_bf16 v[76:79], v[84:87], v[216:219], v[76:79]
	v_mfma_f32_16x16x32_bf16 v[72:75], v[100:103], v[216:219], v[72:75]
	v_mfma_f32_16x16x32_bf16 v[132:135], v[172:175], v[188:191], v[132:135]
	v_mfma_f32_16x16x32_bf16 v[128:131], v[180:183], v[188:191], v[128:131]
	v_mfma_f32_16x16x32_bf16 v[116:119], v[172:175], v[196:199], v[116:119]
	v_mfma_f32_16x16x32_bf16 v[112:115], v[180:183], v[196:199], v[112:115]
	v_mfma_f32_16x16x32_bf16 v[92:95], v[172:175], v[204:207], v[92:95]
	v_mfma_f32_16x16x32_bf16 v[88:91], v[180:183], v[204:207], v[88:91]
	v_mfma_f32_16x16x32_bf16 v[68:71], v[172:175], v[212:215], v[68:71]
	v_mfma_f32_16x16x32_bf16 v[64:67], v[180:183], v[212:215], v[64:67]
	v_mfma_f32_16x16x32_bf16 v[132:135], v[176:179], v[192:195], v[132:135]
	v_mfma_f32_16x16x32_bf16 v[128:131], v[184:187], v[192:195], v[128:131]
	v_mfma_f32_16x16x32_bf16 v[116:119], v[176:179], v[200:203], v[116:119]
	v_mfma_f32_16x16x32_bf16 v[112:115], v[184:187], v[200:203], v[112:115]
	v_mfma_f32_16x16x32_bf16 v[92:95], v[176:179], v[208:211], v[92:95]
	v_mfma_f32_16x16x32_bf16 v[88:91], v[184:187], v[208:211], v[88:91]
	v_mfma_f32_16x16x32_bf16 v[68:71], v[176:179], v[216:219], v[68:71]
	v_mfma_f32_16x16x32_bf16 v[64:67], v[184:187], v[216:219], v[64:67]
	s_barrier
; #define PG8_STAGE(bufoff, gbase, voff) do { _Pragma("unroll") for (int _i = 0; _i < 2; ++_i) \
;         __builtin_amdgcn_global_load_lds((const unsigned*)((const char*)(gbase) + (voff)[_i]), (PG8_LAS unsigned*)(lds + (bufoff) + ldsw + _i * 8192), 16, 0, 0); } while (0)
; #define PG8_LDA(dst, b, h) do { _Pragma("unroll") for (int m = 0; m < 4; ++m) _Pragma("unroll") for (int k = 0; k < 2; ++k) dst[m][k] = *(const PG8_LAS bf16x8*)(lds + PG8_SA(b, h) + aoff + m * 2048 + k * 1024); } while (0)
; #define PG8_MMA(ai, bj, At, Bt) do { __builtin_amdgcn_s_setprio(1); _Pragma("unroll") for (int m = 0; m < 4; ++m) _Pragma("unroll") for (int n = 0; n < 2; ++n) _Pragma("unroll") for (int k = 0; k < 2; ++k) \
;         acc[ai][bj][m][n] = __builtin_amdgcn_mfma_f32_16x16x32_bf16(Bt[n][k], At[m][k], acc[ai][bj][m][n], 0, 0, 0); __builtin_amdgcn_s_setprio(0); } while (0)
; #define PG8_WAIT_V(n) asm volatile("s_waitcnt vmcnt(" #n ")" ::: "memory")
; #define PG8_WAIT_L(n) asm volatile("s_waitcnt lgkmcnt(" #n ")" ::: "memory")
; #define PG8_BAR __builtin_amdgcn_s_barrier()
; #define PG8_SCHED __builtin_amdgcn_sched_barrier(0)
; template <class Epi, class Sched, bool ALIGN_EPI = false, bool SP2 = false>
; __device__ __forceinline__ void gemm_phase(PG8_LAS unsigned char* lds, const Gemm g, const Sched& S, const Epi& E) {
;     ...
;             PG8_LDA(At, 1, 1); PG8_STAGE(PG8_SB(1, 0), b3, voffB); PG8_STAGE(PG8_SB(1, 1), b3 + hstep, voffB); PG8_STAGE(PG8_SA(1, 0), a3, voffA);
;             PG8_WAIT_V(8); PG8_WAIT_L(0); PG8_BAR; PG8_MMA(1, 0, At, B0); PG8_MMA(1, 1, At, B1); PG8_BAR; PG8_SCHED;
;     ...
;         if constexpr (ALIGN_EPI) { if (wr == 0) PG8_BAR; }
	s_add_i32 s48, s72, s3
	v_lshl_add_u64 v[160:161], v[160:161], 0, s[16:17]
	s_mov_b32 m0, s48
	ds_read_b128 v[188:191], v170 offset:49152
	ds_read_b128 v[192:195], v170 offset:50176
	ds_read_b128 v[196:199], v170 offset:51200
	ds_read_b128 v[200:203], v170 offset:52224
	ds_read_b128 v[204:207], v170 offset:53248
	ds_read_b128 v[208:211], v170 offset:54272
	ds_read_b128 v[212:215], v170 offset:55296
	ds_read_b128 v[216:219], v170 offset:56320
	global_load_lds_dwordx4 v[160:161], off
	s_add_i32 m0, s48, 0x2000
	s_add_u32 s46, s46, 0x40080
	v_lshl_add_u64 v[160:161], v[164:165], 0, s[16:17]
	s_addc_u32 s47, s47, 0
	s_add_i32 s48, s73, s3
	global_load_lds_dwordx4 v[160:161], off
	v_lshl_add_u64 v[160:161], s[46:47], 0, v[146:147]
	s_mov_b32 m0, s48
	s_nop 0
	global_load_lds_dwordx4 v[160:161], off
	v_lshl_add_u64 v[160:161], s[46:47], 0, v[150:151]
	s_add_i32 m0, s48, 0x2000
	s_nop 0
	global_load_lds_dwordx4 v[160:161], off
	v_lshl_add_u64 v[160:161], v[220:221], 0, s[16:17]
	s_mov_b32 m0, s57
	s_nop 0
	global_load_lds_dwordx4 v[160:161], off
	v_lshl_add_u64 v[160:161], v[222:223], 0, s[16:17]
	s_mov_b32 m0, s58
	s_nop 0
	global_load_lds_dwordx4 v[160:161], off
	s_waitcnt vmcnt(8)
	s_waitcnt lgkmcnt(0)
	s_barrier
	s_waitcnt lgkmcnt(0)
	v_mfma_f32_16x16x32_bf16 v[60:63], v[80:83], v[188:191], v[60:63]
	v_mfma_f32_16x16x32_bf16 v[56:59], v[96:99], v[188:191], v[56:59]
	v_mfma_f32_16x16x32_bf16 v[44:47], v[80:83], v[196:199], v[44:47]
	v_mfma_f32_16x16x32_bf16 v[40:43], v[96:99], v[196:199], v[40:43]
	v_mfma_f32_16x16x32_bf16 v[28:31], v[80:83], v[204:207], v[28:31]
	v_mfma_f32_16x16x32_bf16 v[24:27], v[96:99], v[204:207], v[24:27]
	v_mfma_f32_16x16x32_bf16 v[12:15], v[80:83], v[212:215], v[12:15]
	v_mfma_f32_16x16x32_bf16 v[8:11], v[96:99], v[212:215], v[8:11]
	v_mfma_f32_16x16x32_bf16 v[60:63], v[84:87], v[192:195], v[60:63]
	v_mfma_f32_16x16x32_bf16 v[56:59], v[100:103], v[192:195], v[56:59]
	v_mfma_f32_16x16x32_bf16 v[44:47], v[84:87], v[200:203], v[44:47]
	v_mfma_f32_16x16x32_bf16 v[40:43], v[100:103], v[200:203], v[40:43]
	v_mfma_f32_16x16x32_bf16 v[28:31], v[84:87], v[208:211], v[28:31]
	v_mfma_f32_16x16x32_bf16 v[24:27], v[100:103], v[208:211], v[24:27]
	v_mfma_f32_16x16x32_bf16 v[12:15], v[84:87], v[216:219], v[12:15]
	v_mfma_f32_16x16x32_bf16 v[8:11], v[100:103], v[216:219], v[8:11]
	v_mfma_f32_16x16x32_bf16 v[52:55], v[172:175], v[188:191], v[52:55]
	v_mfma_f32_16x16x32_bf16 v[48:51], v[180:183], v[188:191], v[48:51]
	v_mfma_f32_16x16x32_bf16 v[36:39], v[172:175], v[196:199], v[36:39]
	v_mfma_f32_16x16x32_bf16 v[32:35], v[180:183], v[196:199], v[32:35]
	v_mfma_f32_16x16x32_bf16 v[20:23], v[172:175], v[204:207], v[20:23]
	v_mfma_f32_16x16x32_bf16 v[16:19], v[180:183], v[204:207], v[16:19]
	v_mfma_f32_16x16x32_bf16 v[4:7], v[172:175], v[212:215], v[4:7]
	v_mfma_f32_16x16x32_bf16 v[0:3], v[180:183], v[212:215], v[0:3]
	v_mfma_f32_16x16x32_bf16 v[52:55], v[176:179], v[192:195], v[52:55]
	v_mfma_f32_16x16x32_bf16 v[48:51], v[184:187], v[192:195], v[48:51]
	v_mfma_f32_16x16x32_bf16 v[36:39], v[176:179], v[200:203], v[36:39]
	v_mfma_f32_16x16x32_bf16 v[32:35], v[184:187], v[200:203], v[32:35]
	v_mfma_f32_16x16x32_bf16 v[20:23], v[176:179], v[208:211], v[20:23]
	v_mfma_f32_16x16x32_bf16 v[16:19], v[184:187], v[208:211], v[16:19]
	v_mfma_f32_16x16x32_bf16 v[4:7], v[176:179], v[216:219], v[4:7]
	v_mfma_f32_16x16x32_bf16 v[0:3], v[184:187], v[216:219], v[0:3]
	s_barrier
	s_add_i32 s71, s71, 2
	s_add_u32 s44, s44, 0x100
	s_addc_u32 s45, s45, 0
	s_add_u32 s69, s69, 0x100
	s_addc_u32 s70, s70, 0
	s_cmp_gt_u32 s71, 13
	s_cbranch_scc0 .LBB0_808
	s_and_b64 vcc, exec, s[18:19]
	s_cbranch_vccz .LBB0_811
	s_barrier

; #define PG8_STAGE(bufoff, gbase, voff) do { _Pragma("unroll") for (int _i = 0; _i < 2; ++_i) \
;         __builtin_amdgcn_global_load_lds((const unsigned*)((const char*)(gbase) + (voff)[_i]), (PG8_LAS unsigned*)(lds + (bufoff) + ldsw + _i * 8192), 16, 0, 0); } while (0)
; #define PG8_BAR __builtin_amdgcn_s_barrier()
;     __host__ __device__ bool next(int i, Unit& u) const {
;         const long L = (long)i * G + c; if (L >= nwg) return false;
;         int wgid = (int)L; { const int q = nwg / NXCD, r = nwg % NXCD, xcd = wgid % NXCD, off = wgid / NXCD; wgid = (xcd < r ? xcd * (q + 1) : r * (q + 1) + (xcd - r) * q) + off; }
;         const int nig = WGM * nN, gid = wgid / nig, fm = gid * WGM, gsz = (nM - fm) < WGM ? (nM - fm) : WGM;
;         u.pm = fm + ((wgid % nig) % gsz); u.pn = (wgid % nig) / gsz; return true;
; template <class Epi, class Sched, bool ALIGN_EPI = false, bool SP2 = false>
; __device__ __forceinline__ void gemm_phase(PG8_LAS unsigned char* lds, const Gemm g, const Sched& S, const Epi& E) {
;     ...
;     for (int i = 0; i < 2; ++i) { int R, C; stage_rc(tid * 16 + i * 8192, R, C); const int Rb = Epi::PERM ? ((R & ~31) + perm32(R & 31)) : R;
;         voffA[i] = (unsigned)(R * K + C) * 2u; voffB[i] = (unsigned)(Rb * K + C) * 2u; }
;     const size_t kstep = (size_t)(BK * 2);
;     const size_t hstep = (size_t)HALF * K * 2;
;     const size_t tstep = 2 * hstep;
;     const unsigned ldsw = (unsigned)wid * 1024u;
;     const int aoff = lds_byte(wr * 64 + fr, fq * 8), boff = lds_byte(wc * 32 + fr, fq * 8);
;     ...
;     Unit cur, nxt; int ui = 0;
;     if (!S.next(0, cur)) return;
;     f32x4 acc[2][2][4][2];
; #pragma unroll
;     for (int a = 0; a < 2; ++a)
; #pragma unroll
;         for (int b = 0; b < 2; ++b)
; #pragma unroll
;             for (int m = 0; m < 4; ++m)
; #pragma unroll
;                 for (int n = 0; n < 2; ++n) acc[a][b][m][n] = (f32x4){0.f, 0.f, 0.f, 0.f};
;     bf16x8 At[4][2], B0[2][2], B1[2][2];
;     const char* cA = (const char*)g.A + (size_t)cur.pm * tstep; const char* cB = (const char*)g.Bt + (size_t)cur.pn * tstep;
;     S.a_ready(cur);
;     if constexpr (SP2) {
;         PG8_STAGE(PG8_SB(0, 0), cB, voffB); PG8_STAGE(PG8_SB(0, 1), cB + hstep, voffB); PG8_STAGE(PG8_SA(0, 0), cA, voffA); PG8_STAGE(PG8_SA(0, 1), cA + hstep, voffA);
;         if (wr == 1) PG8_BAR;
.LBB0_898:
	s_or_b64 exec, exec, s[12:13]
	s_andn2_b64 vcc, exec, s[4:5]
	v_readfirstlane_b32 s5, v226
	s_waitcnt vmcnt(0) lgkmcnt(0)
	s_barrier
	s_cbranch_vccnz .LBB0_914
	s_mov_b32 s4, 0xb00000
	v_mov_b64_e32 v[2:3], s[28:29]
	v_mad_u64_u32 v[144:145], s[0:1], v0, s4, v[2:3]
	v_mov_b32_e32 v0, v145
	v_mad_u64_u32 v[0:1], s[0:1], v1, s4, v[0:1]
	v_mov_b32_e32 v145, v0
	v_lshrrev_b32_e32 v0, 5, v226
	v_lshrrev_b32_e32 v2, 1, v226
	v_and_b32_e32 v0, 4, v0
	v_bfe_u32 v1, v226, 2, 2
	v_and_b32_e32 v13, 24, v2
	v_or3_b32 v0, v0, v1, v13
	v_lshlrev_b32_e32 v1, 4, v226
	v_add_u32_e32 v10, 0x2000, v1
	v_lshrrev_b32_e32 v2, 7, v10
	s_movk_i32 s0, 0xe0
	v_and_b32_e32 v4, 32, v226
	v_and_or_b32 v3, v2, s0, v0
	v_bitop3_b32 v11, v1, v4, 48 bitop3:0x6c
	v_and_b32_e32 v12, 64, v226
	v_bfe_u32 v14, v226, 2, 4
	s_movk_i32 s0, 0xf0
	v_or_b32_e32 v1, v11, v12
	v_and_or_b32 v2, v2, s0, v14
	v_lshl_or_b32 v148, v2, 11, v1
	v_lshrrev_b32_e32 v2, 3, v226
	s_movk_i32 s0, 0x60
	v_and_or_b32 v0, v2, s0, v0
	s_movk_i32 s0, 0x70
	v_lshl_or_b32 v150, v0, 11, v1
	v_and_or_b32 v0, v2, s0, v14
	s_lshr_b32 s0, s3, 29
	s_add_i32 s0, s2, s0
	s_lshr_b32 s16, s5, 6
	s_ashr_i32 s1, s0, 3
	s_and_b32 s0, s0, -8
	s_lshr_b32 s18, s5, 8
	s_lshl_b32 s40, s16, 10
	s_sub_i32 s0, s2, s0
	s_cmp_lt_i32 s0, 0
	s_movk_i32 s41, 0xb1
	s_cselect_b32 s4, s41, 0xb0
	s_mul_i32 s0, s0, s4
	s_add_i32 s0, s0, s1
	s_mul_hi_i32 s1, s0, 0x2e8ba2e9
	s_lshr_b32 s4, s1, 31
	s_ashr_i32 s1, s1, 5
	s_add_i32 s1, s1, s4
	s_lshl_b32 s10, s1, 3
	s_mulk_i32 s1, 0xb0
	s_sub_i32 s0, s0, s1
	s_sext_i32_i16 s1, s0
	s_bfe_u32 s1, s1, 0x3001c
	s_add_i32 s1, s0, s1
	s_sext_i32_i16 s4, s1
	s_and_b32 s1, s1, 0xfff8
	s_sub_i32 s0, s0, s1
	s_lshr_b32 s4, s4, 3
	s_sext_i32_i16 s0, s0
	s_add_i32 s30, s10, s0
	s_bfe_i64 s[0:1], s[4:5], 0x100000
	s_ashr_i32 s31, s30, 31
	s_lshl_b64 s[0:1], s[0:1], 19
	v_lshl_or_b32 v146, v3, 11, v1
	v_lshl_or_b32 v152, v0, 11, v1
	s_lshl_b64 s[10:11], s[30:31], 19
	v_lshl_add_u64 v[0:1], v[144:145], 0, s[0:1]
	s_add_i32 s31, s40, 0
	v_mov_b32_e32 v151, 0
	s_add_i32 m0, s31, 0x10000
	v_lshl_add_u64 v[2:3], v[0:1], 0, v[150:151]
	v_mov_b32_e32 v147, v151
	s_mov_b64 s[0:1], 0x40000
	global_load_lds_dwordx4 v[2:3], off
	v_lshl_add_u64 v[4:5], v[0:1], 0, v[146:147]
	s_add_i32 m0, s31, 0x12000
	v_lshl_add_u64 v[6:7], v[0:1], 0, s[0:1]
	global_load_lds_dwordx4 v[4:5], off
	s_add_i32 m0, s31, 0x14000
	v_lshl_add_u64 v[8:9], v[6:7], 0, v[150:151]
	global_load_lds_dwordx4 v[8:9], off
	s_add_i32 m0, s31, 0x16000
	s_add_u32 s36, s24, s10
	v_lshl_add_u64 v[6:7], v[6:7], 0, v[146:147]
	s_addc_u32 s37, s25, s11
	s_add_i32 s44, s31, 0x2000
	global_load_lds_dwordx4 v[6:7], off
	s_mov_b32 m0, s31
	s_add_u32 s10, s36, 0x40000
	global_load_lds_dwordx4 v152, s[36:37]
	s_mov_b32 m0, s44
	s_addc_u32 s11, s37, 0
	s_add_i32 s45, s31, 0x4000
	global_load_lds_dwordx4 v148, s[36:37]
	s_mov_b32 m0, s45
	s_add_i32 s46, s31, 0x6000
	global_load_lds_dwordx4 v152, s[10:11]
	s_mov_b32 m0, s46
	v_mov_b32_e32 v153, v151
	global_load_lds_dwordx4 v148, s[10:11]
	v_mov_b32_e32 v149, v151
	s_cmp_eq_u32 s18, 1
	s_mov_b32 s47, 0
	v_lshl_add_u64 v[6:7], s[36:37], 0, v[152:153]
	s_cselect_b64 s[10:11], -1, 0
	s_cmp_lg_u32 s18, 1
	v_lshl_add_u64 v[8:9], s[36:37], 0, v[148:149]
	s_cbranch_scc1 .LBB0_901
	s_barrier
	s_setprio 1

; #define PG8_STAGE(bufoff, gbase, voff) do { _Pragma("unroll") for (int _i = 0; _i < 2; ++_i) \
;         __builtin_amdgcn_global_load_lds((const unsigned*)((const char*)(gbase) + (voff)[_i]), (PG8_LAS unsigned*)(lds + (bufoff) + ldsw + _i * 8192), 16, 0, 0); } while (0)
; #define PG8_LDA(dst, b, h) do { _Pragma("unroll") for (int m = 0; m < 4; ++m) _Pragma("unroll") for (int k = 0; k < 2; ++k) dst[m][k] = *(const PG8_LAS bf16x8*)(lds + PG8_SA(b, h) + aoff + m * 2048 + k * 1024); } while (0)
; #define PG8_LDB(dst, b, h) do { _Pragma("unroll") for (int n = 0; n < 2; ++n) _Pragma("unroll") for (int k = 0; k < 2; ++k) dst[n][k] = *(const PG8_LAS bf16x8*)(lds + PG8_SB(b, h) + boff + n * 2048 + k * 1024); } while (0)
; #define PG8_MMA(ai, bj, At, Bt) do { __builtin_amdgcn_s_setprio(1); _Pragma("unroll") for (int m = 0; m < 4; ++m) _Pragma("unroll") for (int n = 0; n < 2; ++n) _Pragma("unroll") for (int k = 0; k < 2; ++k) \
;         acc[ai][bj][m][n] = __builtin_amdgcn_mfma_f32_16x16x32_bf16(Bt[n][k], At[m][k], acc[ai][bj][m][n], 0, 0, 0); __builtin_amdgcn_s_setprio(0); } while (0)
; #define PG8_WAIT_V(n) asm volatile("s_waitcnt vmcnt(" #n ")" ::: "memory")
; #define PG8_WAIT_L(n) asm volatile("s_waitcnt lgkmcnt(" #n ")" ::: "memory")
; template <class Epi, class Sched, bool ALIGN_EPI = false, bool SP2 = false>
; __device__ __forceinline__ void gemm_phase(PG8_LAS unsigned char* lds, const Gemm g, const Sched& S, const Epi& E) {
;     ...
;             const bool last = (t == nt - 2);
;             const char* a1 = cA + (size_t)(t + 1) * kstep;
;             const char* a2 = last ? nA : cA + (size_t)(t + 2) * kstep; const char* b2 = last ? nB : cB + (size_t)(t + 2) * kstep;
;             const char* a3 = a2 + kstep; const char* b3 = b2 + kstep;
;             if (last && has_next) S.a_ready(nxt);
;             if constexpr (SP2) {
;             PG8_LDB(B0, 0, 0); PG8_LDB(B1, 0, 1); PG8_SCHED; PG8_LDA(At, 0, 0); PG8_STAGE(PG8_SA(1, 1), a1 + hstep, voffA);
;             PG8_WAIT_V(8); PG8_WAIT_L(0); PG8_BAR; PG8_MMA(0, 0, At, B0); PG8_MMA(0, 1, At, B1); PG8_BAR; PG8_SCHED;
;             PG8_LDA(At, 0, 1); PG8_STAGE(PG8_SB(0, 0), b2, voffB); PG8_STAGE(PG8_SB(0, 1), b2 + hstep, voffB); PG8_STAGE(PG8_SA(0, 0), a2, voffA);
;             PG8_WAIT_V(8); PG8_WAIT_L(0); PG8_BAR; PG8_MMA(1, 0, At, B0); PG8_MMA(1, 1, At, B1); PG8_BAR; PG8_SCHED;
.LBB0_907:
	ds_read_b128 v[132:135], v171
	ds_read_b128 v[136:139], v171 offset:1024
	ds_read_b128 v[140:143], v171 offset:2048
	ds_read_b128 v[174:177], v171 offset:3072
	ds_read_b128 v[178:181], v172
	ds_read_b128 v[182:185], v172 offset:1024
	ds_read_b128 v[186:189], v172 offset:2048
	ds_read_b128 v[190:193], v172 offset:3072
	s_add_u32 s59, s36, 0xfffc0080
	s_addc_u32 s60, s37, -1
	s_cmp_eq_u32 s21, 12
	s_cselect_b64 vcc, -1, 0
	s_and_b64 s[38:39], vcc, exec
	v_cndmask_b32_e32 v165, v131, v129, vcc
	s_cselect_b32 s39, s23, s60
	s_cselect_b32 s38, s58, s59
	v_cndmask_b32_e32 v164, v130, v128, vcc
	s_mov_b32 m0, s55
	v_lshl_add_u64 v[228:229], s[36:37], 0, v[154:155]
	ds_read_b128 v[194:197], v173
	ds_read_b128 v[198:201], v173 offset:1024
	ds_read_b128 v[202:205], v173 offset:2048
	ds_read_b128 v[206:209], v173 offset:3072
	ds_read_b128 v[210:213], v173 offset:4096
	ds_read_b128 v[214:217], v173 offset:5120
	ds_read_b128 v[218:221], v173 offset:6144
	ds_read_b128 v[222:225], v173 offset:7168
	global_load_lds_dwordx4 v[228:229], off
	v_lshl_add_u64 v[228:229], s[36:37], 0, v[156:157]
	s_mov_b32 m0, s56
	s_nop 0
	global_load_lds_dwordx4 v[228:229], off
	s_waitcnt vmcnt(8)
	s_waitcnt lgkmcnt(0)
	s_barrier
	s_waitcnt lgkmcnt(0)
	v_mfma_f32_16x16x32_bf16 v[124:127], v[132:135], v[194:197], v[124:127]
	v_mfma_f32_16x16x32_bf16 v[120:123], v[140:143], v[194:197], v[120:123]
	v_mfma_f32_16x16x32_bf16 v[108:111], v[132:135], v[202:205], v[108:111]
	v_mfma_f32_16x16x32_bf16 v[104:107], v[140:143], v[202:205], v[104:107]
	v_mfma_f32_16x16x32_bf16 v[92:95], v[132:135], v[210:213], v[92:95]
	v_mfma_f32_16x16x32_bf16 v[88:91], v[140:143], v[210:213], v[88:91]
	v_mfma_f32_16x16x32_bf16 v[76:79], v[132:135], v[218:221], v[76:79]
	v_mfma_f32_16x16x32_bf16 v[72:75], v[140:143], v[218:221], v[72:75]
	v_mfma_f32_16x16x32_bf16 v[124:127], v[136:139], v[198:201], v[124:127]
	v_mfma_f32_16x16x32_bf16 v[120:123], v[174:177], v[198:201], v[120:123]
	v_mfma_f32_16x16x32_bf16 v[108:111], v[136:139], v[206:209], v[108:111]
	v_mfma_f32_16x16x32_bf16 v[104:107], v[174:177], v[206:209], v[104:107]
	v_mfma_f32_16x16x32_bf16 v[92:95], v[136:139], v[214:217], v[92:95]
	v_mfma_f32_16x16x32_bf16 v[88:91], v[174:177], v[214:217], v[88:91]
	v_mfma_f32_16x16x32_bf16 v[76:79], v[136:139], v[222:225], v[76:79]
	v_mfma_f32_16x16x32_bf16 v[72:75], v[174:177], v[222:225], v[72:75]
	v_mfma_f32_16x16x32_bf16 v[116:119], v[178:181], v[194:197], v[116:119]
	v_mfma_f32_16x16x32_bf16 v[112:115], v[186:189], v[194:197], v[112:115]
	v_mfma_f32_16x16x32_bf16 v[100:103], v[178:181], v[202:205], v[100:103]
	v_mfma_f32_16x16x32_bf16 v[96:99], v[186:189], v[202:205], v[96:99]
	v_mfma_f32_16x16x32_bf16 v[84:87], v[178:181], v[210:213], v[84:87]
	v_mfma_f32_16x16x32_bf16 v[80:83], v[186:189], v[210:213], v[80:83]
	v_mfma_f32_16x16x32_bf16 v[68:71], v[178:181], v[218:221], v[68:71]
	v_mfma_f32_16x16x32_bf16 v[64:67], v[186:189], v[218:221], v[64:67]
	v_mfma_f32_16x16x32_bf16 v[116:119], v[182:185], v[198:201], v[116:119]
	v_mfma_f32_16x16x32_bf16 v[112:115], v[190:193], v[198:201], v[112:115]
	v_mfma_f32_16x16x32_bf16 v[100:103], v[182:185], v[206:209], v[100:103]
	v_mfma_f32_16x16x32_bf16 v[96:99], v[190:193], v[206:209], v[96:99]
	v_mfma_f32_16x16x32_bf16 v[84:87], v[182:185], v[214:217], v[84:87]
	v_mfma_f32_16x16x32_bf16 v[80:83], v[190:193], v[214:217], v[80:83]
	v_mfma_f32_16x16x32_bf16 v[68:71], v[182:185], v[222:225], v[68:71]
	v_mfma_f32_16x16x32_bf16 v[64:67], v[190:193], v[222:225], v[64:67]
	s_barrier
	s_add_i32 s59, s52, s40
	v_lshl_add_u64 v[228:229], v[164:165], 0, v[150:151]
	s_mov_b32 m0, s59
	ds_read_b128 v[194:197], v173 offset:16384
	ds_read_b128 v[198:201], v173 offset:17408
	ds_read_b128 v[202:205], v173 offset:18432
	ds_read_b128 v[206:209], v173 offset:19456
	ds_read_b128 v[210:213], v173 offset:20480
	ds_read_b128 v[214:217], v173 offset:21504
	ds_read_b128 v[218:221], v173 offset:22528
	ds_read_b128 v[222:225], v173 offset:23552
	global_load_lds_dwordx4 v[228:229], off
	v_lshl_add_u64 v[230:231], v[164:165], 0, v[146:147]
	s_add_i32 m0, s59, 0x2000
	v_lshl_add_u64 v[232:233], v[164:165], 0, s[0:1]
	s_add_i32 s59, s53, s40
	global_load_lds_dwordx4 v[230:231], off
	v_lshl_add_u64 v[234:235], v[232:233], 0, v[150:151]
	s_mov_b32 m0, s59
	v_lshl_add_u64 v[232:233], v[232:233], 0, v[146:147]
	global_load_lds_dwordx4 v[234:235], off
	s_add_i32 m0, s59, 0x2000
	v_lshl_add_u64 v[234:235], s[38:39], 0, v[148:149]
	global_load_lds_dwordx4 v[232:233], off
	v_lshl_add_u64 v[232:233], s[38:39], 0, v[152:153]
	s_mov_b32 m0, s31
	s_nop 0
	global_load_lds_dwordx4 v[232:233], off
	s_mov_b32 m0, s44
	s_nop 0
	global_load_lds_dwordx4 v[234:235], off
	s_waitcnt vmcnt(8)
	s_waitcnt lgkmcnt(0)
	s_barrier
; #define PG8_STAGE(bufoff, gbase, voff) do { _Pragma("unroll") for (int _i = 0; _i < 2; ++_i) \
;         __builtin_amdgcn_global_load_lds((const unsigned*)((const char*)(gbase) + (voff)[_i]), (PG8_LAS unsigned*)(lds + (bufoff) + ldsw + _i * 8192), 16, 0, 0); } while (0)
; #define PG8_LDA(dst, b, h) do { _Pragma("unroll") for (int m = 0; m < 4; ++m) _Pragma("unroll") for (int k = 0; k < 2; ++k) dst[m][k] = *(const PG8_LAS bf16x8*)(lds + PG8_SA(b, h) + aoff + m * 2048 + k * 1024); } while (0)
; #define PG8_LDB(dst, b, h) do { _Pragma("unroll") for (int n = 0; n < 2; ++n) _Pragma("unroll") for (int k = 0; k < 2; ++k) dst[n][k] = *(const PG8_LAS bf16x8*)(lds + PG8_SB(b, h) + boff + n * 2048 + k * 1024); } while (0)
; #define PG8_MMA(ai, bj, At, Bt) do { __builtin_amdgcn_s_setprio(1); _Pragma("unroll") for (int m = 0; m < 4; ++m) _Pragma("unroll") for (int n = 0; n < 2; ++n) _Pragma("unroll") for (int k = 0; k < 2; ++k) \
;         acc[ai][bj][m][n] = __builtin_amdgcn_mfma_f32_16x16x32_bf16(Bt[n][k], At[m][k], acc[ai][bj][m][n], 0, 0, 0); __builtin_amdgcn_s_setprio(0); } while (0)
; #define PG8_WAIT_V(n) asm volatile("s_waitcnt vmcnt(" #n ")" ::: "memory")
; #define PG8_WAIT_L(n) asm volatile("s_waitcnt lgkmcnt(" #n ")" ::: "memory")
; #define PG8_BAR __builtin_amdgcn_s_barrier()
; #define PG8_SCHED __builtin_amdgcn_sched_barrier(0)
; template <class Epi, class Sched, bool ALIGN_EPI = false, bool SP2 = false>
; __device__ __forceinline__ void gemm_phase(PG8_LAS unsigned char* lds, const Gemm g, const Sched& S, const Epi& E) {
;     ...
;             PG8_WAIT_V(8); PG8_WAIT_L(0); PG8_BAR; PG8_MMA(1, 0, At, B0); PG8_MMA(1, 1, At, B1); PG8_BAR; PG8_SCHED;
;             PG8_LDB(B0, 1, 0); PG8_LDB(B1, 1, 1); PG8_SCHED; PG8_LDA(At, 1, 0); PG8_STAGE(PG8_SA(0, 1), a2 + hstep, voffA);
;             PG8_WAIT_V(8); PG8_WAIT_L(0); PG8_BAR; PG8_MMA(0, 0, At, B0); PG8_MMA(0, 1, At, B1); PG8_BAR; PG8_SCHED;
;             PG8_LDA(At, 1, 1); PG8_STAGE(PG8_SB(1, 0), b3, voffB); PG8_STAGE(PG8_SB(1, 1), b3 + hstep, voffB); PG8_STAGE(PG8_SA(1, 0), a3, voffA);
	s_waitcnt lgkmcnt(0)
	v_mfma_f32_16x16x32_bf16 v[60:63], v[132:135], v[194:197], v[60:63]
	v_mfma_f32_16x16x32_bf16 v[56:59], v[140:143], v[194:197], v[56:59]
	v_mfma_f32_16x16x32_bf16 v[44:47], v[132:135], v[202:205], v[44:47]
	v_mfma_f32_16x16x32_bf16 v[40:43], v[140:143], v[202:205], v[40:43]
	v_mfma_f32_16x16x32_bf16 v[28:31], v[132:135], v[210:213], v[28:31]
	v_mfma_f32_16x16x32_bf16 v[24:27], v[140:143], v[210:213], v[24:27]
	v_mfma_f32_16x16x32_bf16 v[12:15], v[132:135], v[218:221], v[12:15]
	v_mfma_f32_16x16x32_bf16 v[8:11], v[140:143], v[218:221], v[8:11]
	v_mfma_f32_16x16x32_bf16 v[60:63], v[136:139], v[198:201], v[60:63]
	v_mfma_f32_16x16x32_bf16 v[56:59], v[174:177], v[198:201], v[56:59]
	v_mfma_f32_16x16x32_bf16 v[44:47], v[136:139], v[206:209], v[44:47]
	v_mfma_f32_16x16x32_bf16 v[40:43], v[174:177], v[206:209], v[40:43]
	v_mfma_f32_16x16x32_bf16 v[28:31], v[136:139], v[214:217], v[28:31]
	v_mfma_f32_16x16x32_bf16 v[24:27], v[174:177], v[214:217], v[24:27]
	v_mfma_f32_16x16x32_bf16 v[12:15], v[136:139], v[222:225], v[12:15]
	v_mfma_f32_16x16x32_bf16 v[8:11], v[174:177], v[222:225], v[8:11]
	v_mfma_f32_16x16x32_bf16 v[52:55], v[178:181], v[194:197], v[52:55]
	v_mfma_f32_16x16x32_bf16 v[48:51], v[186:189], v[194:197], v[48:51]
	v_mfma_f32_16x16x32_bf16 v[36:39], v[178:181], v[202:205], v[36:39]
	v_mfma_f32_16x16x32_bf16 v[32:35], v[186:189], v[202:205], v[32:35]
	v_mfma_f32_16x16x32_bf16 v[20:23], v[178:181], v[210:213], v[20:23]
	v_mfma_f32_16x16x32_bf16 v[16:19], v[186:189], v[210:213], v[16:19]
	v_mfma_f32_16x16x32_bf16 v[4:7], v[178:181], v[218:221], v[4:7]
	v_mfma_f32_16x16x32_bf16 v[0:3], v[186:189], v[218:221], v[0:3]
	v_mfma_f32_16x16x32_bf16 v[52:55], v[182:185], v[198:201], v[52:55]
	v_mfma_f32_16x16x32_bf16 v[48:51], v[190:193], v[198:201], v[48:51]
	v_mfma_f32_16x16x32_bf16 v[36:39], v[182:185], v[206:209], v[36:39]
	v_mfma_f32_16x16x32_bf16 v[32:35], v[190:193], v[206:209], v[32:35]
	v_mfma_f32_16x16x32_bf16 v[20:23], v[182:185], v[214:217], v[20:23]
	v_mfma_f32_16x16x32_bf16 v[16:19], v[190:193], v[214:217], v[16:19]
	v_mfma_f32_16x16x32_bf16 v[4:7], v[182:185], v[222:225], v[4:7]
	v_mfma_f32_16x16x32_bf16 v[0:3], v[190:193], v[222:225], v[0:3]
	s_barrier
	s_add_i32 s59, 0, 0x18000
	s_add_i32 s60, 0, 0x1c000
	v_add_u32_e32 v174, s59, v167
	v_add_u32_e32 v190, s60, v167
	ds_read_b128 v[132:135], v174
	ds_read_b128 v[136:139], v174 offset:1024
	ds_read_b128 v[140:143], v174 offset:2048
	ds_read_b128 v[174:177], v174 offset:3072
	ds_read_b128 v[178:181], v190
	ds_read_b128 v[182:185], v190 offset:1024
	ds_read_b128 v[186:189], v190 offset:2048
	ds_read_b128 v[190:193], v190 offset:3072
	s_add_u32 s38, s38, 0x40000
	s_addc_u32 s39, s39, 0
	s_mov_b32 m0, s45
	v_lshl_add_u64 v[236:237], s[38:39], 0, v[152:153]
	ds_read_b128 v[194:197], v173 offset:32768
	ds_read_b128 v[198:201], v173 offset:33792
	ds_read_b128 v[202:205], v173 offset:34816
	ds_read_b128 v[206:209], v173 offset:35840
	ds_read_b128 v[210:213], v173 offset:36864
	ds_read_b128 v[214:217], v173 offset:37888
	ds_read_b128 v[218:221], v173 offset:38912
	ds_read_b128 v[222:225], v173 offset:39936
	global_load_lds_dwordx4 v[236:237], off
	v_lshl_add_u64 v[236:237], s[38:39], 0, v[148:149]
	s_mov_b32 m0, s46
	s_nop 0
	global_load_lds_dwordx4 v[236:237], off
	s_waitcnt vmcnt(8)
	s_waitcnt lgkmcnt(0)
	s_barrier
	s_waitcnt lgkmcnt(0)
	v_mfma_f32_16x16x32_bf16 v[124:127], v[132:135], v[194:197], v[124:127]
	v_mfma_f32_16x16x32_bf16 v[120:123], v[140:143], v[194:197], v[120:123]
	v_mfma_f32_16x16x32_bf16 v[108:111], v[132:135], v[202:205], v[108:111]
	v_mfma_f32_16x16x32_bf16 v[104:107], v[140:143], v[202:205], v[104:107]
	v_mfma_f32_16x16x32_bf16 v[92:95], v[132:135], v[210:213], v[92:95]
	v_mfma_f32_16x16x32_bf16 v[88:91], v[140:143], v[210:213], v[88:91]
	v_mfma_f32_16x16x32_bf16 v[76:79], v[132:135], v[218:221], v[76:79]
	v_mfma_f32_16x16x32_bf16 v[72:75], v[140:143], v[218:221], v[72:75]
	v_mfma_f32_16x16x32_bf16 v[124:127], v[136:139], v[198:201], v[124:127]
	v_mfma_f32_16x16x32_bf16 v[120:123], v[174:177], v[198:201], v[120:123]
	v_mfma_f32_16x16x32_bf16 v[108:111], v[136:139], v[206:209], v[108:111]
	v_mfma_f32_16x16x32_bf16 v[104:107], v[174:177], v[206:209], v[104:107]
	v_mfma_f32_16x16x32_bf16 v[92:95], v[136:139], v[214:217], v[92:95]
	v_mfma_f32_16x16x32_bf16 v[88:91], v[174:177], v[214:217], v[88:91]
	v_mfma_f32_16x16x32_bf16 v[76:79], v[136:139], v[222:225], v[76:79]
	v_mfma_f32_16x16x32_bf16 v[72:75], v[174:177], v[222:225], v[72:75]
	v_mfma_f32_16x16x32_bf16 v[116:119], v[178:181], v[194:197], v[116:119]
	v_mfma_f32_16x16x32_bf16 v[112:115], v[186:189], v[194:197], v[112:115]
	v_mfma_f32_16x16x32_bf16 v[100:103], v[178:181], v[202:205], v[100:103]
	v_mfma_f32_16x16x32_bf16 v[96:99], v[186:189], v[202:205], v[96:99]
	v_mfma_f32_16x16x32_bf16 v[84:87], v[178:181], v[210:213], v[84:87]
	v_mfma_f32_16x16x32_bf16 v[80:83], v[186:189], v[210:213], v[80:83]
	v_mfma_f32_16x16x32_bf16 v[68:71], v[178:181], v[218:221], v[68:71]
	v_mfma_f32_16x16x32_bf16 v[64:67], v[186:189], v[218:221], v[64:67]
	v_mfma_f32_16x16x32_bf16 v[116:119], v[182:185], v[198:201], v[116:119]
	v_mfma_f32_16x16x32_bf16 v[112:115], v[190:193], v[198:201], v[112:115]
	v_mfma_f32_16x16x32_bf16 v[100:103], v[182:185], v[206:209], v[100:103]
	v_mfma_f32_16x16x32_bf16 v[96:99], v[190:193], v[206:209], v[96:99]
	v_mfma_f32_16x16x32_bf16 v[84:87], v[182:185], v[214:217], v[84:87]
	v_mfma_f32_16x16x32_bf16 v[80:83], v[190:193], v[214:217], v[80:83]
	v_mfma_f32_16x16x32_bf16 v[68:71], v[182:185], v[222:225], v[68:71]
	v_mfma_f32_16x16x32_bf16 v[64:67], v[190:193], v[222:225], v[64:67]
	s_barrier
; #define PG8_STAGE(bufoff, gbase, voff) do { _Pragma("unroll") for (int _i = 0; _i < 2; ++_i) \
;         __builtin_amdgcn_global_load_lds((const unsigned*)((const char*)(gbase) + (voff)[_i]), (PG8_LAS unsigned*)(lds + (bufoff) + ldsw + _i * 8192), 16, 0, 0); } while (0)
; #define PG8_LDA(dst, b, h) do { _Pragma("unroll") for (int m = 0; m < 4; ++m) _Pragma("unroll") for (int k = 0; k < 2; ++k) dst[m][k] = *(const PG8_LAS bf16x8*)(lds + PG8_SA(b, h) + aoff + m * 2048 + k * 1024); } while (0)
; #define PG8_MMA(ai, bj, At, Bt) do { __builtin_amdgcn_s_setprio(1); _Pragma("unroll") for (int m = 0; m < 4; ++m) _Pragma("unroll") for (int n = 0; n < 2; ++n) _Pragma("unroll") for (int k = 0; k < 2; ++k) \
;         acc[ai][bj][m][n] = __builtin_amdgcn_mfma_f32_16x16x32_bf16(Bt[n][k], At[m][k], acc[ai][bj][m][n], 0, 0, 0); __builtin_amdgcn_s_setprio(0); } while (0)
; #define PG8_WAIT_V(n) asm volatile("s_waitcnt vmcnt(" #n ")" ::: "memory")
; #define PG8_WAIT_L(n) asm volatile("s_waitcnt lgkmcnt(" #n ")" ::: "memory")
; #define PG8_BAR __builtin_amdgcn_s_barrier()
; #define PG8_SCHED __builtin_amdgcn_sched_barrier(0)
; template <class Epi, class Sched, bool ALIGN_EPI = false, bool SP2 = false>
; __device__ __forceinline__ void gemm_phase(PG8_LAS unsigned char* lds, const Gemm g, const Sched& S, const Epi& E) {
;     ...
;             PG8_LDA(At, 1, 1); PG8_STAGE(PG8_SB(1, 0), b3, voffB); PG8_STAGE(PG8_SB(1, 1), b3 + hstep, voffB); PG8_STAGE(PG8_SA(1, 0), a3, voffA);
;             PG8_WAIT_V(8); PG8_WAIT_L(0); PG8_BAR; PG8_MMA(1, 0, At, B0); PG8_MMA(1, 1, At, B1); PG8_BAR; PG8_SCHED;
;     ...
;         if constexpr (ALIGN_EPI) { if (wr == 0) PG8_BAR; }
	s_add_i32 s38, s59, s40
	v_lshl_add_u64 v[228:229], v[228:229], 0, s[12:13]
	s_mov_b32 m0, s38
	ds_read_b128 v[194:197], v173 offset:49152
	ds_read_b128 v[198:201], v173 offset:50176
	ds_read_b128 v[202:205], v173 offset:51200
	ds_read_b128 v[206:209], v173 offset:52224
	ds_read_b128 v[210:213], v173 offset:53248
	ds_read_b128 v[214:217], v173 offset:54272
	ds_read_b128 v[218:221], v173 offset:55296
	ds_read_b128 v[222:225], v173 offset:56320
	global_load_lds_dwordx4 v[228:229], off
	v_lshl_add_u64 v[228:229], v[230:231], 0, s[12:13]
	s_add_i32 m0, s38, 0x2000
	v_lshl_add_u64 v[164:165], v[164:165], 0, s[14:15]
	s_add_i32 s38, s60, s40
	global_load_lds_dwordx4 v[228:229], off
	v_lshl_add_u64 v[228:229], v[164:165], 0, v[150:151]
	s_mov_b32 m0, s38
	v_lshl_add_u64 v[164:165], v[164:165], 0, v[146:147]
	global_load_lds_dwordx4 v[228:229], off
	s_add_i32 m0, s38, 0x2000
	s_nop 0
	global_load_lds_dwordx4 v[164:165], off
	v_lshl_add_u64 v[164:165], v[232:233], 0, s[12:13]
	s_mov_b32 m0, s48
	s_nop 0
	global_load_lds_dwordx4 v[164:165], off
	v_lshl_add_u64 v[164:165], v[234:235], 0, s[12:13]
	s_mov_b32 m0, s49
	s_nop 0
	global_load_lds_dwordx4 v[164:165], off
	s_waitcnt vmcnt(8)
	s_waitcnt lgkmcnt(0)
	s_barrier
	s_waitcnt lgkmcnt(0)
	v_mfma_f32_16x16x32_bf16 v[60:63], v[132:135], v[194:197], v[60:63]
	v_mfma_f32_16x16x32_bf16 v[56:59], v[140:143], v[194:197], v[56:59]
	v_mfma_f32_16x16x32_bf16 v[44:47], v[132:135], v[202:205], v[44:47]
	v_mfma_f32_16x16x32_bf16 v[40:43], v[140:143], v[202:205], v[40:43]
	v_mfma_f32_16x16x32_bf16 v[28:31], v[132:135], v[210:213], v[28:31]
	v_mfma_f32_16x16x32_bf16 v[24:27], v[140:143], v[210:213], v[24:27]
	v_mfma_f32_16x16x32_bf16 v[12:15], v[132:135], v[218:221], v[12:15]
	v_mfma_f32_16x16x32_bf16 v[8:11], v[140:143], v[218:221], v[8:11]
	v_mfma_f32_16x16x32_bf16 v[60:63], v[136:139], v[198:201], v[60:63]
	v_mfma_f32_16x16x32_bf16 v[56:59], v[174:177], v[198:201], v[56:59]
	v_mfma_f32_16x16x32_bf16 v[44:47], v[136:139], v[206:209], v[44:47]
	v_mfma_f32_16x16x32_bf16 v[40:43], v[174:177], v[206:209], v[40:43]
	v_mfma_f32_16x16x32_bf16 v[28:31], v[136:139], v[214:217], v[28:31]
	v_mfma_f32_16x16x32_bf16 v[24:27], v[174:177], v[214:217], v[24:27]
	v_mfma_f32_16x16x32_bf16 v[12:15], v[136:139], v[222:225], v[12:15]
	v_mfma_f32_16x16x32_bf16 v[8:11], v[174:177], v[222:225], v[8:11]
	v_mfma_f32_16x16x32_bf16 v[52:55], v[178:181], v[194:197], v[52:55]
	v_mfma_f32_16x16x32_bf16 v[48:51], v[186:189], v[194:197], v[48:51]
	v_mfma_f32_16x16x32_bf16 v[36:39], v[178:181], v[202:205], v[36:39]
	v_mfma_f32_16x16x32_bf16 v[32:35], v[186:189], v[202:205], v[32:35]
	v_mfma_f32_16x16x32_bf16 v[20:23], v[178:181], v[210:213], v[20:23]
	v_mfma_f32_16x16x32_bf16 v[16:19], v[186:189], v[210:213], v[16:19]
	v_mfma_f32_16x16x32_bf16 v[4:7], v[178:181], v[218:221], v[4:7]
	v_mfma_f32_16x16x32_bf16 v[0:3], v[186:189], v[218:221], v[0:3]
	v_mfma_f32_16x16x32_bf16 v[52:55], v[182:185], v[198:201], v[52:55]
	v_mfma_f32_16x16x32_bf16 v[48:51], v[190:193], v[198:201], v[48:51]
	v_mfma_f32_16x16x32_bf16 v[36:39], v[182:185], v[206:209], v[36:39]
	v_mfma_f32_16x16x32_bf16 v[32:35], v[190:193], v[206:209], v[32:35]
	v_mfma_f32_16x16x32_bf16 v[20:23], v[182:185], v[214:217], v[20:23]
	v_mfma_f32_16x16x32_bf16 v[16:19], v[190:193], v[214:217], v[16:19]
	v_mfma_f32_16x16x32_bf16 v[4:7], v[182:185], v[222:225], v[4:7]
	v_mfma_f32_16x16x32_bf16 v[0:3], v[190:193], v[222:225], v[0:3]
	s_barrier
	s_add_i32 s21, s21, 2
	s_add_u32 s36, s36, 0x100
	s_addc_u32 s37, s37, 0
	s_cmp_gt_u32 s21, 13
	v_lshl_add_u64 v[130:131], v[130:131], 0, s[18:19]
	s_cbranch_scc0 .LBB0_907
	s_and_b64 vcc, exec, s[16:17]
	s_cbranch_vccz .LBB0_910
	s_barrier

; #define PG8_STAGE(bufoff, gbase, voff) do { _Pragma("unroll") for (int _i = 0; _i < 2; ++_i) \
;         __builtin_amdgcn_global_load_lds((const unsigned*)((const char*)(gbase) + (voff)[_i]), (PG8_LAS unsigned*)(lds + (bufoff) + ldsw + _i * 8192), 16, 0, 0); } while (0)
; #define PG8_BAR __builtin_amdgcn_s_barrier()
;     __host__ __device__ bool next(int i, Unit& u) const {
;         const long L = (long)i * G + c; if (L >= nwg) return false;
;         int wgid = (int)L; { const int q = nwg / NXCD, r = nwg % NXCD, xcd = wgid % NXCD, off = wgid / NXCD; wgid = (xcd < r ? xcd * (q + 1) : r * (q + 1) + (xcd - r) * q) + off; }
;         const int nig = WGM * nN, gid = wgid / nig, fm = gid * WGM, gsz = (nM - fm) < WGM ? (nM - fm) : WGM;
;         u.pm = fm + ((wgid % nig) % gsz); u.pn = (wgid % nig) / gsz; return true;
; template <class Epi, class Sched, bool ALIGN_EPI = false, bool SP2 = false>
; __device__ __forceinline__ void gemm_phase(PG8_LAS unsigned char* lds, const Gemm g, const Sched& S, const Epi& E) {
;     ...
;     for (int i = 0; i < 2; ++i) { int R, C; stage_rc(tid * 16 + i * 8192, R, C); const int Rb = Epi::PERM ? ((R & ~31) + perm32(R & 31)) : R;
;         voffA[i] = (unsigned)(R * K + C) * 2u; voffB[i] = (unsigned)(Rb * K + C) * 2u; }
;     const size_t kstep = (size_t)(BK * 2);
;     const size_t hstep = (size_t)HALF * K * 2;
;     const size_t tstep = 2 * hstep;
;     const unsigned ldsw = (unsigned)wid * 1024u;
;     const int aoff = lds_byte(wr * 64 + fr, fq * 8), boff = lds_byte(wc * 32 + fr, fq * 8);
;     ...
;     Unit cur, nxt; int ui = 0;
;     if (!S.next(0, cur)) return;
;     f32x4 acc[2][2][4][2];
; #pragma unroll
;     for (int a = 0; a < 2; ++a)
; #pragma unroll
;         for (int b = 0; b < 2; ++b)
; #pragma unroll
;             for (int m = 0; m < 4; ++m)
; #pragma unroll
;                 for (int n = 0; n < 2; ++n) acc[a][b][m][n] = (f32x4){0.f, 0.f, 0.f, 0.f};
;     bf16x8 At[4][2], B0[2][2], B1[2][2];
;     const char* cA = (const char*)g.A + (size_t)cur.pm * tstep; const char* cB = (const char*)g.Bt + (size_t)cur.pn * tstep;
;     S.a_ready(cur);
;     if constexpr (SP2) {
;         PG8_STAGE(PG8_SB(0, 0), cB, voffB); PG8_STAGE(PG8_SB(0, 1), cB + hstep, voffB); PG8_STAGE(PG8_SA(0, 0), cA, voffA); PG8_STAGE(PG8_SA(0, 1), cA + hstep, voffA);
;         if (wr == 1) PG8_BAR;
.LBB0_991:
	s_add_i32 s1, s6, s1
	s_ashr_i32 s6, s1, 31
	s_lshr_b32 s6, s6, 27
	s_add_i32 s6, s1, s6
	s_ashr_i32 s7, s6, 5
	s_and_b32 s6, s6, 0xffe0
	v_lshrrev_b32_e32 v3, 1, v226
	s_sub_i32 s6, s1, s6
	v_and_b32_e32 v10, 24, v3
	v_lshrrev_b32_e32 v3, 5, v226
	s_bfe_i32 s1, s6, 0x80000
	v_and_b32_e32 v3, 4, v3
	v_bfe_u32 v4, v226, 2, 2
	s_bfe_u32 s1, s1, 0x3000c
	v_lshlrev_b32_e32 v0, 4, v226
	s_waitcnt lgkmcnt(0)
	v_and_b32_e32 v1, 32, v226
	v_bfe_u32 v2, v226, 2, 4
	v_or3_b32 v3, v3, v4, v10
	v_lshrrev_b32_e32 v4, 3, v226
	s_movk_i32 s5, 0x70
	s_add_i32 s8, s6, s1
	v_bitop3_b32 v8, v0, v1, 48 bitop3:0x6c
	v_and_or_b32 v5, v4, s5, v2
	s_movk_i32 s5, 0x60
	v_add_u32_e32 v0, 0x2000, v0
	s_bfe_i32 s1, s8, 0x80000
	s_and_b32 s8, s8, 0xf8
	v_and_or_b32 v4, v4, s5, v3
	v_lshrrev_b32_e32 v0, 7, v0
	s_movk_i32 s5, 0xf0
	s_sub_i32 s6, s6, s8
	v_and_or_b32 v2, v0, s5, v2
	s_movk_i32 s5, 0xe0
	s_lshl_b32 s7, s7, 3
	s_sext_i32_i16 s9, s1
	s_sext_i32_i8 s6, s6
	v_and_b32_e32 v9, 64, v226
	v_and_or_b32 v0, v0, s5, v3
	s_lshr_b32 s5, s4, 6
	s_add_i32 s49, s7, s6
	s_ashr_i32 s6, s9, 3
	s_lshr_b32 s0, s4, 8
	v_or_b32_e32 v1, v8, v9
	s_lshl_b32 s30, s5, 10
	s_lshr_b32 s1, s9, 3
	s_mul_hi_i32 s7, s6, 0x160000
	s_mul_i32 s6, s6, 0x160000
	v_lshrrev_b32_e32 v1, 1, v1
	v_mul_u32_u24_e32 v4, 0xb00, v4
	s_add_u32 s26, s58, s6
	v_or_b32_e32 v4, v4, v1
	s_addc_u32 s27, s59, s7
	s_add_i32 s31, s30, 0
	v_lshlrev_b32_e32 v130, 1, v4
	v_mul_u32_u24_e32 v0, 0xb00, v0
	s_add_i32 m0, s31, 0x10000
	v_or_b32_e32 v0, v0, v1
	global_load_lds_dwordx4 v130, s[26:27]
	s_add_i32 m0, s31, 0x12000
	v_lshlrev_b32_e32 v134, 1, v0
	s_add_u32 s6, s26, 0xb0000
	global_load_lds_dwordx4 v134, s[26:27]
	s_addc_u32 s7, s27, 0
	s_add_i32 m0, s31, 0x14000
	s_mul_i32 s10, s49, 0x160000
	global_load_lds_dwordx4 v130, s[6:7]
	s_add_i32 m0, s31, 0x16000
	v_mul_u32_u24_e32 v11, 0xb00, v5
	s_mul_hi_i32 s8, s49, 0x160000
	s_add_u32 s22, s34, s10
	v_or_b32_e32 v5, v1, v11
	v_mul_u32_u24_e32 v12, 0xb00, v2
	s_addc_u32 s23, s35, s8
	s_add_i32 s33, s31, 0x2000
	v_lshlrev_b32_e32 v128, 1, v5
	v_or_b32_e32 v2, v12, v1
	global_load_lds_dwordx4 v134, s[6:7]
	s_mov_b32 m0, s31
	s_add_u32 s6, s22, 0xb0000
	v_lshlrev_b32_e32 v132, 1, v2
	global_load_lds_dwordx4 v128, s[22:23]
	s_mov_b32 m0, s33
	s_addc_u32 s7, s23, 0
	s_add_i32 s36, s31, 0x4000
	global_load_lds_dwordx4 v132, s[22:23]
	s_mov_b32 m0, s36
	s_add_i32 s37, s31, 0x6000
	global_load_lds_dwordx4 v128, s[6:7]
	s_mov_b32 m0, s37
	v_mov_b32_e32 v131, 0
	global_load_lds_dwordx4 v132, s[6:7]
	v_mov_b32_e32 v135, v131
	v_mov_b32_e32 v129, v131
	v_mov_b32_e32 v133, v131
	s_cmp_eq_u32 s0, 1
	s_mov_b32 s38, 0
	v_lshl_add_u64 v[6:7], s[26:27], 0, v[130:131]
	v_lshl_add_u64 v[4:5], s[26:27], 0, v[134:135]
	v_lshl_add_u64 v[0:1], s[22:23], 0, v[128:129]
	s_cselect_b64 s[6:7], -1, 0
	s_cmp_lg_u32 s0, 1
	v_lshl_add_u64 v[2:3], s[22:23], 0, v[132:133]
	s_cbranch_scc1 .LBB0_993
	s_barrier
	s_setprio 1

; #define PG8_STAGE(bufoff, gbase, voff) do { _Pragma("unroll") for (int _i = 0; _i < 2; ++_i) \
;         __builtin_amdgcn_global_load_lds((const unsigned*)((const char*)(gbase) + (voff)[_i]), (PG8_LAS unsigned*)(lds + (bufoff) + ldsw + _i * 8192), 16, 0, 0); } while (0)
; #define PG8_LDA(dst, b, h) do { _Pragma("unroll") for (int m = 0; m < 4; ++m) _Pragma("unroll") for (int k = 0; k < 2; ++k) dst[m][k] = *(const PG8_LAS bf16x8*)(lds + PG8_SA(b, h) + aoff + m * 2048 + k * 1024); } while (0)
; #define PG8_LDB(dst, b, h) do { _Pragma("unroll") for (int n = 0; n < 2; ++n) _Pragma("unroll") for (int k = 0; k < 2; ++k) dst[n][k] = *(const PG8_LAS bf16x8*)(lds + PG8_SB(b, h) + boff + n * 2048 + k * 1024); } while (0)
; #define PG8_MMA(ai, bj, At, Bt) do { __builtin_amdgcn_s_setprio(1); _Pragma("unroll") for (int m = 0; m < 4; ++m) _Pragma("unroll") for (int n = 0; n < 2; ++n) _Pragma("unroll") for (int k = 0; k < 2; ++k) \
;         acc[ai][bj][m][n] = __builtin_amdgcn_mfma_f32_16x16x32_bf16(Bt[n][k], At[m][k], acc[ai][bj][m][n], 0, 0, 0); __builtin_amdgcn_s_setprio(0); } while (0)
; #define PG8_WAIT_V(n) asm volatile("s_waitcnt vmcnt(" #n ")" ::: "memory")
; #define PG8_WAIT_L(n) asm volatile("s_waitcnt lgkmcnt(" #n ")" ::: "memory")
; template <class Epi, class Sched, bool ALIGN_EPI = false, bool SP2 = false>
; __device__ __forceinline__ void gemm_phase(PG8_LAS unsigned char* lds, const Gemm g, const Sched& S, const Epi& E) {
;     ...
;             const bool last = (t == nt - 2);
;             const char* a1 = cA + (size_t)(t + 1) * kstep;
;             const char* a2 = last ? nA : cA + (size_t)(t + 2) * kstep; const char* b2 = last ? nB : cB + (size_t)(t + 2) * kstep;
;             const char* a3 = a2 + kstep; const char* b3 = b2 + kstep;
;             if (last && has_next) S.a_ready(nxt);
;             if constexpr (SP2) {
;             PG8_LDB(B0, 0, 0); PG8_LDB(B1, 0, 1); PG8_SCHED; PG8_LDA(At, 0, 0); PG8_STAGE(PG8_SA(1, 1), a1 + hstep, voffA);
;             PG8_WAIT_V(8); PG8_WAIT_L(0); PG8_BAR; PG8_MMA(0, 0, At, B0); PG8_MMA(0, 1, At, B1); PG8_BAR; PG8_SCHED;
;             PG8_LDA(At, 0, 1); PG8_STAGE(PG8_SB(0, 0), b2, voffB); PG8_STAGE(PG8_SB(0, 1), b2 + hstep, voffB); PG8_STAGE(PG8_SA(0, 0), a2, voffA);
;             PG8_WAIT_V(8); PG8_WAIT_L(0); PG8_BAR; PG8_MMA(1, 0, At, B0); PG8_MMA(1, 1, At, B1); PG8_BAR; PG8_SCHED;
.LBB0_1007:
	ds_read_b128 v[144:147], v169
	ds_read_b128 v[148:151], v169 offset:1024
	ds_read_b128 v[152:155], v169 offset:2048
	ds_read_b128 v[156:159], v169 offset:3072
	ds_read_b128 v[160:163], v170
	ds_read_b128 v[172:175], v170 offset:1024
	ds_read_b128 v[176:179], v170 offset:2048
	ds_read_b128 v[180:183], v170 offset:3072
	s_add_u32 s26, s22, 0xfff50080
	s_addc_u32 s27, s23, -1
	s_cmp_eq_u32 s53, 40
	s_cselect_b32 s29, s5, s27
	s_cselect_b32 s28, s4, s26
	s_cselect_b32 s27, s21, s52
	s_cselect_b32 s26, s20, s51
	v_lshl_add_u64 v[164:165], s[22:23], 0, v[136:137]
	s_add_i32 m0, s31, 0xc000
	ds_read_b128 v[184:187], v171
	ds_read_b128 v[188:191], v171 offset:1024
	ds_read_b128 v[192:195], v171 offset:2048
	ds_read_b128 v[196:199], v171 offset:3072
	ds_read_b128 v[200:203], v171 offset:4096
	ds_read_b128 v[204:207], v171 offset:5120
	ds_read_b128 v[208:211], v171 offset:6144
	ds_read_b128 v[212:215], v171 offset:7168
	global_load_lds_dwordx4 v[164:165], off
	v_lshl_add_u64 v[164:165], s[22:23], 0, v[138:139]
	s_add_i32 m0, s31, 0xe000
	s_nop 0
	global_load_lds_dwordx4 v[164:165], off
	s_waitcnt vmcnt(8)
	s_waitcnt lgkmcnt(0)
	s_barrier
	s_waitcnt lgkmcnt(0)
	v_mfma_f32_16x16x32_bf16 v[124:127], v[144:147], v[184:187], v[124:127]
	v_mfma_f32_16x16x32_bf16 v[120:123], v[152:155], v[184:187], v[120:123]
	v_mfma_f32_16x16x32_bf16 v[108:111], v[144:147], v[192:195], v[108:111]
	v_mfma_f32_16x16x32_bf16 v[104:107], v[152:155], v[192:195], v[104:107]
	v_mfma_f32_16x16x32_bf16 v[92:95], v[144:147], v[200:203], v[92:95]
	v_mfma_f32_16x16x32_bf16 v[88:91], v[152:155], v[200:203], v[88:91]
	v_mfma_f32_16x16x32_bf16 v[76:79], v[144:147], v[208:211], v[76:79]
	v_mfma_f32_16x16x32_bf16 v[72:75], v[152:155], v[208:211], v[72:75]
	v_mfma_f32_16x16x32_bf16 v[124:127], v[148:151], v[188:191], v[124:127]
	v_mfma_f32_16x16x32_bf16 v[120:123], v[156:159], v[188:191], v[120:123]
	v_mfma_f32_16x16x32_bf16 v[108:111], v[148:151], v[196:199], v[108:111]
	v_mfma_f32_16x16x32_bf16 v[104:107], v[156:159], v[196:199], v[104:107]
	v_mfma_f32_16x16x32_bf16 v[92:95], v[148:151], v[204:207], v[92:95]
	v_mfma_f32_16x16x32_bf16 v[88:91], v[156:159], v[204:207], v[88:91]
	v_mfma_f32_16x16x32_bf16 v[76:79], v[148:151], v[212:215], v[76:79]
	v_mfma_f32_16x16x32_bf16 v[72:75], v[156:159], v[212:215], v[72:75]
	v_mfma_f32_16x16x32_bf16 v[116:119], v[160:163], v[184:187], v[116:119]
	v_mfma_f32_16x16x32_bf16 v[112:115], v[176:179], v[184:187], v[112:115]
	v_mfma_f32_16x16x32_bf16 v[100:103], v[160:163], v[192:195], v[100:103]
	v_mfma_f32_16x16x32_bf16 v[96:99], v[176:179], v[192:195], v[96:99]
	v_mfma_f32_16x16x32_bf16 v[84:87], v[160:163], v[200:203], v[84:87]
	v_mfma_f32_16x16x32_bf16 v[80:83], v[176:179], v[200:203], v[80:83]
	v_mfma_f32_16x16x32_bf16 v[68:71], v[160:163], v[208:211], v[68:71]
	v_mfma_f32_16x16x32_bf16 v[64:67], v[176:179], v[208:211], v[64:67]
	v_mfma_f32_16x16x32_bf16 v[116:119], v[172:175], v[188:191], v[116:119]
	v_mfma_f32_16x16x32_bf16 v[112:115], v[180:183], v[188:191], v[112:115]
	v_mfma_f32_16x16x32_bf16 v[100:103], v[172:175], v[196:199], v[100:103]
	v_mfma_f32_16x16x32_bf16 v[96:99], v[180:183], v[196:199], v[96:99]
	v_mfma_f32_16x16x32_bf16 v[84:87], v[172:175], v[204:207], v[84:87]
	v_mfma_f32_16x16x32_bf16 v[80:83], v[180:183], v[204:207], v[80:83]
	v_mfma_f32_16x16x32_bf16 v[68:71], v[172:175], v[212:215], v[68:71]
	v_mfma_f32_16x16x32_bf16 v[64:67], v[180:183], v[212:215], v[64:67]
	s_barrier
	s_add_i32 s54, s45, s30
	v_lshl_add_u64 v[164:165], s[26:27], 0, v[130:131]
	s_mov_b32 m0, s54
	ds_read_b128 v[184:187], v171 offset:16384
	ds_read_b128 v[188:191], v171 offset:17408
	ds_read_b128 v[192:195], v171 offset:18432
	ds_read_b128 v[196:199], v171 offset:19456
	ds_read_b128 v[200:203], v171 offset:20480
	ds_read_b128 v[204:207], v171 offset:21504
	ds_read_b128 v[208:211], v171 offset:22528
	ds_read_b128 v[212:215], v171 offset:23552
	global_load_lds_dwordx4 v[164:165], off
	s_add_i32 m0, s54, 0x2000
	s_add_u32 s54, s26, 0xb0000
	v_lshl_add_u64 v[216:217], s[26:27], 0, v[134:135]
	s_addc_u32 s55, s27, 0
	s_add_i32 s56, s46, s30
	global_load_lds_dwordx4 v[216:217], off
	v_lshl_add_u64 v[218:219], s[54:55], 0, v[130:131]
	s_mov_b32 m0, s56
	v_lshl_add_u64 v[220:221], s[28:29], 0, v[132:133]
	global_load_lds_dwordx4 v[218:219], off
	v_lshl_add_u64 v[218:219], s[54:55], 0, v[134:135]
	s_add_i32 m0, s56, 0x2000
	s_nop 0
	global_load_lds_dwordx4 v[218:219], off
	v_lshl_add_u64 v[218:219], s[28:29], 0, v[128:129]
	s_mov_b32 m0, s31
	s_nop 0
	global_load_lds_dwordx4 v[218:219], off
	s_mov_b32 m0, s33
	s_nop 0
	global_load_lds_dwordx4 v[220:221], off
	s_waitcnt vmcnt(8)
	s_waitcnt lgkmcnt(0)
	s_barrier
; #define PG8_STAGE(bufoff, gbase, voff) do { _Pragma("unroll") for (int _i = 0; _i < 2; ++_i) \
;         __builtin_amdgcn_global_load_lds((const unsigned*)((const char*)(gbase) + (voff)[_i]), (PG8_LAS unsigned*)(lds + (bufoff) + ldsw + _i * 8192), 16, 0, 0); } while (0)
; #define PG8_LDA(dst, b, h) do { _Pragma("unroll") for (int m = 0; m < 4; ++m) _Pragma("unroll") for (int k = 0; k < 2; ++k) dst[m][k] = *(const PG8_LAS bf16x8*)(lds + PG8_SA(b, h) + aoff + m * 2048 + k * 1024); } while (0)
; #define PG8_LDB(dst, b, h) do { _Pragma("unroll") for (int n = 0; n < 2; ++n) _Pragma("unroll") for (int k = 0; k < 2; ++k) dst[n][k] = *(const PG8_LAS bf16x8*)(lds + PG8_SB(b, h) + boff + n * 2048 + k * 1024); } while (0)
; #define PG8_MMA(ai, bj, At, Bt) do { __builtin_amdgcn_s_setprio(1); _Pragma("unroll") for (int m = 0; m < 4; ++m) _Pragma("unroll") for (int n = 0; n < 2; ++n) _Pragma("unroll") for (int k = 0; k < 2; ++k) \
;         acc[ai][bj][m][n] = __builtin_amdgcn_mfma_f32_16x16x32_bf16(Bt[n][k], At[m][k], acc[ai][bj][m][n], 0, 0, 0); __builtin_amdgcn_s_setprio(0); } while (0)
; #define PG8_WAIT_V(n) asm volatile("s_waitcnt vmcnt(" #n ")" ::: "memory")
; #define PG8_WAIT_L(n) asm volatile("s_waitcnt lgkmcnt(" #n ")" ::: "memory")
; #define PG8_BAR __builtin_amdgcn_s_barrier()
; #define PG8_SCHED __builtin_amdgcn_sched_barrier(0)
; template <class Epi, class Sched, bool ALIGN_EPI = false, bool SP2 = false>
; __device__ __forceinline__ void gemm_phase(PG8_LAS unsigned char* lds, const Gemm g, const Sched& S, const Epi& E) {
;     ...
;             PG8_WAIT_V(8); PG8_WAIT_L(0); PG8_BAR; PG8_MMA(1, 0, At, B0); PG8_MMA(1, 1, At, B1); PG8_BAR; PG8_SCHED;
;             PG8_LDB(B0, 1, 0); PG8_LDB(B1, 1, 1); PG8_SCHED; PG8_LDA(At, 1, 0); PG8_STAGE(PG8_SA(0, 1), a2 + hstep, voffA);
;             PG8_WAIT_V(8); PG8_WAIT_L(0); PG8_BAR; PG8_MMA(0, 0, At, B0); PG8_MMA(0, 1, At, B1); PG8_BAR; PG8_SCHED;
;             PG8_LDA(At, 1, 1); PG8_STAGE(PG8_SB(1, 0), b3, voffB); PG8_STAGE(PG8_SB(1, 1), b3 + hstep, voffB); PG8_STAGE(PG8_SA(1, 0), a3, voffA);
	s_waitcnt lgkmcnt(0)
	v_mfma_f32_16x16x32_bf16 v[60:63], v[144:147], v[184:187], v[60:63]
	v_mfma_f32_16x16x32_bf16 v[56:59], v[152:155], v[184:187], v[56:59]
	v_mfma_f32_16x16x32_bf16 v[44:47], v[144:147], v[192:195], v[44:47]
	v_mfma_f32_16x16x32_bf16 v[40:43], v[152:155], v[192:195], v[40:43]
	v_mfma_f32_16x16x32_bf16 v[28:31], v[144:147], v[200:203], v[28:31]
	v_mfma_f32_16x16x32_bf16 v[24:27], v[152:155], v[200:203], v[24:27]
	v_mfma_f32_16x16x32_bf16 v[12:15], v[144:147], v[208:211], v[12:15]
	v_mfma_f32_16x16x32_bf16 v[8:11], v[152:155], v[208:211], v[8:11]
	v_mfma_f32_16x16x32_bf16 v[60:63], v[148:151], v[188:191], v[60:63]
	v_mfma_f32_16x16x32_bf16 v[56:59], v[156:159], v[188:191], v[56:59]
	v_mfma_f32_16x16x32_bf16 v[44:47], v[148:151], v[196:199], v[44:47]
	v_mfma_f32_16x16x32_bf16 v[40:43], v[156:159], v[196:199], v[40:43]
	v_mfma_f32_16x16x32_bf16 v[28:31], v[148:151], v[204:207], v[28:31]
	v_mfma_f32_16x16x32_bf16 v[24:27], v[156:159], v[204:207], v[24:27]
	v_mfma_f32_16x16x32_bf16 v[12:15], v[148:151], v[212:215], v[12:15]
	v_mfma_f32_16x16x32_bf16 v[8:11], v[156:159], v[212:215], v[8:11]
	v_mfma_f32_16x16x32_bf16 v[52:55], v[160:163], v[184:187], v[52:55]
	v_mfma_f32_16x16x32_bf16 v[48:51], v[176:179], v[184:187], v[48:51]
	v_mfma_f32_16x16x32_bf16 v[36:39], v[160:163], v[192:195], v[36:39]
	v_mfma_f32_16x16x32_bf16 v[32:35], v[176:179], v[192:195], v[32:35]
	v_mfma_f32_16x16x32_bf16 v[20:23], v[160:163], v[200:203], v[20:23]
	v_mfma_f32_16x16x32_bf16 v[16:19], v[176:179], v[200:203], v[16:19]
	v_mfma_f32_16x16x32_bf16 v[4:7], v[160:163], v[208:211], v[4:7]
	v_mfma_f32_16x16x32_bf16 v[0:3], v[176:179], v[208:211], v[0:3]
	v_mfma_f32_16x16x32_bf16 v[52:55], v[172:175], v[188:191], v[52:55]
	v_mfma_f32_16x16x32_bf16 v[48:51], v[180:183], v[188:191], v[48:51]
	v_mfma_f32_16x16x32_bf16 v[36:39], v[172:175], v[196:199], v[36:39]
	v_mfma_f32_16x16x32_bf16 v[32:35], v[180:183], v[196:199], v[32:35]
	v_mfma_f32_16x16x32_bf16 v[20:23], v[172:175], v[204:207], v[20:23]
	v_mfma_f32_16x16x32_bf16 v[16:19], v[180:183], v[204:207], v[16:19]
	v_mfma_f32_16x16x32_bf16 v[4:7], v[172:175], v[212:215], v[4:7]
	v_mfma_f32_16x16x32_bf16 v[0:3], v[180:183], v[212:215], v[0:3]
	s_barrier
	s_add_i32 s54, 0, 0x18000
	s_add_i32 s55, 0, 0x1c000
	v_add_u32_e32 v156, s54, v167
	v_add_u32_e32 v180, s55, v167
	ds_read_b128 v[144:147], v156
	ds_read_b128 v[148:151], v156 offset:1024
	ds_read_b128 v[152:155], v156 offset:2048
	ds_read_b128 v[156:159], v156 offset:3072
	ds_read_b128 v[160:163], v180
	ds_read_b128 v[172:175], v180 offset:1024
	ds_read_b128 v[176:179], v180 offset:2048
	ds_read_b128 v[180:183], v180 offset:3072
	s_add_u32 s28, s28, 0xb0000
	s_addc_u32 s29, s29, 0
	s_mov_b32 m0, s36
	v_lshl_add_u64 v[222:223], s[28:29], 0, v[128:129]
	ds_read_b128 v[184:187], v171 offset:32768
	ds_read_b128 v[188:191], v171 offset:33792
	ds_read_b128 v[192:195], v171 offset:34816
	ds_read_b128 v[196:199], v171 offset:35840
	ds_read_b128 v[200:203], v171 offset:36864
	ds_read_b128 v[204:207], v171 offset:37888
	ds_read_b128 v[208:211], v171 offset:38912
	ds_read_b128 v[212:215], v171 offset:39936
	global_load_lds_dwordx4 v[222:223], off
	v_lshl_add_u64 v[222:223], s[28:29], 0, v[132:133]
	s_mov_b32 m0, s37
	s_nop 0
	global_load_lds_dwordx4 v[222:223], off
	s_waitcnt vmcnt(8)
	s_waitcnt lgkmcnt(0)
	s_barrier
	s_waitcnt lgkmcnt(0)
	v_mfma_f32_16x16x32_bf16 v[124:127], v[144:147], v[184:187], v[124:127]
	v_mfma_f32_16x16x32_bf16 v[120:123], v[152:155], v[184:187], v[120:123]
	v_mfma_f32_16x16x32_bf16 v[108:111], v[144:147], v[192:195], v[108:111]
	v_mfma_f32_16x16x32_bf16 v[104:107], v[152:155], v[192:195], v[104:107]
	v_mfma_f32_16x16x32_bf16 v[92:95], v[144:147], v[200:203], v[92:95]
	v_mfma_f32_16x16x32_bf16 v[88:91], v[152:155], v[200:203], v[88:91]
	v_mfma_f32_16x16x32_bf16 v[76:79], v[144:147], v[208:211], v[76:79]
	v_mfma_f32_16x16x32_bf16 v[72:75], v[152:155], v[208:211], v[72:75]
	v_mfma_f32_16x16x32_bf16 v[124:127], v[148:151], v[188:191], v[124:127]
	v_mfma_f32_16x16x32_bf16 v[120:123], v[156:159], v[188:191], v[120:123]
	v_mfma_f32_16x16x32_bf16 v[108:111], v[148:151], v[196:199], v[108:111]
	v_mfma_f32_16x16x32_bf16 v[104:107], v[156:159], v[196:199], v[104:107]
	v_mfma_f32_16x16x32_bf16 v[92:95], v[148:151], v[204:207], v[92:95]
	v_mfma_f32_16x16x32_bf16 v[88:91], v[156:159], v[204:207], v[88:91]
	v_mfma_f32_16x16x32_bf16 v[76:79], v[148:151], v[212:215], v[76:79]
	v_mfma_f32_16x16x32_bf16 v[72:75], v[156:159], v[212:215], v[72:75]
	v_mfma_f32_16x16x32_bf16 v[116:119], v[160:163], v[184:187], v[116:119]
	v_mfma_f32_16x16x32_bf16 v[112:115], v[176:179], v[184:187], v[112:115]
	v_mfma_f32_16x16x32_bf16 v[100:103], v[160:163], v[192:195], v[100:103]
	v_mfma_f32_16x16x32_bf16 v[96:99], v[176:179], v[192:195], v[96:99]
	v_mfma_f32_16x16x32_bf16 v[84:87], v[160:163], v[200:203], v[84:87]
	v_mfma_f32_16x16x32_bf16 v[80:83], v[176:179], v[200:203], v[80:83]
	v_mfma_f32_16x16x32_bf16 v[68:71], v[160:163], v[208:211], v[68:71]
	v_mfma_f32_16x16x32_bf16 v[64:67], v[176:179], v[208:211], v[64:67]
	v_mfma_f32_16x16x32_bf16 v[116:119], v[172:175], v[188:191], v[116:119]
	v_mfma_f32_16x16x32_bf16 v[112:115], v[180:183], v[188:191], v[112:115]
	v_mfma_f32_16x16x32_bf16 v[100:103], v[172:175], v[196:199], v[100:103]
	v_mfma_f32_16x16x32_bf16 v[96:99], v[180:183], v[196:199], v[96:99]
	v_mfma_f32_16x16x32_bf16 v[84:87], v[172:175], v[204:207], v[84:87]
	v_mfma_f32_16x16x32_bf16 v[80:83], v[180:183], v[204:207], v[80:83]
	v_mfma_f32_16x16x32_bf16 v[68:71], v[172:175], v[212:215], v[68:71]
	v_mfma_f32_16x16x32_bf16 v[64:67], v[180:183], v[212:215], v[64:67]
	s_barrier
; #define PG8_STAGE(bufoff, gbase, voff) do { _Pragma("unroll") for (int _i = 0; _i < 2; ++_i) \
;         __builtin_amdgcn_global_load_lds((const unsigned*)((const char*)(gbase) + (voff)[_i]), (PG8_LAS unsigned*)(lds + (bufoff) + ldsw + _i * 8192), 16, 0, 0); } while (0)
; #define PG8_LDA(dst, b, h) do { _Pragma("unroll") for (int m = 0; m < 4; ++m) _Pragma("unroll") for (int k = 0; k < 2; ++k) dst[m][k] = *(const PG8_LAS bf16x8*)(lds + PG8_SA(b, h) + aoff + m * 2048 + k * 1024); } while (0)
; #define PG8_MMA(ai, bj, At, Bt) do { __builtin_amdgcn_s_setprio(1); _Pragma("unroll") for (int m = 0; m < 4; ++m) _Pragma("unroll") for (int n = 0; n < 2; ++n) _Pragma("unroll") for (int k = 0; k < 2; ++k) \
;         acc[ai][bj][m][n] = __builtin_amdgcn_mfma_f32_16x16x32_bf16(Bt[n][k], At[m][k], acc[ai][bj][m][n], 0, 0, 0); __builtin_amdgcn_s_setprio(0); } while (0)
; #define PG8_WAIT_V(n) asm volatile("s_waitcnt vmcnt(" #n ")" ::: "memory")
; #define PG8_WAIT_L(n) asm volatile("s_waitcnt lgkmcnt(" #n ")" ::: "memory")
; #define PG8_BAR __builtin_amdgcn_s_barrier()
; #define PG8_SCHED __builtin_amdgcn_sched_barrier(0)
; template <class Epi, class Sched, bool ALIGN_EPI = false, bool SP2 = false>
; __device__ __forceinline__ void gemm_phase(PG8_LAS unsigned char* lds, const Gemm g, const Sched& S, const Epi& E) {
;     ...
;             PG8_LDA(At, 1, 1); PG8_STAGE(PG8_SB(1, 0), b3, voffB); PG8_STAGE(PG8_SB(1, 1), b3 + hstep, voffB); PG8_STAGE(PG8_SA(1, 0), a3, voffA);
;             PG8_WAIT_V(8); PG8_WAIT_L(0); PG8_BAR; PG8_MMA(1, 0, At, B0); PG8_MMA(1, 1, At, B1); PG8_BAR; PG8_SCHED;
;     ...
;         if constexpr (ALIGN_EPI) { if (wr == 0) PG8_BAR; }
	s_add_i32 s28, s54, s30
	v_lshl_add_u64 v[164:165], v[164:165], 0, s[8:9]
	s_mov_b32 m0, s28
	ds_read_b128 v[184:187], v171 offset:49152
	ds_read_b128 v[188:191], v171 offset:50176
	ds_read_b128 v[192:195], v171 offset:51200
	ds_read_b128 v[196:199], v171 offset:52224
	ds_read_b128 v[200:203], v171 offset:53248
	ds_read_b128 v[204:207], v171 offset:54272
	ds_read_b128 v[208:211], v171 offset:55296
	ds_read_b128 v[212:215], v171 offset:56320
	global_load_lds_dwordx4 v[164:165], off
	s_add_i32 m0, s28, 0x2000
	s_add_u32 s26, s26, 0xb0080
	v_lshl_add_u64 v[164:165], v[216:217], 0, s[8:9]
	s_addc_u32 s27, s27, 0
	s_add_i32 s28, s55, s30
	global_load_lds_dwordx4 v[164:165], off
	v_lshl_add_u64 v[164:165], s[26:27], 0, v[130:131]
	s_mov_b32 m0, s28
	s_nop 0
	global_load_lds_dwordx4 v[164:165], off
	v_lshl_add_u64 v[164:165], s[26:27], 0, v[134:135]
	s_add_i32 m0, s28, 0x2000
	s_nop 0
	global_load_lds_dwordx4 v[164:165], off
	v_lshl_add_u64 v[164:165], v[218:219], 0, s[8:9]
	s_mov_b32 m0, s41
	s_nop 0
	global_load_lds_dwordx4 v[164:165], off
	v_lshl_add_u64 v[164:165], v[220:221], 0, s[8:9]
	s_mov_b32 m0, s43
	s_nop 0
	global_load_lds_dwordx4 v[164:165], off
	s_waitcnt vmcnt(8)
	s_waitcnt lgkmcnt(0)
	s_barrier
	s_waitcnt lgkmcnt(0)
	v_mfma_f32_16x16x32_bf16 v[60:63], v[144:147], v[184:187], v[60:63]
	v_mfma_f32_16x16x32_bf16 v[56:59], v[152:155], v[184:187], v[56:59]
	v_mfma_f32_16x16x32_bf16 v[44:47], v[144:147], v[192:195], v[44:47]
	v_mfma_f32_16x16x32_bf16 v[40:43], v[152:155], v[192:195], v[40:43]
	v_mfma_f32_16x16x32_bf16 v[28:31], v[144:147], v[200:203], v[28:31]
	v_mfma_f32_16x16x32_bf16 v[24:27], v[152:155], v[200:203], v[24:27]
	v_mfma_f32_16x16x32_bf16 v[12:15], v[144:147], v[208:211], v[12:15]
	v_mfma_f32_16x16x32_bf16 v[8:11], v[152:155], v[208:211], v[8:11]
	v_mfma_f32_16x16x32_bf16 v[60:63], v[148:151], v[188:191], v[60:63]
	v_mfma_f32_16x16x32_bf16 v[56:59], v[156:159], v[188:191], v[56:59]
	v_mfma_f32_16x16x32_bf16 v[44:47], v[148:151], v[196:199], v[44:47]
	v_mfma_f32_16x16x32_bf16 v[40:43], v[156:159], v[196:199], v[40:43]
	v_mfma_f32_16x16x32_bf16 v[28:31], v[148:151], v[204:207], v[28:31]
	v_mfma_f32_16x16x32_bf16 v[24:27], v[156:159], v[204:207], v[24:27]
	v_mfma_f32_16x16x32_bf16 v[12:15], v[148:151], v[212:215], v[12:15]
	v_mfma_f32_16x16x32_bf16 v[8:11], v[156:159], v[212:215], v[8:11]
	v_mfma_f32_16x16x32_bf16 v[52:55], v[160:163], v[184:187], v[52:55]
	v_mfma_f32_16x16x32_bf16 v[48:51], v[176:179], v[184:187], v[48:51]
	v_mfma_f32_16x16x32_bf16 v[36:39], v[160:163], v[192:195], v[36:39]
	v_mfma_f32_16x16x32_bf16 v[32:35], v[176:179], v[192:195], v[32:35]
	v_mfma_f32_16x16x32_bf16 v[20:23], v[160:163], v[200:203], v[20:23]
	v_mfma_f32_16x16x32_bf16 v[16:19], v[176:179], v[200:203], v[16:19]
	v_mfma_f32_16x16x32_bf16 v[4:7], v[160:163], v[208:211], v[4:7]
	v_mfma_f32_16x16x32_bf16 v[0:3], v[176:179], v[208:211], v[0:3]
	v_mfma_f32_16x16x32_bf16 v[52:55], v[172:175], v[188:191], v[52:55]
	v_mfma_f32_16x16x32_bf16 v[48:51], v[180:183], v[188:191], v[48:51]
	v_mfma_f32_16x16x32_bf16 v[36:39], v[172:175], v[196:199], v[36:39]
	v_mfma_f32_16x16x32_bf16 v[32:35], v[180:183], v[196:199], v[32:35]
	v_mfma_f32_16x16x32_bf16 v[20:23], v[172:175], v[204:207], v[20:23]
	v_mfma_f32_16x16x32_bf16 v[16:19], v[180:183], v[204:207], v[16:19]
	v_mfma_f32_16x16x32_bf16 v[4:7], v[172:175], v[212:215], v[4:7]
	v_mfma_f32_16x16x32_bf16 v[0:3], v[180:183], v[212:215], v[0:3]
	s_barrier
	s_add_i32 s53, s53, 2
	s_add_u32 s22, s22, 0x100
	s_addc_u32 s23, s23, 0
	s_add_u32 s51, s51, 0x100
	s_addc_u32 s52, s52, 0
	s_cmp_gt_u32 s53, 41
	s_cbranch_scc0 .LBB0_1007
	s_and_b64 vcc, exec, s[10:11]
	s_cbranch_vccz .LBB0_1010
	s_barrier
